# GEMM compute-segment heads: priority raised before the segment barrier (not after) and duplicate lgkmcnt(0) removed: the first MFMA is the first instruction after the barrier release
# baseline (speedup 1.0000x reference)
; #define PG8_STAGE(bufoff, gbase, voff) do { _Pragma("unroll") for (int _i = 0; _i < 2; ++_i) \
;         __builtin_amdgcn_global_load_lds((const unsigned*)((const char*)(gbase) + (voff)[_i]), (LAS unsigned*)(lds + (bufoff) + ldsw + _i * 8192), 16, 0, 0); } while (0)
; #define PG8_LDA(dst, b, h) do { _Pragma("unroll") for (int m = 0; m < 4; ++m) _Pragma("unroll") for (int k = 0; k < 2; ++k) dst[m][k] = *(const LAS bf16x8*)(lds + PG8_SA(b, h) + aoff + m * 2048 + k * 1024); } while (0)
; #define PG8_LDB(dst, b, h) do { _Pragma("unroll") for (int n = 0; n < 2; ++n) _Pragma("unroll") for (int k = 0; k < 2; ++k) dst[n][k] = *(const LAS bf16x8*)(lds + PG8_SB(b, h) + boff + n * 2048 + k * 1024); } while (0)
; #define PG8_MMA(ai, bj, At, Bt) do { __builtin_amdgcn_s_setprio(3); _Pragma("unroll") for (int m = 0; m < 4; ++m) _Pragma("unroll") for (int n = 0; n < 2; ++n) _Pragma("unroll") for (int k = 0; k < 2; ++k) \
;         acc[ai][bj][m][n] = __builtin_amdgcn_mfma_f32_16x16x32_bf16(Bt[n][k], At[m][k], acc[ai][bj][m][n], 0, 0, 0); __builtin_amdgcn_s_setprio(0); } while (0)
; #define PG8_WAIT_V(n) asm volatile("s_waitcnt vmcnt(" #n ")" ::: "memory")
; template <class Epi, class Sched>
; __device__ __forceinline__ void gemm_phase(LAS unsigned char* lds, const Gemm g, const Sched& S, const Epi& E, int tid_in) {
;     ...
;         const char* nA = has_next ? (const char*)g.A + (size_t)nxt.pm * tstep + nxt.koff : cA; const char* nB = has_next ? (const char*)g.Bt + (size_t)nxt.pn * tstep + nxt.koff : cB;
;         for (int t = 0; t < nt; t += 2) {
;             const bool last = (t == nt - 2);
;             const char* a1 = cA + (size_t)(t + 1) * kstep;
;             const char* a2 = last ? nA : cA + (size_t)(t + 2) * kstep; const char* b2 = last ? nB : cB + (size_t)(t + 2) * kstep;
;             const char* a3 = a2 + kstep; const char* b3 = b2 + kstep;
;             PG8_LDB(B0, 0, 0); PG8_LDB(B1, 0, 1); PG8_SCHED; PG8_LDA(At, 0, 0); PG8_STAGE(PG8_SA(1, 0), a1, voffA); PG8_STAGE(PG8_SA(1, 1), a1 + hstep, voffA);
;             PG8_WAIT_V(8); PG8_WAIT_L(0); PG8_BAR; PG8_MMA(0, 0, At, B0); PG8_MMA(0, 1, At, B1); PG8_BAR; PG8_SCHED;
;             PG8_LDA(At, 0, 1); PG8_STAGE(PG8_SB(0, 0), b2, voffB); PG8_STAGE(PG8_SB(0, 1), b2 + hstep, voffB);
;             PG8_WAIT_V(6); PG8_WAIT_L(0); PG8_BAR; PG8_MMA(1, 0, At, B0); PG8_MMA(1, 1, At, B1); PG8_BAR; PG8_SCHED;
.LBB0_101:
	s_ashr_i32 s31, s30, 31
	s_lshl_b64 s[34:35], s[30:31], 20
	s_add_u32 s34, s58, s34
	s_addc_u32 s35, s59, s35
	s_and_b64 s[36:37], s[0:1], exec
	s_cselect_b32 s31, s35, s43
	s_cselect_b32 s39, s34, s42
	s_ashr_i32 s29, s28, 31
	s_lshl_b64 s[36:37], s[28:29], 20
	s_add_u32 s36, s56, s36
	s_addc_u32 s37, s57, s37
	s_and_b64 s[46:47], s[0:1], exec
	s_cselect_b32 s29, s37, s45
	s_cselect_b32 s41, s36, s44
	s_add_u32 s94, s44, 0x100
	s_addc_u32 s95, s45, 0
	s_mov_b32 s96, -2
	s_mov_b64 s[44:45], 0
	v_lshl_add_u64 v[128:129], s[42:43], 0, v[158:159]
	v_lshl_add_u64 v[130:131], s[42:43], 0, v[160:161]
	ds_read_b128 v[132:135], v179
	ds_read_b128 v[136:139], v179 offset:1024
	ds_read_b128 v[140:143], v179 offset:2048
	ds_read_b128 v[172:175], v179 offset:3072
	ds_read_b128 v[188:191], v180
	ds_read_b128 v[192:195], v180 offset:1024
	ds_read_b128 v[196:199], v180 offset:2048
	ds_read_b128 v[200:203], v180 offset:3072
	s_add_u32 s46, s42, s44
	s_addc_u32 s47, s43, s45
	s_add_u32 s48, s46, 0x100
	s_addc_u32 s49, s47, 0
	s_add_u32 s46, s94, s44
	s_addc_u32 s47, s95, s45
	s_cmpk_eq_i32 s44, 0xf00
	s_cselect_b32 s47, s29, s47
	s_cselect_b32 s46, s41, s46
	s_cselect_b32 s49, s31, s49
	s_cselect_b32 s48, s39, s48
	v_lshl_add_u64 v[168:169], v[130:131], 0, s[44:45]
	v_lshl_add_u64 v[176:177], v[168:169], 0, s[10:11]
	s_add_i32 m0, s60, 0x8000
	ds_read_b128 v[204:207], v181
	ds_read_b128 v[208:211], v181 offset:1024
	ds_read_b128 v[212:215], v181 offset:2048
	ds_read_b128 v[216:219], v181 offset:3072
	ds_read_b128 v[220:223], v181 offset:4096
	ds_read_b128 v[224:227], v181 offset:5120
	ds_read_b128 v[228:231], v181 offset:6144
	ds_read_b128 v[232:235], v181 offset:7168
	global_load_lds_dwordx4 v[176:177], off
	v_lshl_add_u64 v[176:177], v[128:129], 0, s[44:45]
	v_lshl_add_u64 v[184:185], v[176:177], 0, s[10:11]
	s_add_i32 m0, s60, 0xa000
	v_lshl_add_u64 v[168:169], v[168:169], 0, s[12:13]
	global_load_lds_dwordx4 v[184:185], off
	s_add_i32 m0, s60, 0xc000
	s_nop 0
	global_load_lds_dwordx4 v[168:169], off
	v_lshl_add_u64 v[168:169], v[176:177], 0, s[12:13]
	s_add_i32 m0, s60, 0xe000
	s_nop 0
	global_load_lds_dwordx4 v[168:169], off
	s_waitcnt vmcnt(8)
	s_waitcnt lgkmcnt(0)
	s_setprio 3
	s_barrier
	v_mfma_f32_16x16x32_bf16 v[124:127], v[132:135], v[204:207], 0
	v_mfma_f32_16x16x32_bf16 v[120:123], v[140:143], v[204:207], 0
	v_mfma_f32_16x16x32_bf16 v[108:111], v[132:135], v[212:215], 0
	v_mfma_f32_16x16x32_bf16 v[104:107], v[140:143], v[212:215], 0
	v_mfma_f32_16x16x32_bf16 v[92:95], v[132:135], v[220:223], 0
	v_mfma_f32_16x16x32_bf16 v[88:91], v[140:143], v[220:223], 0
	v_mfma_f32_16x16x32_bf16 v[76:79], v[132:135], v[228:231], 0
	v_mfma_f32_16x16x32_bf16 v[72:75], v[140:143], v[228:231], 0
	v_mfma_f32_16x16x32_bf16 v[124:127], v[136:139], v[208:211], v[124:127]
	v_mfma_f32_16x16x32_bf16 v[120:123], v[172:175], v[208:211], v[120:123]
	v_mfma_f32_16x16x32_bf16 v[108:111], v[136:139], v[216:219], v[108:111]
	v_mfma_f32_16x16x32_bf16 v[104:107], v[172:175], v[216:219], v[104:107]
	v_mfma_f32_16x16x32_bf16 v[92:95], v[136:139], v[224:227], v[92:95]
	v_mfma_f32_16x16x32_bf16 v[88:91], v[172:175], v[224:227], v[88:91]
	v_mfma_f32_16x16x32_bf16 v[76:79], v[136:139], v[232:235], v[76:79]
	v_mfma_f32_16x16x32_bf16 v[72:75], v[172:175], v[232:235], v[72:75]
	s_setprio 0
	s_setprio 3
	v_mfma_f32_16x16x32_bf16 v[116:119], v[188:191], v[204:207], 0
	v_mfma_f32_16x16x32_bf16 v[112:115], v[196:199], v[204:207], 0
	v_mfma_f32_16x16x32_bf16 v[100:103], v[188:191], v[212:215], 0
	v_mfma_f32_16x16x32_bf16 v[96:99], v[196:199], v[212:215], 0
	v_mfma_f32_16x16x32_bf16 v[84:87], v[188:191], v[220:223], 0
	v_mfma_f32_16x16x32_bf16 v[80:83], v[196:199], v[220:223], 0
	v_mfma_f32_16x16x32_bf16 v[68:71], v[188:191], v[228:231], 0
	v_mfma_f32_16x16x32_bf16 v[64:67], v[196:199], v[228:231], 0
	v_mfma_f32_16x16x32_bf16 v[116:119], v[192:195], v[208:211], v[116:119]
	v_mfma_f32_16x16x32_bf16 v[112:115], v[200:203], v[208:211], v[112:115]
	v_mfma_f32_16x16x32_bf16 v[100:103], v[192:195], v[216:219], v[100:103]
	v_mfma_f32_16x16x32_bf16 v[96:99], v[200:203], v[216:219], v[96:99]
	v_mfma_f32_16x16x32_bf16 v[84:87], v[192:195], v[224:227], v[84:87]
	v_mfma_f32_16x16x32_bf16 v[80:83], v[200:203], v[224:227], v[80:83]
	v_mfma_f32_16x16x32_bf16 v[68:71], v[192:195], v[232:235], v[68:71]
	v_mfma_f32_16x16x32_bf16 v[64:67], v[200:203], v[232:235], v[64:67]
	s_setprio 0
	s_barrier
	s_add_i32 s97, s66, s2
	v_lshl_add_u64 v[168:169], s[46:47], 0, v[148:149]
	s_mov_b32 m0, s97
	ds_read_b128 v[204:207], v181 offset:16384
	ds_read_b128 v[208:211], v181 offset:17408
	ds_read_b128 v[212:215], v181 offset:18432
	ds_read_b128 v[216:219], v181 offset:19456
	ds_read_b128 v[220:223], v181 offset:20480
	ds_read_b128 v[224:227], v181 offset:21504
	ds_read_b128 v[228:231], v181 offset:22528
	ds_read_b128 v[232:235], v181 offset:23552
	global_load_lds_dwordx4 v[168:169], off
	s_add_i32 m0, s97, 0x2000
	s_add_u32 vcc_lo, s46, 0x80000
	v_lshl_add_u64 v[176:177], s[46:47], 0, v[144:145]
	s_addc_u32 vcc_hi, s47, 0
	s_add_i32 s97, s67, s2
	global_load_lds_dwordx4 v[176:177], off
	v_lshl_add_u64 v[184:185], vcc, 0, v[148:149]
	s_mov_b32 m0, s97
	s_nop 0
	global_load_lds_dwordx4 v[184:185], off
	v_lshl_add_u64 v[184:185], vcc, 0, v[144:145]
	s_add_i32 m0, s97, 0x2000
	s_nop 0
	global_load_lds_dwordx4 v[184:185], off
	s_waitcnt vmcnt(6)
	s_waitcnt lgkmcnt(0)
	s_setprio 3
	s_barrier
; #define PG8_STAGE(bufoff, gbase, voff) do { _Pragma("unroll") for (int _i = 0; _i < 2; ++_i) \
;         __builtin_amdgcn_global_load_lds((const unsigned*)((const char*)(gbase) + (voff)[_i]), (LAS unsigned*)(lds + (bufoff) + ldsw + _i * 8192), 16, 0, 0); } while (0)
; #define PG8_LDA(dst, b, h) do { _Pragma("unroll") for (int m = 0; m < 4; ++m) _Pragma("unroll") for (int k = 0; k < 2; ++k) dst[m][k] = *(const LAS bf16x8*)(lds + PG8_SA(b, h) + aoff + m * 2048 + k * 1024); } while (0)
; #define PG8_LDB(dst, b, h) do { _Pragma("unroll") for (int n = 0; n < 2; ++n) _Pragma("unroll") for (int k = 0; k < 2; ++k) dst[n][k] = *(const LAS bf16x8*)(lds + PG8_SB(b, h) + boff + n * 2048 + k * 1024); } while (0)
; #define PG8_MMA(ai, bj, At, Bt) do { __builtin_amdgcn_s_setprio(3); _Pragma("unroll") for (int m = 0; m < 4; ++m) _Pragma("unroll") for (int n = 0; n < 2; ++n) _Pragma("unroll") for (int k = 0; k < 2; ++k) \
;         acc[ai][bj][m][n] = __builtin_amdgcn_mfma_f32_16x16x32_bf16(Bt[n][k], At[m][k], acc[ai][bj][m][n], 0, 0, 0); __builtin_amdgcn_s_setprio(0); } while (0)
; #define PG8_WAIT_V(n) asm volatile("s_waitcnt vmcnt(" #n ")" ::: "memory")
; #define PG8_WAIT_L(n) asm volatile("s_waitcnt lgkmcnt(" #n ")" ::: "memory")
; #define PG8_BAR __builtin_amdgcn_s_barrier()
; #define PG8_SCHED __builtin_amdgcn_sched_barrier(0)
; template <class Epi, class Sched>
; __device__ __forceinline__ void gemm_phase(LAS unsigned char* lds, const Gemm g, const Sched& S, const Epi& E, int tid_in) {
;     ...
;             PG8_WAIT_V(6); PG8_WAIT_L(0); PG8_BAR; PG8_MMA(1, 0, At, B0); PG8_MMA(1, 1, At, B1); PG8_BAR; PG8_SCHED;
;             PG8_LDB(B0, 1, 0); PG8_LDB(B1, 1, 1); PG8_SCHED; PG8_LDA(At, 1, 0); PG8_STAGE(PG8_SA(0, 0), a2, voffA); PG8_STAGE(PG8_SA(0, 1), a2 + hstep, voffA);
;             PG8_WAIT_V(8); PG8_WAIT_L(0); PG8_BAR; PG8_MMA(0, 0, At, B0); PG8_MMA(0, 1, At, B1); PG8_BAR; PG8_SCHED;
	v_mfma_f32_16x16x32_bf16 v[60:63], v[132:135], v[204:207], 0
	v_mfma_f32_16x16x32_bf16 v[56:59], v[140:143], v[204:207], 0
	v_mfma_f32_16x16x32_bf16 v[44:47], v[132:135], v[212:215], 0
	v_mfma_f32_16x16x32_bf16 v[40:43], v[140:143], v[212:215], 0
	v_mfma_f32_16x16x32_bf16 v[28:31], v[132:135], v[220:223], 0
	v_mfma_f32_16x16x32_bf16 v[24:27], v[140:143], v[220:223], 0
	v_mfma_f32_16x16x32_bf16 v[12:15], v[132:135], v[228:231], 0
	v_mfma_f32_16x16x32_bf16 v[8:11], v[140:143], v[228:231], 0
	v_mfma_f32_16x16x32_bf16 v[60:63], v[136:139], v[208:211], v[60:63]
	v_mfma_f32_16x16x32_bf16 v[56:59], v[172:175], v[208:211], v[56:59]
	v_mfma_f32_16x16x32_bf16 v[44:47], v[136:139], v[216:219], v[44:47]
	v_mfma_f32_16x16x32_bf16 v[40:43], v[172:175], v[216:219], v[40:43]
	v_mfma_f32_16x16x32_bf16 v[28:31], v[136:139], v[224:227], v[28:31]
	v_mfma_f32_16x16x32_bf16 v[24:27], v[172:175], v[224:227], v[24:27]
	v_mfma_f32_16x16x32_bf16 v[12:15], v[136:139], v[232:235], v[12:15]
	v_mfma_f32_16x16x32_bf16 v[8:11], v[172:175], v[232:235], v[8:11]
	s_setprio 0
	s_setprio 3
	v_mfma_f32_16x16x32_bf16 v[52:55], v[188:191], v[204:207], 0
	v_mfma_f32_16x16x32_bf16 v[48:51], v[196:199], v[204:207], 0
	v_mfma_f32_16x16x32_bf16 v[36:39], v[188:191], v[212:215], 0
	v_mfma_f32_16x16x32_bf16 v[32:35], v[196:199], v[212:215], 0
	v_mfma_f32_16x16x32_bf16 v[20:23], v[188:191], v[220:223], 0
	v_mfma_f32_16x16x32_bf16 v[16:19], v[196:199], v[220:223], 0
	v_mfma_f32_16x16x32_bf16 v[4:7], v[188:191], v[228:231], 0
	v_mfma_f32_16x16x32_bf16 v[0:3], v[196:199], v[228:231], 0
	v_mfma_f32_16x16x32_bf16 v[52:55], v[192:195], v[208:211], v[52:55]
	v_mfma_f32_16x16x32_bf16 v[48:51], v[200:203], v[208:211], v[48:51]
	v_mfma_f32_16x16x32_bf16 v[36:39], v[192:195], v[216:219], v[36:39]
	v_mfma_f32_16x16x32_bf16 v[32:35], v[200:203], v[216:219], v[32:35]
	v_mfma_f32_16x16x32_bf16 v[20:23], v[192:195], v[224:227], v[20:23]
	v_mfma_f32_16x16x32_bf16 v[16:19], v[200:203], v[224:227], v[16:19]
	v_mfma_f32_16x16x32_bf16 v[4:7], v[192:195], v[232:235], v[4:7]
	v_mfma_f32_16x16x32_bf16 v[0:3], v[200:203], v[232:235], v[0:3]
	s_setprio 0
	s_barrier
	s_add_i32 s97, 0, 0x18000
	v_add_u32_e32 v152, s97, v171
	s_add_i32 vcc_lo, 0, 0x1c000
	ds_read_b128 v[132:135], v152
	ds_read_b128 v[136:139], v152 offset:1024
	ds_read_b128 v[140:143], v152 offset:2048
	ds_read_b128 v[172:175], v152 offset:3072
	v_add_u32_e32 v152, vcc_lo, v171
	ds_read_b128 v[188:191], v152
	ds_read_b128 v[192:195], v152 offset:1024
	ds_read_b128 v[196:199], v152 offset:2048
	ds_read_b128 v[200:203], v152 offset:3072
	s_mov_b32 m0, s60
	v_lshl_add_u64 v[184:185], s[48:49], 0, v[150:151]
	ds_read_b128 v[204:207], v181 offset:32768
	ds_read_b128 v[208:211], v181 offset:33792
	ds_read_b128 v[212:215], v181 offset:34816
	ds_read_b128 v[216:219], v181 offset:35840
	ds_read_b128 v[220:223], v181 offset:36864
	ds_read_b128 v[224:227], v181 offset:37888
	ds_read_b128 v[228:231], v181 offset:38912
	ds_read_b128 v[232:235], v181 offset:39936
	global_load_lds_dwordx4 v[184:185], off
	v_lshl_add_u64 v[184:185], s[48:49], 0, v[146:147]
	s_add_u32 s48, s48, 0x80000
	s_mov_b32 m0, s61
	s_addc_u32 s49, s49, 0
	global_load_lds_dwordx4 v[184:185], off
	v_lshl_add_u64 v[184:185], s[48:49], 0, v[150:151]
	s_mov_b32 m0, s62
	s_nop 0
	global_load_lds_dwordx4 v[184:185], off
	v_lshl_add_u64 v[184:185], s[48:49], 0, v[146:147]
	s_mov_b32 m0, s63
	s_nop 0
	global_load_lds_dwordx4 v[184:185], off
	s_waitcnt vmcnt(8)
	s_waitcnt lgkmcnt(0)
	s_setprio 3
	s_barrier
	v_mfma_f32_16x16x32_bf16 v[124:127], v[132:135], v[204:207], v[124:127]
	v_mfma_f32_16x16x32_bf16 v[120:123], v[140:143], v[204:207], v[120:123]
	v_mfma_f32_16x16x32_bf16 v[108:111], v[132:135], v[212:215], v[108:111]
	v_mfma_f32_16x16x32_bf16 v[104:107], v[140:143], v[212:215], v[104:107]
	v_mfma_f32_16x16x32_bf16 v[92:95], v[132:135], v[220:223], v[92:95]
	v_mfma_f32_16x16x32_bf16 v[88:91], v[140:143], v[220:223], v[88:91]
	v_mfma_f32_16x16x32_bf16 v[76:79], v[132:135], v[228:231], v[76:79]
	v_mfma_f32_16x16x32_bf16 v[72:75], v[140:143], v[228:231], v[72:75]
	v_mfma_f32_16x16x32_bf16 v[124:127], v[136:139], v[208:211], v[124:127]
	v_mfma_f32_16x16x32_bf16 v[120:123], v[172:175], v[208:211], v[120:123]
	v_mfma_f32_16x16x32_bf16 v[108:111], v[136:139], v[216:219], v[108:111]
	v_mfma_f32_16x16x32_bf16 v[104:107], v[172:175], v[216:219], v[104:107]
	v_mfma_f32_16x16x32_bf16 v[92:95], v[136:139], v[224:227], v[92:95]
	v_mfma_f32_16x16x32_bf16 v[88:91], v[172:175], v[224:227], v[88:91]
	v_mfma_f32_16x16x32_bf16 v[76:79], v[136:139], v[232:235], v[76:79]
	v_mfma_f32_16x16x32_bf16 v[72:75], v[172:175], v[232:235], v[72:75]
	s_setprio 0
	s_setprio 3
	v_mfma_f32_16x16x32_bf16 v[116:119], v[188:191], v[204:207], v[116:119]
	v_mfma_f32_16x16x32_bf16 v[112:115], v[196:199], v[204:207], v[112:115]
	v_mfma_f32_16x16x32_bf16 v[100:103], v[188:191], v[212:215], v[100:103]
	v_mfma_f32_16x16x32_bf16 v[96:99], v[196:199], v[212:215], v[96:99]
	v_mfma_f32_16x16x32_bf16 v[84:87], v[188:191], v[220:223], v[84:87]
	v_mfma_f32_16x16x32_bf16 v[80:83], v[196:199], v[220:223], v[80:83]
	v_mfma_f32_16x16x32_bf16 v[68:71], v[188:191], v[228:231], v[68:71]
	v_mfma_f32_16x16x32_bf16 v[64:67], v[196:199], v[228:231], v[64:67]
	v_mfma_f32_16x16x32_bf16 v[116:119], v[192:195], v[208:211], v[116:119]
	v_mfma_f32_16x16x32_bf16 v[112:115], v[200:203], v[208:211], v[112:115]
	v_mfma_f32_16x16x32_bf16 v[100:103], v[192:195], v[216:219], v[100:103]
	v_mfma_f32_16x16x32_bf16 v[96:99], v[200:203], v[216:219], v[96:99]
	v_mfma_f32_16x16x32_bf16 v[84:87], v[192:195], v[224:227], v[84:87]
	v_mfma_f32_16x16x32_bf16 v[80:83], v[200:203], v[224:227], v[80:83]
	v_mfma_f32_16x16x32_bf16 v[68:71], v[192:195], v[232:235], v[68:71]
	v_mfma_f32_16x16x32_bf16 v[64:67], v[200:203], v[232:235], v[64:67]
	s_setprio 0
	s_barrier
; #define PG8_STAGE(bufoff, gbase, voff) do { _Pragma("unroll") for (int _i = 0; _i < 2; ++_i) \
;         __builtin_amdgcn_global_load_lds((const unsigned*)((const char*)(gbase) + (voff)[_i]), (LAS unsigned*)(lds + (bufoff) + ldsw + _i * 8192), 16, 0, 0); } while (0)
; #define PG8_LDA(dst, b, h) do { _Pragma("unroll") for (int m = 0; m < 4; ++m) _Pragma("unroll") for (int k = 0; k < 2; ++k) dst[m][k] = *(const LAS bf16x8*)(lds + PG8_SA(b, h) + aoff + m * 2048 + k * 1024); } while (0)
; #define PG8_LDB(dst, b, h) do { _Pragma("unroll") for (int n = 0; n < 2; ++n) _Pragma("unroll") for (int k = 0; k < 2; ++k) dst[n][k] = *(const LAS bf16x8*)(lds + PG8_SB(b, h) + boff + n * 2048 + k * 1024); } while (0)
; #define PG8_MMA(ai, bj, At, Bt) do { __builtin_amdgcn_s_setprio(3); _Pragma("unroll") for (int m = 0; m < 4; ++m) _Pragma("unroll") for (int n = 0; n < 2; ++n) _Pragma("unroll") for (int k = 0; k < 2; ++k) \
;         acc[ai][bj][m][n] = __builtin_amdgcn_mfma_f32_16x16x32_bf16(Bt[n][k], At[m][k], acc[ai][bj][m][n], 0, 0, 0); __builtin_amdgcn_s_setprio(0); } while (0)
; #define PG8_WAIT_V(n) asm volatile("s_waitcnt vmcnt(" #n ")" ::: "memory")
; #define PG8_BAR __builtin_amdgcn_s_barrier()
; template <class Epi, class Sched>
; __device__ __forceinline__ void gemm_phase(LAS unsigned char* lds, const Gemm g, const Sched& S, const Epi& E, int tid_in) {
;     ...
;             PG8_LDB(B0, 0, 0); PG8_LDB(B1, 0, 1); PG8_SCHED; PG8_LDA(At, 0, 0); PG8_STAGE(PG8_SA(1, 0), a1, voffA); PG8_STAGE(PG8_SA(1, 1), a1 + hstep, voffA);
;             PG8_WAIT_V(8); PG8_WAIT_L(0); PG8_BAR; PG8_MMA(0, 0, At, B0); PG8_MMA(0, 1, At, B1); PG8_BAR; PG8_SCHED;
;             PG8_LDA(At, 0, 1); PG8_STAGE(PG8_SB(0, 0), b2, voffB); PG8_STAGE(PG8_SB(0, 1), b2 + hstep, voffB);
;             PG8_WAIT_V(6); PG8_WAIT_L(0); PG8_BAR; PG8_MMA(1, 0, At, B0); PG8_MMA(1, 1, At, B1); PG8_BAR; PG8_SCHED;
;             PG8_LDB(B0, 1, 0); PG8_LDB(B1, 1, 1); PG8_SCHED; PG8_LDA(At, 1, 0); PG8_STAGE(PG8_SA(0, 0), a2, voffA); PG8_STAGE(PG8_SA(0, 1), a2 + hstep, voffA);
;             PG8_WAIT_V(8); PG8_WAIT_L(0); PG8_BAR; PG8_MMA(0, 0, At, B0); PG8_MMA(0, 1, At, B1); PG8_BAR; PG8_SCHED;
;             PG8_LDA(At, 1, 1); PG8_STAGE(PG8_SB(1, 0), b3, voffB); PG8_STAGE(PG8_SB(1, 1), b3 + hstep, voffB);
;             PG8_WAIT_V(6); PG8_WAIT_L(0); PG8_BAR; PG8_MMA(1, 0, At, B0); PG8_MMA(1, 1, At, B1); PG8_BAR; PG8_SCHED;
	s_add_i32 s48, s97, s2
	v_lshl_add_u64 v[168:169], v[168:169], 0, s[10:11]
	s_mov_b32 m0, s48
	ds_read_b128 v[204:207], v181 offset:49152
	ds_read_b128 v[208:211], v181 offset:50176
	ds_read_b128 v[212:215], v181 offset:51200
	ds_read_b128 v[216:219], v181 offset:52224
	ds_read_b128 v[220:223], v181 offset:53248
	ds_read_b128 v[224:227], v181 offset:54272
	ds_read_b128 v[228:231], v181 offset:55296
	ds_read_b128 v[232:235], v181 offset:56320
	global_load_lds_dwordx4 v[168:169], off
	s_add_i32 m0, s48, 0x2000
	s_add_u32 s46, s46, 0x80080
	v_lshl_add_u64 v[168:169], v[176:177], 0, s[10:11]
	s_addc_u32 s47, s47, 0
	s_add_i32 s48, vcc_lo, s2
	global_load_lds_dwordx4 v[168:169], off
	v_lshl_add_u64 v[168:169], s[46:47], 0, v[148:149]
	s_mov_b32 m0, s48
	s_nop 0
	global_load_lds_dwordx4 v[168:169], off
	v_lshl_add_u64 v[168:169], s[46:47], 0, v[144:145]
	s_add_i32 m0, s48, 0x2000
	s_nop 0
	global_load_lds_dwordx4 v[168:169], off
	s_waitcnt vmcnt(6)
	s_waitcnt lgkmcnt(0)
	s_setprio 3
	s_barrier
	v_mfma_f32_16x16x32_bf16 v[60:63], v[132:135], v[204:207], v[60:63]
	v_mfma_f32_16x16x32_bf16 v[56:59], v[140:143], v[204:207], v[56:59]
	v_mfma_f32_16x16x32_bf16 v[44:47], v[132:135], v[212:215], v[44:47]
	v_mfma_f32_16x16x32_bf16 v[40:43], v[140:143], v[212:215], v[40:43]
	v_mfma_f32_16x16x32_bf16 v[28:31], v[132:135], v[220:223], v[28:31]
	v_mfma_f32_16x16x32_bf16 v[24:27], v[140:143], v[220:223], v[24:27]
	v_mfma_f32_16x16x32_bf16 v[12:15], v[132:135], v[228:231], v[12:15]
	v_mfma_f32_16x16x32_bf16 v[8:11], v[140:143], v[228:231], v[8:11]
	v_mfma_f32_16x16x32_bf16 v[60:63], v[136:139], v[208:211], v[60:63]
	v_mfma_f32_16x16x32_bf16 v[56:59], v[172:175], v[208:211], v[56:59]
	v_mfma_f32_16x16x32_bf16 v[44:47], v[136:139], v[216:219], v[44:47]
	v_mfma_f32_16x16x32_bf16 v[40:43], v[172:175], v[216:219], v[40:43]
	v_mfma_f32_16x16x32_bf16 v[28:31], v[136:139], v[224:227], v[28:31]
	v_mfma_f32_16x16x32_bf16 v[24:27], v[172:175], v[224:227], v[24:27]
	v_mfma_f32_16x16x32_bf16 v[12:15], v[136:139], v[232:235], v[12:15]
	v_mfma_f32_16x16x32_bf16 v[8:11], v[172:175], v[232:235], v[8:11]
	s_setprio 0
	s_setprio 3
	v_mfma_f32_16x16x32_bf16 v[52:55], v[188:191], v[204:207], v[52:55]
	v_mfma_f32_16x16x32_bf16 v[48:51], v[196:199], v[204:207], v[48:51]
	v_mfma_f32_16x16x32_bf16 v[36:39], v[188:191], v[212:215], v[36:39]
	v_mfma_f32_16x16x32_bf16 v[32:35], v[196:199], v[212:215], v[32:35]
	v_mfma_f32_16x16x32_bf16 v[20:23], v[188:191], v[220:223], v[20:23]
	v_mfma_f32_16x16x32_bf16 v[16:19], v[196:199], v[220:223], v[16:19]
	v_mfma_f32_16x16x32_bf16 v[4:7], v[188:191], v[228:231], v[4:7]
	v_mfma_f32_16x16x32_bf16 v[0:3], v[196:199], v[228:231], v[0:3]
	v_mfma_f32_16x16x32_bf16 v[52:55], v[192:195], v[208:211], v[52:55]
	v_mfma_f32_16x16x32_bf16 v[48:51], v[200:203], v[208:211], v[48:51]
	v_mfma_f32_16x16x32_bf16 v[36:39], v[192:195], v[216:219], v[36:39]
	v_mfma_f32_16x16x32_bf16 v[32:35], v[200:203], v[216:219], v[32:35]
	v_mfma_f32_16x16x32_bf16 v[20:23], v[192:195], v[224:227], v[20:23]
	v_mfma_f32_16x16x32_bf16 v[16:19], v[200:203], v[224:227], v[16:19]
	v_mfma_f32_16x16x32_bf16 v[4:7], v[192:195], v[232:235], v[4:7]
	v_mfma_f32_16x16x32_bf16 v[0:3], v[200:203], v[232:235], v[0:3]
	s_setprio 0
	s_barrier
	s_add_i32 s96, s96, 2
	s_add_u32 s44, s44, 0x100
	s_addc_u32 s45, s45, 0
	s_cmp_gt_u32 s96, 29
	s_cbranch_scc0 .LBB0_102
	s_branch .Lpeel_exit_0
.LBB0_102:
	ds_read_b128 v[132:135], v179
	ds_read_b128 v[136:139], v179 offset:1024
	ds_read_b128 v[140:143], v179 offset:2048
	ds_read_b128 v[172:175], v179 offset:3072
	ds_read_b128 v[188:191], v180
	ds_read_b128 v[192:195], v180 offset:1024
	ds_read_b128 v[196:199], v180 offset:2048
	ds_read_b128 v[200:203], v180 offset:3072
	s_add_u32 s46, s42, s44
	s_addc_u32 s47, s43, s45
	s_add_u32 s48, s46, 0x100
	s_addc_u32 s49, s47, 0
	s_add_u32 s46, s94, s44
	s_addc_u32 s47, s95, s45
	s_cmpk_eq_i32 s44, 0xf00
	s_cselect_b32 s47, s29, s47
	s_cselect_b32 s46, s41, s46
	s_cselect_b32 s49, s31, s49
	s_cselect_b32 s48, s39, s48
	v_lshl_add_u64 v[168:169], v[130:131], 0, s[44:45]
	v_lshl_add_u64 v[176:177], v[168:169], 0, s[10:11]
	s_add_i32 m0, s60, 0x8000
	ds_read_b128 v[204:207], v181
	ds_read_b128 v[208:211], v181 offset:1024
	ds_read_b128 v[212:215], v181 offset:2048
	ds_read_b128 v[216:219], v181 offset:3072
	ds_read_b128 v[220:223], v181 offset:4096
	ds_read_b128 v[224:227], v181 offset:5120
	ds_read_b128 v[228:231], v181 offset:6144
	ds_read_b128 v[232:235], v181 offset:7168
	global_load_lds_dwordx4 v[176:177], off
	v_lshl_add_u64 v[176:177], v[128:129], 0, s[44:45]
	v_lshl_add_u64 v[184:185], v[176:177], 0, s[10:11]
	s_add_i32 m0, s60, 0xa000
	v_lshl_add_u64 v[168:169], v[168:169], 0, s[12:13]
	global_load_lds_dwordx4 v[184:185], off
	s_add_i32 m0, s60, 0xc000
	s_nop 0
	global_load_lds_dwordx4 v[168:169], off
	v_lshl_add_u64 v[168:169], v[176:177], 0, s[12:13]
	s_add_i32 m0, s60, 0xe000
	s_nop 0
	global_load_lds_dwordx4 v[168:169], off
	s_waitcnt vmcnt(8)
	s_waitcnt lgkmcnt(0)
	s_setprio 3
	s_barrier
; #define PG8_STAGE(bufoff, gbase, voff) do { _Pragma("unroll") for (int _i = 0; _i < 2; ++_i) \
;         __builtin_amdgcn_global_load_lds((const unsigned*)((const char*)(gbase) + (voff)[_i]), (LAS unsigned*)(lds + (bufoff) + ldsw + _i * 8192), 16, 0, 0); } while (0)
; #define PG8_LDA(dst, b, h) do { _Pragma("unroll") for (int m = 0; m < 4; ++m) _Pragma("unroll") for (int k = 0; k < 2; ++k) dst[m][k] = *(const LAS bf16x8*)(lds + PG8_SA(b, h) + aoff + m * 2048 + k * 1024); } while (0)
; #define PG8_MMA(ai, bj, At, Bt) do { __builtin_amdgcn_s_setprio(3); _Pragma("unroll") for (int m = 0; m < 4; ++m) _Pragma("unroll") for (int n = 0; n < 2; ++n) _Pragma("unroll") for (int k = 0; k < 2; ++k) \
;         acc[ai][bj][m][n] = __builtin_amdgcn_mfma_f32_16x16x32_bf16(Bt[n][k], At[m][k], acc[ai][bj][m][n], 0, 0, 0); __builtin_amdgcn_s_setprio(0); } while (0)
; #define PG8_WAIT_V(n) asm volatile("s_waitcnt vmcnt(" #n ")" ::: "memory")
; #define PG8_WAIT_L(n) asm volatile("s_waitcnt lgkmcnt(" #n ")" ::: "memory")
; #define PG8_BAR __builtin_amdgcn_s_barrier()
; #define PG8_SCHED __builtin_amdgcn_sched_barrier(0)
; template <class Epi, class Sched>
; __device__ __forceinline__ void gemm_phase(LAS unsigned char* lds, const Gemm g, const Sched& S, const Epi& E, int tid_in) {
;     ...
;             PG8_WAIT_V(8); PG8_WAIT_L(0); PG8_BAR; PG8_MMA(0, 0, At, B0); PG8_MMA(0, 1, At, B1); PG8_BAR; PG8_SCHED;
;             PG8_LDA(At, 0, 1); PG8_STAGE(PG8_SB(0, 0), b2, voffB); PG8_STAGE(PG8_SB(0, 1), b2 + hstep, voffB);
;             PG8_WAIT_V(6); PG8_WAIT_L(0); PG8_BAR; PG8_MMA(1, 0, At, B0); PG8_MMA(1, 1, At, B1); PG8_BAR; PG8_SCHED;
	v_mfma_f32_16x16x32_bf16 v[124:127], v[132:135], v[204:207], v[124:127]
	v_mfma_f32_16x16x32_bf16 v[120:123], v[140:143], v[204:207], v[120:123]
	v_mfma_f32_16x16x32_bf16 v[108:111], v[132:135], v[212:215], v[108:111]
	v_mfma_f32_16x16x32_bf16 v[104:107], v[140:143], v[212:215], v[104:107]
	v_mfma_f32_16x16x32_bf16 v[92:95], v[132:135], v[220:223], v[92:95]
	v_mfma_f32_16x16x32_bf16 v[88:91], v[140:143], v[220:223], v[88:91]
	v_mfma_f32_16x16x32_bf16 v[76:79], v[132:135], v[228:231], v[76:79]
	v_mfma_f32_16x16x32_bf16 v[72:75], v[140:143], v[228:231], v[72:75]
	v_mfma_f32_16x16x32_bf16 v[124:127], v[136:139], v[208:211], v[124:127]
	v_mfma_f32_16x16x32_bf16 v[120:123], v[172:175], v[208:211], v[120:123]
	v_mfma_f32_16x16x32_bf16 v[108:111], v[136:139], v[216:219], v[108:111]
	v_mfma_f32_16x16x32_bf16 v[104:107], v[172:175], v[216:219], v[104:107]
	v_mfma_f32_16x16x32_bf16 v[92:95], v[136:139], v[224:227], v[92:95]
	v_mfma_f32_16x16x32_bf16 v[88:91], v[172:175], v[224:227], v[88:91]
	v_mfma_f32_16x16x32_bf16 v[76:79], v[136:139], v[232:235], v[76:79]
	v_mfma_f32_16x16x32_bf16 v[72:75], v[172:175], v[232:235], v[72:75]
	s_setprio 0
	s_setprio 3
	v_mfma_f32_16x16x32_bf16 v[116:119], v[188:191], v[204:207], v[116:119]
	v_mfma_f32_16x16x32_bf16 v[112:115], v[196:199], v[204:207], v[112:115]
	v_mfma_f32_16x16x32_bf16 v[100:103], v[188:191], v[212:215], v[100:103]
	v_mfma_f32_16x16x32_bf16 v[96:99], v[196:199], v[212:215], v[96:99]
	v_mfma_f32_16x16x32_bf16 v[84:87], v[188:191], v[220:223], v[84:87]
	v_mfma_f32_16x16x32_bf16 v[80:83], v[196:199], v[220:223], v[80:83]
	v_mfma_f32_16x16x32_bf16 v[68:71], v[188:191], v[228:231], v[68:71]
	v_mfma_f32_16x16x32_bf16 v[64:67], v[196:199], v[228:231], v[64:67]
	v_mfma_f32_16x16x32_bf16 v[116:119], v[192:195], v[208:211], v[116:119]
	v_mfma_f32_16x16x32_bf16 v[112:115], v[200:203], v[208:211], v[112:115]
	v_mfma_f32_16x16x32_bf16 v[100:103], v[192:195], v[216:219], v[100:103]
	v_mfma_f32_16x16x32_bf16 v[96:99], v[200:203], v[216:219], v[96:99]
	v_mfma_f32_16x16x32_bf16 v[84:87], v[192:195], v[224:227], v[84:87]
	v_mfma_f32_16x16x32_bf16 v[80:83], v[200:203], v[224:227], v[80:83]
	v_mfma_f32_16x16x32_bf16 v[68:71], v[192:195], v[232:235], v[68:71]
	v_mfma_f32_16x16x32_bf16 v[64:67], v[200:203], v[232:235], v[64:67]
	s_setprio 0
	s_barrier
	s_add_i32 s97, s66, s2
	v_lshl_add_u64 v[168:169], s[46:47], 0, v[148:149]
	s_mov_b32 m0, s97
	ds_read_b128 v[204:207], v181 offset:16384
	ds_read_b128 v[208:211], v181 offset:17408
	ds_read_b128 v[212:215], v181 offset:18432
	ds_read_b128 v[216:219], v181 offset:19456
	ds_read_b128 v[220:223], v181 offset:20480
	ds_read_b128 v[224:227], v181 offset:21504
	ds_read_b128 v[228:231], v181 offset:22528
	ds_read_b128 v[232:235], v181 offset:23552
	global_load_lds_dwordx4 v[168:169], off
	s_add_i32 m0, s97, 0x2000
	s_add_u32 vcc_lo, s46, 0x80000
	v_lshl_add_u64 v[176:177], s[46:47], 0, v[144:145]
	s_addc_u32 vcc_hi, s47, 0
	s_add_i32 s97, s67, s2
	global_load_lds_dwordx4 v[176:177], off
	v_lshl_add_u64 v[184:185], vcc, 0, v[148:149]
	s_mov_b32 m0, s97
	s_nop 0
	global_load_lds_dwordx4 v[184:185], off
	v_lshl_add_u64 v[184:185], vcc, 0, v[144:145]
	s_add_i32 m0, s97, 0x2000
	s_nop 0
	global_load_lds_dwordx4 v[184:185], off
	s_waitcnt vmcnt(6)
	s_waitcnt lgkmcnt(0)
	s_setprio 3
	s_barrier
	v_mfma_f32_16x16x32_bf16 v[60:63], v[132:135], v[204:207], v[60:63]
	v_mfma_f32_16x16x32_bf16 v[56:59], v[140:143], v[204:207], v[56:59]
	v_mfma_f32_16x16x32_bf16 v[44:47], v[132:135], v[212:215], v[44:47]
	v_mfma_f32_16x16x32_bf16 v[40:43], v[140:143], v[212:215], v[40:43]
	v_mfma_f32_16x16x32_bf16 v[28:31], v[132:135], v[220:223], v[28:31]
	v_mfma_f32_16x16x32_bf16 v[24:27], v[140:143], v[220:223], v[24:27]
	v_mfma_f32_16x16x32_bf16 v[12:15], v[132:135], v[228:231], v[12:15]
	v_mfma_f32_16x16x32_bf16 v[8:11], v[140:143], v[228:231], v[8:11]
	v_mfma_f32_16x16x32_bf16 v[60:63], v[136:139], v[208:211], v[60:63]
	v_mfma_f32_16x16x32_bf16 v[56:59], v[172:175], v[208:211], v[56:59]
	v_mfma_f32_16x16x32_bf16 v[44:47], v[136:139], v[216:219], v[44:47]
	v_mfma_f32_16x16x32_bf16 v[40:43], v[172:175], v[216:219], v[40:43]
	v_mfma_f32_16x16x32_bf16 v[28:31], v[136:139], v[224:227], v[28:31]
	v_mfma_f32_16x16x32_bf16 v[24:27], v[172:175], v[224:227], v[24:27]
	v_mfma_f32_16x16x32_bf16 v[12:15], v[136:139], v[232:235], v[12:15]
	v_mfma_f32_16x16x32_bf16 v[8:11], v[172:175], v[232:235], v[8:11]
	s_setprio 0
	s_setprio 3
	v_mfma_f32_16x16x32_bf16 v[52:55], v[188:191], v[204:207], v[52:55]
	v_mfma_f32_16x16x32_bf16 v[48:51], v[196:199], v[204:207], v[48:51]
	v_mfma_f32_16x16x32_bf16 v[36:39], v[188:191], v[212:215], v[36:39]
	v_mfma_f32_16x16x32_bf16 v[32:35], v[196:199], v[212:215], v[32:35]
	v_mfma_f32_16x16x32_bf16 v[20:23], v[188:191], v[220:223], v[20:23]
	v_mfma_f32_16x16x32_bf16 v[16:19], v[196:199], v[220:223], v[16:19]
	v_mfma_f32_16x16x32_bf16 v[4:7], v[188:191], v[228:231], v[4:7]
	v_mfma_f32_16x16x32_bf16 v[0:3], v[196:199], v[228:231], v[0:3]
	v_mfma_f32_16x16x32_bf16 v[52:55], v[192:195], v[208:211], v[52:55]
	v_mfma_f32_16x16x32_bf16 v[48:51], v[200:203], v[208:211], v[48:51]
	v_mfma_f32_16x16x32_bf16 v[36:39], v[192:195], v[216:219], v[36:39]
	v_mfma_f32_16x16x32_bf16 v[32:35], v[200:203], v[216:219], v[32:35]
	v_mfma_f32_16x16x32_bf16 v[20:23], v[192:195], v[224:227], v[20:23]
	v_mfma_f32_16x16x32_bf16 v[16:19], v[200:203], v[224:227], v[16:19]
	v_mfma_f32_16x16x32_bf16 v[4:7], v[192:195], v[232:235], v[4:7]
	v_mfma_f32_16x16x32_bf16 v[0:3], v[200:203], v[232:235], v[0:3]
	s_setprio 0
	s_barrier
; #define PG8_STAGE(bufoff, gbase, voff) do { _Pragma("unroll") for (int _i = 0; _i < 2; ++_i) \
;         __builtin_amdgcn_global_load_lds((const unsigned*)((const char*)(gbase) + (voff)[_i]), (LAS unsigned*)(lds + (bufoff) + ldsw + _i * 8192), 16, 0, 0); } while (0)
; #define PG8_LDA(dst, b, h) do { _Pragma("unroll") for (int m = 0; m < 4; ++m) _Pragma("unroll") for (int k = 0; k < 2; ++k) dst[m][k] = *(const LAS bf16x8*)(lds + PG8_SA(b, h) + aoff + m * 2048 + k * 1024); } while (0)
; #define PG8_LDB(dst, b, h) do { _Pragma("unroll") for (int n = 0; n < 2; ++n) _Pragma("unroll") for (int k = 0; k < 2; ++k) dst[n][k] = *(const LAS bf16x8*)(lds + PG8_SB(b, h) + boff + n * 2048 + k * 1024); } while (0)
; #define PG8_MMA(ai, bj, At, Bt) do { __builtin_amdgcn_s_setprio(3); _Pragma("unroll") for (int m = 0; m < 4; ++m) _Pragma("unroll") for (int n = 0; n < 2; ++n) _Pragma("unroll") for (int k = 0; k < 2; ++k) \
;         acc[ai][bj][m][n] = __builtin_amdgcn_mfma_f32_16x16x32_bf16(Bt[n][k], At[m][k], acc[ai][bj][m][n], 0, 0, 0); __builtin_amdgcn_s_setprio(0); } while (0)
; #define PG8_WAIT_V(n) asm volatile("s_waitcnt vmcnt(" #n ")" ::: "memory")
; #define PG8_WAIT_L(n) asm volatile("s_waitcnt lgkmcnt(" #n ")" ::: "memory")
; #define PG8_BAR __builtin_amdgcn_s_barrier()
; #define PG8_SCHED __builtin_amdgcn_sched_barrier(0)
; template <class Epi, class Sched>
; __device__ __forceinline__ void gemm_phase(LAS unsigned char* lds, const Gemm g, const Sched& S, const Epi& E, int tid_in) {
;     ...
;             PG8_LDB(B0, 1, 0); PG8_LDB(B1, 1, 1); PG8_SCHED; PG8_LDA(At, 1, 0); PG8_STAGE(PG8_SA(0, 0), a2, voffA); PG8_STAGE(PG8_SA(0, 1), a2 + hstep, voffA);
;             PG8_WAIT_V(8); PG8_WAIT_L(0); PG8_BAR; PG8_MMA(0, 0, At, B0); PG8_MMA(0, 1, At, B1); PG8_BAR; PG8_SCHED;
	s_add_i32 s97, 0, 0x18000
	v_add_u32_e32 v152, s97, v171
	s_add_i32 vcc_lo, 0, 0x1c000
	ds_read_b128 v[132:135], v152
	ds_read_b128 v[136:139], v152 offset:1024
	ds_read_b128 v[140:143], v152 offset:2048
	ds_read_b128 v[172:175], v152 offset:3072
	v_add_u32_e32 v152, vcc_lo, v171
	ds_read_b128 v[188:191], v152
	ds_read_b128 v[192:195], v152 offset:1024
	ds_read_b128 v[196:199], v152 offset:2048
	ds_read_b128 v[200:203], v152 offset:3072
	s_mov_b32 m0, s60
	v_lshl_add_u64 v[184:185], s[48:49], 0, v[150:151]
	ds_read_b128 v[204:207], v181 offset:32768
	ds_read_b128 v[208:211], v181 offset:33792
	ds_read_b128 v[212:215], v181 offset:34816
	ds_read_b128 v[216:219], v181 offset:35840
	ds_read_b128 v[220:223], v181 offset:36864
	ds_read_b128 v[224:227], v181 offset:37888
	ds_read_b128 v[228:231], v181 offset:38912
	ds_read_b128 v[232:235], v181 offset:39936
	global_load_lds_dwordx4 v[184:185], off
	v_lshl_add_u64 v[184:185], s[48:49], 0, v[146:147]
	s_add_u32 s48, s48, 0x80000
	s_mov_b32 m0, s61
	s_addc_u32 s49, s49, 0
	global_load_lds_dwordx4 v[184:185], off
	v_lshl_add_u64 v[184:185], s[48:49], 0, v[150:151]
	s_mov_b32 m0, s62
	s_nop 0
	global_load_lds_dwordx4 v[184:185], off
	v_lshl_add_u64 v[184:185], s[48:49], 0, v[146:147]
	s_mov_b32 m0, s63
	s_nop 0
	global_load_lds_dwordx4 v[184:185], off
	s_waitcnt vmcnt(8)
	s_waitcnt lgkmcnt(0)
	s_setprio 3
	s_barrier
	v_mfma_f32_16x16x32_bf16 v[124:127], v[132:135], v[204:207], v[124:127]
	v_mfma_f32_16x16x32_bf16 v[120:123], v[140:143], v[204:207], v[120:123]
	v_mfma_f32_16x16x32_bf16 v[108:111], v[132:135], v[212:215], v[108:111]
	v_mfma_f32_16x16x32_bf16 v[104:107], v[140:143], v[212:215], v[104:107]
	v_mfma_f32_16x16x32_bf16 v[92:95], v[132:135], v[220:223], v[92:95]
	v_mfma_f32_16x16x32_bf16 v[88:91], v[140:143], v[220:223], v[88:91]
	v_mfma_f32_16x16x32_bf16 v[76:79], v[132:135], v[228:231], v[76:79]
	v_mfma_f32_16x16x32_bf16 v[72:75], v[140:143], v[228:231], v[72:75]
	v_mfma_f32_16x16x32_bf16 v[124:127], v[136:139], v[208:211], v[124:127]
	v_mfma_f32_16x16x32_bf16 v[120:123], v[172:175], v[208:211], v[120:123]
	v_mfma_f32_16x16x32_bf16 v[108:111], v[136:139], v[216:219], v[108:111]
	v_mfma_f32_16x16x32_bf16 v[104:107], v[172:175], v[216:219], v[104:107]
	v_mfma_f32_16x16x32_bf16 v[92:95], v[136:139], v[224:227], v[92:95]
	v_mfma_f32_16x16x32_bf16 v[88:91], v[172:175], v[224:227], v[88:91]
	v_mfma_f32_16x16x32_bf16 v[76:79], v[136:139], v[232:235], v[76:79]
	v_mfma_f32_16x16x32_bf16 v[72:75], v[172:175], v[232:235], v[72:75]
	s_setprio 0
	s_setprio 3
	v_mfma_f32_16x16x32_bf16 v[116:119], v[188:191], v[204:207], v[116:119]
	v_mfma_f32_16x16x32_bf16 v[112:115], v[196:199], v[204:207], v[112:115]
	v_mfma_f32_16x16x32_bf16 v[100:103], v[188:191], v[212:215], v[100:103]
	v_mfma_f32_16x16x32_bf16 v[96:99], v[196:199], v[212:215], v[96:99]
	v_mfma_f32_16x16x32_bf16 v[84:87], v[188:191], v[220:223], v[84:87]
	v_mfma_f32_16x16x32_bf16 v[80:83], v[196:199], v[220:223], v[80:83]
	v_mfma_f32_16x16x32_bf16 v[68:71], v[188:191], v[228:231], v[68:71]
	v_mfma_f32_16x16x32_bf16 v[64:67], v[196:199], v[228:231], v[64:67]
	v_mfma_f32_16x16x32_bf16 v[116:119], v[192:195], v[208:211], v[116:119]
	v_mfma_f32_16x16x32_bf16 v[112:115], v[200:203], v[208:211], v[112:115]
	v_mfma_f32_16x16x32_bf16 v[100:103], v[192:195], v[216:219], v[100:103]
	v_mfma_f32_16x16x32_bf16 v[96:99], v[200:203], v[216:219], v[96:99]
	v_mfma_f32_16x16x32_bf16 v[84:87], v[192:195], v[224:227], v[84:87]
	v_mfma_f32_16x16x32_bf16 v[80:83], v[200:203], v[224:227], v[80:83]
	v_mfma_f32_16x16x32_bf16 v[68:71], v[192:195], v[232:235], v[68:71]
	v_mfma_f32_16x16x32_bf16 v[64:67], v[200:203], v[232:235], v[64:67]
	s_setprio 0
	s_barrier
; #define PG8_STAGE(bufoff, gbase, voff) do { _Pragma("unroll") for (int _i = 0; _i < 2; ++_i) \
;         __builtin_amdgcn_global_load_lds((const unsigned*)((const char*)(gbase) + (voff)[_i]), (LAS unsigned*)(lds + (bufoff) + ldsw + _i * 8192), 16, 0, 0); } while (0)
; #define PG8_LDA(dst, b, h) do { _Pragma("unroll") for (int m = 0; m < 4; ++m) _Pragma("unroll") for (int k = 0; k < 2; ++k) dst[m][k] = *(const LAS bf16x8*)(lds + PG8_SA(b, h) + aoff + m * 2048 + k * 1024); } while (0)
; #define PG8_MMA(ai, bj, At, Bt) do { __builtin_amdgcn_s_setprio(3); _Pragma("unroll") for (int m = 0; m < 4; ++m) _Pragma("unroll") for (int n = 0; n < 2; ++n) _Pragma("unroll") for (int k = 0; k < 2; ++k) \
;         acc[ai][bj][m][n] = __builtin_amdgcn_mfma_f32_16x16x32_bf16(Bt[n][k], At[m][k], acc[ai][bj][m][n], 0, 0, 0); __builtin_amdgcn_s_setprio(0); } while (0)
; #define PG8_WAIT_V(n) asm volatile("s_waitcnt vmcnt(" #n ")" ::: "memory")
; #define PG8_WAIT_L(n) asm volatile("s_waitcnt lgkmcnt(" #n ")" ::: "memory")
; #define PG8_BAR __builtin_amdgcn_s_barrier()
; #define PG8_SCHED __builtin_amdgcn_sched_barrier(0)
; template <class Epi, class Sched>
; __device__ __forceinline__ void gemm_phase(LAS unsigned char* lds, const Gemm g, const Sched& S, const Epi& E, int tid_in) {
;     ...
;         for (int t = 0; t < nt; t += 2) {
;     ...
;             PG8_LDA(At, 1, 1); PG8_STAGE(PG8_SB(1, 0), b3, voffB); PG8_STAGE(PG8_SB(1, 1), b3 + hstep, voffB);
;             PG8_WAIT_V(6); PG8_WAIT_L(0); PG8_BAR; PG8_MMA(1, 0, At, B0); PG8_MMA(1, 1, At, B1); PG8_BAR; PG8_SCHED;
	s_add_i32 s48, s97, s2
	v_lshl_add_u64 v[168:169], v[168:169], 0, s[10:11]
	s_mov_b32 m0, s48
	ds_read_b128 v[204:207], v181 offset:49152
	ds_read_b128 v[208:211], v181 offset:50176
	ds_read_b128 v[212:215], v181 offset:51200
	ds_read_b128 v[216:219], v181 offset:52224
	ds_read_b128 v[220:223], v181 offset:53248
	ds_read_b128 v[224:227], v181 offset:54272
	ds_read_b128 v[228:231], v181 offset:55296
	ds_read_b128 v[232:235], v181 offset:56320
	global_load_lds_dwordx4 v[168:169], off
	s_add_i32 m0, s48, 0x2000
	s_add_u32 s46, s46, 0x80080
	v_lshl_add_u64 v[168:169], v[176:177], 0, s[10:11]
	s_addc_u32 s47, s47, 0
	s_add_i32 s48, vcc_lo, s2
	global_load_lds_dwordx4 v[168:169], off
	v_lshl_add_u64 v[168:169], s[46:47], 0, v[148:149]
	s_mov_b32 m0, s48
	s_nop 0
	global_load_lds_dwordx4 v[168:169], off
	v_lshl_add_u64 v[168:169], s[46:47], 0, v[144:145]
	s_add_i32 m0, s48, 0x2000
	s_nop 0
	global_load_lds_dwordx4 v[168:169], off
	s_waitcnt vmcnt(6)
	s_waitcnt lgkmcnt(0)
	s_setprio 3
	s_barrier
	v_mfma_f32_16x16x32_bf16 v[60:63], v[132:135], v[204:207], v[60:63]
	v_mfma_f32_16x16x32_bf16 v[56:59], v[140:143], v[204:207], v[56:59]
	v_mfma_f32_16x16x32_bf16 v[44:47], v[132:135], v[212:215], v[44:47]
	v_mfma_f32_16x16x32_bf16 v[40:43], v[140:143], v[212:215], v[40:43]
	v_mfma_f32_16x16x32_bf16 v[28:31], v[132:135], v[220:223], v[28:31]
	v_mfma_f32_16x16x32_bf16 v[24:27], v[140:143], v[220:223], v[24:27]
	v_mfma_f32_16x16x32_bf16 v[12:15], v[132:135], v[228:231], v[12:15]
	v_mfma_f32_16x16x32_bf16 v[8:11], v[140:143], v[228:231], v[8:11]
	v_mfma_f32_16x16x32_bf16 v[60:63], v[136:139], v[208:211], v[60:63]
	v_mfma_f32_16x16x32_bf16 v[56:59], v[172:175], v[208:211], v[56:59]
	v_mfma_f32_16x16x32_bf16 v[44:47], v[136:139], v[216:219], v[44:47]
	v_mfma_f32_16x16x32_bf16 v[40:43], v[172:175], v[216:219], v[40:43]
	v_mfma_f32_16x16x32_bf16 v[28:31], v[136:139], v[224:227], v[28:31]
	v_mfma_f32_16x16x32_bf16 v[24:27], v[172:175], v[224:227], v[24:27]
	v_mfma_f32_16x16x32_bf16 v[12:15], v[136:139], v[232:235], v[12:15]
	v_mfma_f32_16x16x32_bf16 v[8:11], v[172:175], v[232:235], v[8:11]
	s_setprio 0
	s_setprio 3
	v_mfma_f32_16x16x32_bf16 v[52:55], v[188:191], v[204:207], v[52:55]
	v_mfma_f32_16x16x32_bf16 v[48:51], v[196:199], v[204:207], v[48:51]
	v_mfma_f32_16x16x32_bf16 v[36:39], v[188:191], v[212:215], v[36:39]
	v_mfma_f32_16x16x32_bf16 v[32:35], v[196:199], v[212:215], v[32:35]
	v_mfma_f32_16x16x32_bf16 v[20:23], v[188:191], v[220:223], v[20:23]
	v_mfma_f32_16x16x32_bf16 v[16:19], v[196:199], v[220:223], v[16:19]
	v_mfma_f32_16x16x32_bf16 v[4:7], v[188:191], v[228:231], v[4:7]
	v_mfma_f32_16x16x32_bf16 v[0:3], v[196:199], v[228:231], v[0:3]
	v_mfma_f32_16x16x32_bf16 v[52:55], v[192:195], v[208:211], v[52:55]
	v_mfma_f32_16x16x32_bf16 v[48:51], v[200:203], v[208:211], v[48:51]
	v_mfma_f32_16x16x32_bf16 v[36:39], v[192:195], v[216:219], v[36:39]
	v_mfma_f32_16x16x32_bf16 v[32:35], v[200:203], v[216:219], v[32:35]
	v_mfma_f32_16x16x32_bf16 v[20:23], v[192:195], v[224:227], v[20:23]
	v_mfma_f32_16x16x32_bf16 v[16:19], v[200:203], v[224:227], v[16:19]
	v_mfma_f32_16x16x32_bf16 v[4:7], v[192:195], v[232:235], v[4:7]
	v_mfma_f32_16x16x32_bf16 v[0:3], v[200:203], v[232:235], v[0:3]
	s_setprio 0
	s_barrier
	s_add_i32 s96, s96, 2
	s_add_u32 s44, s44, 0x100
	s_addc_u32 s45, s45, 0
	s_cmp_gt_u32 s96, 29
	s_cbranch_scc0 .LBB0_102

; #define PG8_STAGE(bufoff, gbase, voff) do { _Pragma("unroll") for (int _i = 0; _i < 2; ++_i) \
;         __builtin_amdgcn_global_load_lds((const unsigned*)((const char*)(gbase) + (voff)[_i]), (LAS unsigned*)(lds + (bufoff) + ldsw + _i * 8192), 16, 0, 0); } while (0)
; #define PG8_LDA(dst, b, h) do { _Pragma("unroll") for (int m = 0; m < 4; ++m) _Pragma("unroll") for (int k = 0; k < 2; ++k) dst[m][k] = *(const LAS bf16x8*)(lds + PG8_SA(b, h) + aoff + m * 2048 + k * 1024); } while (0)
; #define PG8_LDB(dst, b, h) do { _Pragma("unroll") for (int n = 0; n < 2; ++n) _Pragma("unroll") for (int k = 0; k < 2; ++k) dst[n][k] = *(const LAS bf16x8*)(lds + PG8_SB(b, h) + boff + n * 2048 + k * 1024); } while (0)
; #define PG8_MMA(ai, bj, At, Bt) do { __builtin_amdgcn_s_setprio(3); _Pragma("unroll") for (int m = 0; m < 4; ++m) _Pragma("unroll") for (int n = 0; n < 2; ++n) _Pragma("unroll") for (int k = 0; k < 2; ++k) \
;         acc[ai][bj][m][n] = __builtin_amdgcn_mfma_f32_16x16x32_bf16(Bt[n][k], At[m][k], acc[ai][bj][m][n], 0, 0, 0); __builtin_amdgcn_s_setprio(0); } while (0)
; #define PG8_WAIT_V(n) asm volatile("s_waitcnt vmcnt(" #n ")" ::: "memory")
; #define PG8_WAIT_L(n) asm volatile("s_waitcnt lgkmcnt(" #n ")" ::: "memory")
; #define PG8_BAR __builtin_amdgcn_s_barrier()
; #define PG8_SCHED __builtin_amdgcn_sched_barrier(0)
; template <class Epi, class Sched>
; __device__ __forceinline__ void gemm_phase(LAS unsigned char* lds, const Gemm g, const Sched& S, const Epi& E, int tid_in) {
;     ...
;             const bool last = (t == nt - 2);
;             const char* a1 = cA + (size_t)(t + 1) * kstep;
;             const char* a2 = last ? nA : cA + (size_t)(t + 2) * kstep; const char* b2 = last ? nB : cB + (size_t)(t + 2) * kstep;
;             const char* a3 = a2 + kstep; const char* b3 = b2 + kstep;
;             PG8_LDB(B0, 0, 0); PG8_LDB(B1, 0, 1); PG8_SCHED; PG8_LDA(At, 0, 0); PG8_STAGE(PG8_SA(1, 0), a1, voffA); PG8_STAGE(PG8_SA(1, 1), a1 + hstep, voffA);
;             PG8_WAIT_V(8); PG8_WAIT_L(0); PG8_BAR; PG8_MMA(0, 0, At, B0); PG8_MMA(0, 1, At, B1); PG8_BAR; PG8_SCHED;
;             PG8_LDA(At, 0, 1); PG8_STAGE(PG8_SB(0, 0), b2, voffB); PG8_STAGE(PG8_SB(0, 1), b2 + hstep, voffB);
;             PG8_WAIT_V(6); PG8_WAIT_L(0); PG8_BAR; PG8_MMA(1, 0, At, B0); PG8_MMA(1, 1, At, B1); PG8_BAR; PG8_SCHED;
.LBB0_511:
	v_add_u32_e32 v144, s49, v188
	v_add_u32_e32 v176, s51, v188
	s_add_u32 s42, s38, s40
	ds_read_b128 v[132:135], v144
	ds_read_b128 v[136:139], v144 offset:1024
	ds_read_b128 v[140:143], v144 offset:2048
	ds_read_b128 v[144:147], v144 offset:3072
	ds_read_b128 v[148:151], v176
	ds_read_b128 v[152:155], v176 offset:1024
	ds_read_b128 v[172:175], v176 offset:2048
	ds_read_b128 v[176:179], v176 offset:3072
	s_addc_u32 s43, s39, s41
	s_add_u32 s44, s42, 0x100
	s_addc_u32 s45, s43, 0
	s_add_u32 s42, s77, s40
	s_addc_u32 s43, s78, s41
	s_cmpk_eq_i32 s40, 0x700
	s_cselect_b32 s43, s27, s43
	s_cselect_b32 s42, s76, s42
	s_cselect_b32 s45, s29, s45
	s_cselect_b32 s44, s37, s44
	v_lshl_add_u64 v[184:185], v[130:131], 0, s[40:41]
	v_lshl_add_u64 v[220:221], v[184:185], 0, s[14:15]
	s_add_i32 m0, s3, 0x8000
	ds_read_b128 v[180:183], v190
	ds_read_b128 v[192:195], v190 offset:1024
	ds_read_b128 v[196:199], v190 offset:2048
	ds_read_b128 v[200:203], v190 offset:3072
	ds_read_b128 v[204:207], v190 offset:4096
	ds_read_b128 v[208:211], v190 offset:5120
	ds_read_b128 v[212:215], v190 offset:6144
	ds_read_b128 v[216:219], v190 offset:7168
	global_load_lds_dwordx4 v[220:221], off
	v_lshl_add_u64 v[220:221], v[128:129], 0, s[40:41]
	v_lshl_add_u64 v[222:223], v[220:221], 0, s[14:15]
	s_add_i32 m0, s3, 0xa000
	v_lshl_add_u64 v[184:185], v[184:185], 0, s[16:17]
	global_load_lds_dwordx4 v[222:223], off
	s_add_i32 m0, s3, 0xc000
	s_nop 0
	global_load_lds_dwordx4 v[184:185], off
	v_lshl_add_u64 v[184:185], v[220:221], 0, s[16:17]
	s_add_i32 m0, s3, 0xe000
	s_nop 0
	global_load_lds_dwordx4 v[184:185], off
	s_waitcnt vmcnt(8)
	s_waitcnt lgkmcnt(0)
	s_setprio 3
	s_barrier
	v_mfma_f32_16x16x32_bf16 v[124:127], v[132:135], v[180:183], v[124:127]
	v_mfma_f32_16x16x32_bf16 v[120:123], v[140:143], v[180:183], v[120:123]
	v_mfma_f32_16x16x32_bf16 v[116:119], v[132:135], v[196:199], v[116:119]
	v_mfma_f32_16x16x32_bf16 v[112:115], v[140:143], v[196:199], v[112:115]
	v_mfma_f32_16x16x32_bf16 v[108:111], v[132:135], v[204:207], v[108:111]
	v_mfma_f32_16x16x32_bf16 v[104:107], v[140:143], v[204:207], v[104:107]
	v_mfma_f32_16x16x32_bf16 v[100:103], v[132:135], v[212:215], v[100:103]
	v_mfma_f32_16x16x32_bf16 v[96:99], v[140:143], v[212:215], v[96:99]
	v_mfma_f32_16x16x32_bf16 v[124:127], v[136:139], v[192:195], v[124:127]
	v_mfma_f32_16x16x32_bf16 v[120:123], v[144:147], v[192:195], v[120:123]
	v_mfma_f32_16x16x32_bf16 v[116:119], v[136:139], v[200:203], v[116:119]
	v_mfma_f32_16x16x32_bf16 v[112:115], v[144:147], v[200:203], v[112:115]
	v_mfma_f32_16x16x32_bf16 v[108:111], v[136:139], v[208:211], v[108:111]
	v_mfma_f32_16x16x32_bf16 v[104:107], v[144:147], v[208:211], v[104:107]
	v_mfma_f32_16x16x32_bf16 v[100:103], v[136:139], v[216:219], v[100:103]
	v_mfma_f32_16x16x32_bf16 v[96:99], v[144:147], v[216:219], v[96:99]
	s_setprio 0
	s_setprio 3
	v_mfma_f32_16x16x32_bf16 v[92:95], v[148:151], v[180:183], v[92:95]
	v_mfma_f32_16x16x32_bf16 v[88:91], v[172:175], v[180:183], v[88:91]
	v_mfma_f32_16x16x32_bf16 v[84:87], v[148:151], v[196:199], v[84:87]
	v_mfma_f32_16x16x32_bf16 v[80:83], v[172:175], v[196:199], v[80:83]
	v_mfma_f32_16x16x32_bf16 v[76:79], v[148:151], v[204:207], v[76:79]
	v_mfma_f32_16x16x32_bf16 v[72:75], v[172:175], v[204:207], v[72:75]
	v_mfma_f32_16x16x32_bf16 v[68:71], v[148:151], v[212:215], v[68:71]
	v_mfma_f32_16x16x32_bf16 v[64:67], v[172:175], v[212:215], v[64:67]
	v_mfma_f32_16x16x32_bf16 v[92:95], v[152:155], v[192:195], v[92:95]
	v_mfma_f32_16x16x32_bf16 v[88:91], v[176:179], v[192:195], v[88:91]
	v_mfma_f32_16x16x32_bf16 v[84:87], v[152:155], v[200:203], v[84:87]
	v_mfma_f32_16x16x32_bf16 v[80:83], v[176:179], v[200:203], v[80:83]
	v_mfma_f32_16x16x32_bf16 v[76:79], v[152:155], v[208:211], v[76:79]
	v_mfma_f32_16x16x32_bf16 v[72:75], v[176:179], v[208:211], v[72:75]
	v_mfma_f32_16x16x32_bf16 v[68:71], v[152:155], v[216:219], v[68:71]
	v_mfma_f32_16x16x32_bf16 v[64:67], v[176:179], v[216:219], v[64:67]
	s_setprio 0
	s_barrier
	s_add_i32 s80, s49, s2
	v_lshl_add_u64 v[184:185], s[42:43], 0, v[158:159]
	s_mov_b32 m0, s80
	ds_read_b128 v[180:183], v190 offset:16384
	ds_read_b128 v[192:195], v190 offset:17408
	ds_read_b128 v[196:199], v190 offset:18432
	ds_read_b128 v[200:203], v190 offset:19456
	ds_read_b128 v[204:207], v190 offset:20480
	ds_read_b128 v[208:211], v190 offset:21504
	ds_read_b128 v[212:215], v190 offset:22528
	ds_read_b128 v[216:219], v190 offset:23552
	global_load_lds_dwordx4 v[184:185], off
	s_add_i32 m0, s80, 0x2000
	s_add_u32 s80, s42, 0x80000
	v_lshl_add_u64 v[220:221], s[42:43], 0, v[162:163]
	s_addc_u32 s81, s43, 0
	s_add_i32 s82, s51, s2
	global_load_lds_dwordx4 v[220:221], off
	v_lshl_add_u64 v[222:223], s[80:81], 0, v[158:159]
	s_mov_b32 m0, s82
	s_nop 0
	global_load_lds_dwordx4 v[222:223], off
	v_lshl_add_u64 v[222:223], s[80:81], 0, v[162:163]
	s_add_i32 m0, s82, 0x2000
	s_nop 0
	global_load_lds_dwordx4 v[222:223], off
	s_waitcnt vmcnt(6)
	s_waitcnt lgkmcnt(0)
	s_setprio 3
	s_barrier
; #define PG8_STAGE(bufoff, gbase, voff) do { _Pragma("unroll") for (int _i = 0; _i < 2; ++_i) \
;         __builtin_amdgcn_global_load_lds((const unsigned*)((const char*)(gbase) + (voff)[_i]), (LAS unsigned*)(lds + (bufoff) + ldsw + _i * 8192), 16, 0, 0); } while (0)
; #define PG8_LDA(dst, b, h) do { _Pragma("unroll") for (int m = 0; m < 4; ++m) _Pragma("unroll") for (int k = 0; k < 2; ++k) dst[m][k] = *(const LAS bf16x8*)(lds + PG8_SA(b, h) + aoff + m * 2048 + k * 1024); } while (0)
; #define PG8_LDB(dst, b, h) do { _Pragma("unroll") for (int n = 0; n < 2; ++n) _Pragma("unroll") for (int k = 0; k < 2; ++k) dst[n][k] = *(const LAS bf16x8*)(lds + PG8_SB(b, h) + boff + n * 2048 + k * 1024); } while (0)
; #define PG8_MMA(ai, bj, At, Bt) do { __builtin_amdgcn_s_setprio(3); _Pragma("unroll") for (int m = 0; m < 4; ++m) _Pragma("unroll") for (int n = 0; n < 2; ++n) _Pragma("unroll") for (int k = 0; k < 2; ++k) \
;         acc[ai][bj][m][n] = __builtin_amdgcn_mfma_f32_16x16x32_bf16(Bt[n][k], At[m][k], acc[ai][bj][m][n], 0, 0, 0); __builtin_amdgcn_s_setprio(0); } while (0)
; #define PG8_WAIT_V(n) asm volatile("s_waitcnt vmcnt(" #n ")" ::: "memory")
; #define PG8_WAIT_L(n) asm volatile("s_waitcnt lgkmcnt(" #n ")" ::: "memory")
; #define PG8_BAR __builtin_amdgcn_s_barrier()
; #define PG8_SCHED __builtin_amdgcn_sched_barrier(0)
; template <class Epi, class Sched>
; __device__ __forceinline__ void gemm_phase(LAS unsigned char* lds, const Gemm g, const Sched& S, const Epi& E, int tid_in) {
;     ...
;             PG8_WAIT_V(6); PG8_WAIT_L(0); PG8_BAR; PG8_MMA(1, 0, At, B0); PG8_MMA(1, 1, At, B1); PG8_BAR; PG8_SCHED;
;             PG8_LDB(B0, 1, 0); PG8_LDB(B1, 1, 1); PG8_SCHED; PG8_LDA(At, 1, 0); PG8_STAGE(PG8_SA(0, 0), a2, voffA); PG8_STAGE(PG8_SA(0, 1), a2 + hstep, voffA);
;             PG8_WAIT_V(8); PG8_WAIT_L(0); PG8_BAR; PG8_MMA(0, 0, At, B0); PG8_MMA(0, 1, At, B1); PG8_BAR; PG8_SCHED;
	v_mfma_f32_16x16x32_bf16 v[60:63], v[132:135], v[180:183], v[60:63]
	v_mfma_f32_16x16x32_bf16 v[56:59], v[140:143], v[180:183], v[56:59]
	v_mfma_f32_16x16x32_bf16 v[52:55], v[132:135], v[196:199], v[52:55]
	v_mfma_f32_16x16x32_bf16 v[48:51], v[140:143], v[196:199], v[48:51]
	v_mfma_f32_16x16x32_bf16 v[44:47], v[132:135], v[204:207], v[44:47]
	v_mfma_f32_16x16x32_bf16 v[40:43], v[140:143], v[204:207], v[40:43]
	v_mfma_f32_16x16x32_bf16 v[36:39], v[132:135], v[212:215], v[36:39]
	v_mfma_f32_16x16x32_bf16 v[32:35], v[140:143], v[212:215], v[32:35]
	v_mfma_f32_16x16x32_bf16 v[60:63], v[136:139], v[192:195], v[60:63]
	v_mfma_f32_16x16x32_bf16 v[56:59], v[144:147], v[192:195], v[56:59]
	v_mfma_f32_16x16x32_bf16 v[52:55], v[136:139], v[200:203], v[52:55]
	v_mfma_f32_16x16x32_bf16 v[48:51], v[144:147], v[200:203], v[48:51]
	v_mfma_f32_16x16x32_bf16 v[44:47], v[136:139], v[208:211], v[44:47]
	v_mfma_f32_16x16x32_bf16 v[40:43], v[144:147], v[208:211], v[40:43]
	v_mfma_f32_16x16x32_bf16 v[36:39], v[136:139], v[216:219], v[36:39]
	v_mfma_f32_16x16x32_bf16 v[32:35], v[144:147], v[216:219], v[32:35]
	s_setprio 0
	s_setprio 3
	v_mfma_f32_16x16x32_bf16 v[28:31], v[148:151], v[180:183], v[28:31]
	v_mfma_f32_16x16x32_bf16 v[24:27], v[172:175], v[180:183], v[24:27]
	v_mfma_f32_16x16x32_bf16 v[20:23], v[148:151], v[196:199], v[20:23]
	v_mfma_f32_16x16x32_bf16 v[16:19], v[172:175], v[196:199], v[16:19]
	v_mfma_f32_16x16x32_bf16 v[12:15], v[148:151], v[204:207], v[12:15]
	v_mfma_f32_16x16x32_bf16 v[8:11], v[172:175], v[204:207], v[8:11]
	v_mfma_f32_16x16x32_bf16 v[4:7], v[148:151], v[212:215], v[4:7]
	v_mfma_f32_16x16x32_bf16 v[0:3], v[172:175], v[212:215], v[0:3]
	v_mfma_f32_16x16x32_bf16 v[28:31], v[152:155], v[192:195], v[28:31]
	v_mfma_f32_16x16x32_bf16 v[24:27], v[176:179], v[192:195], v[24:27]
	v_mfma_f32_16x16x32_bf16 v[20:23], v[152:155], v[200:203], v[20:23]
	v_mfma_f32_16x16x32_bf16 v[16:19], v[176:179], v[200:203], v[16:19]
	v_mfma_f32_16x16x32_bf16 v[12:15], v[152:155], v[208:211], v[12:15]
	v_mfma_f32_16x16x32_bf16 v[8:11], v[176:179], v[208:211], v[8:11]
	v_mfma_f32_16x16x32_bf16 v[4:7], v[152:155], v[216:219], v[4:7]
	v_mfma_f32_16x16x32_bf16 v[0:3], v[176:179], v[216:219], v[0:3]
	s_setprio 0
	s_barrier
	s_add_i32 s80, 0, 0x18000
	s_add_i32 s81, 0, 0x1c000
	v_add_u32_e32 v144, s80, v188
	v_add_u32_e32 v176, s81, v188
	ds_read_b128 v[132:135], v144
	ds_read_b128 v[136:139], v144 offset:1024
	ds_read_b128 v[140:143], v144 offset:2048
	ds_read_b128 v[144:147], v144 offset:3072
	ds_read_b128 v[148:151], v176
	ds_read_b128 v[152:155], v176 offset:1024
	ds_read_b128 v[172:175], v176 offset:2048
	ds_read_b128 v[176:179], v176 offset:3072
	s_mov_b32 m0, s3
	v_lshl_add_u64 v[222:223], s[44:45], 0, v[156:157]
	ds_read_b128 v[180:183], v190 offset:32768
	ds_read_b128 v[192:195], v190 offset:33792
	ds_read_b128 v[196:199], v190 offset:34816
	ds_read_b128 v[200:203], v190 offset:35840
	ds_read_b128 v[204:207], v190 offset:36864
	ds_read_b128 v[208:211], v190 offset:37888
	ds_read_b128 v[212:215], v190 offset:38912
	ds_read_b128 v[216:219], v190 offset:39936
	global_load_lds_dwordx4 v[222:223], off
	v_lshl_add_u64 v[222:223], s[44:45], 0, v[160:161]
	s_add_u32 s44, s44, 0x80000
	s_mov_b32 m0, s46
	s_addc_u32 s45, s45, 0
	global_load_lds_dwordx4 v[222:223], off
	v_lshl_add_u64 v[222:223], s[44:45], 0, v[156:157]
	s_mov_b32 m0, s47
	s_nop 0
	global_load_lds_dwordx4 v[222:223], off
	v_lshl_add_u64 v[222:223], s[44:45], 0, v[160:161]
	s_mov_b32 m0, s48
	s_nop 0
	global_load_lds_dwordx4 v[222:223], off
	s_waitcnt vmcnt(8)
	s_waitcnt lgkmcnt(0)
	s_setprio 3
	s_barrier
; #define PG8_STAGE(bufoff, gbase, voff) do { _Pragma("unroll") for (int _i = 0; _i < 2; ++_i) \
;         __builtin_amdgcn_global_load_lds((const unsigned*)((const char*)(gbase) + (voff)[_i]), (LAS unsigned*)(lds + (bufoff) + ldsw + _i * 8192), 16, 0, 0); } while (0)
; #define PG8_LDA(dst, b, h) do { _Pragma("unroll") for (int m = 0; m < 4; ++m) _Pragma("unroll") for (int k = 0; k < 2; ++k) dst[m][k] = *(const LAS bf16x8*)(lds + PG8_SA(b, h) + aoff + m * 2048 + k * 1024); } while (0)
; #define PG8_MMA(ai, bj, At, Bt) do { __builtin_amdgcn_s_setprio(3); _Pragma("unroll") for (int m = 0; m < 4; ++m) _Pragma("unroll") for (int n = 0; n < 2; ++n) _Pragma("unroll") for (int k = 0; k < 2; ++k) \
;         acc[ai][bj][m][n] = __builtin_amdgcn_mfma_f32_16x16x32_bf16(Bt[n][k], At[m][k], acc[ai][bj][m][n], 0, 0, 0); __builtin_amdgcn_s_setprio(0); } while (0)
; #define PG8_WAIT_V(n) asm volatile("s_waitcnt vmcnt(" #n ")" ::: "memory")
; #define PG8_WAIT_L(n) asm volatile("s_waitcnt lgkmcnt(" #n ")" ::: "memory")
; #define PG8_BAR __builtin_amdgcn_s_barrier()
; #define PG8_SCHED __builtin_amdgcn_sched_barrier(0)
; template <class Epi, class Sched>
; __device__ __forceinline__ void gemm_phase(LAS unsigned char* lds, const Gemm g, const Sched& S, const Epi& E, int tid_in) {
;     ...
;             PG8_WAIT_V(8); PG8_WAIT_L(0); PG8_BAR; PG8_MMA(0, 0, At, B0); PG8_MMA(0, 1, At, B1); PG8_BAR; PG8_SCHED;
;             PG8_LDA(At, 1, 1); PG8_STAGE(PG8_SB(1, 0), b3, voffB); PG8_STAGE(PG8_SB(1, 1), b3 + hstep, voffB);
;             PG8_WAIT_V(6); PG8_WAIT_L(0); PG8_BAR; PG8_MMA(1, 0, At, B0); PG8_MMA(1, 1, At, B1); PG8_BAR; PG8_SCHED;
;         }
;         if (wr == 0) PG8_BAR;
	v_mfma_f32_16x16x32_bf16 v[124:127], v[132:135], v[180:183], v[124:127]
	v_mfma_f32_16x16x32_bf16 v[120:123], v[140:143], v[180:183], v[120:123]
	v_mfma_f32_16x16x32_bf16 v[116:119], v[132:135], v[196:199], v[116:119]
	v_mfma_f32_16x16x32_bf16 v[112:115], v[140:143], v[196:199], v[112:115]
	v_mfma_f32_16x16x32_bf16 v[108:111], v[132:135], v[204:207], v[108:111]
	v_mfma_f32_16x16x32_bf16 v[104:107], v[140:143], v[204:207], v[104:107]
	v_mfma_f32_16x16x32_bf16 v[100:103], v[132:135], v[212:215], v[100:103]
	v_mfma_f32_16x16x32_bf16 v[96:99], v[140:143], v[212:215], v[96:99]
	v_mfma_f32_16x16x32_bf16 v[124:127], v[136:139], v[192:195], v[124:127]
	v_mfma_f32_16x16x32_bf16 v[120:123], v[144:147], v[192:195], v[120:123]
	v_mfma_f32_16x16x32_bf16 v[116:119], v[136:139], v[200:203], v[116:119]
	v_mfma_f32_16x16x32_bf16 v[112:115], v[144:147], v[200:203], v[112:115]
	v_mfma_f32_16x16x32_bf16 v[108:111], v[136:139], v[208:211], v[108:111]
	v_mfma_f32_16x16x32_bf16 v[104:107], v[144:147], v[208:211], v[104:107]
	v_mfma_f32_16x16x32_bf16 v[100:103], v[136:139], v[216:219], v[100:103]
	v_mfma_f32_16x16x32_bf16 v[96:99], v[144:147], v[216:219], v[96:99]
	s_setprio 0
	s_setprio 3
	v_mfma_f32_16x16x32_bf16 v[92:95], v[148:151], v[180:183], v[92:95]
	v_mfma_f32_16x16x32_bf16 v[88:91], v[172:175], v[180:183], v[88:91]
	v_mfma_f32_16x16x32_bf16 v[84:87], v[148:151], v[196:199], v[84:87]
	v_mfma_f32_16x16x32_bf16 v[80:83], v[172:175], v[196:199], v[80:83]
	v_mfma_f32_16x16x32_bf16 v[76:79], v[148:151], v[204:207], v[76:79]
	v_mfma_f32_16x16x32_bf16 v[72:75], v[172:175], v[204:207], v[72:75]
	v_mfma_f32_16x16x32_bf16 v[68:71], v[148:151], v[212:215], v[68:71]
	v_mfma_f32_16x16x32_bf16 v[64:67], v[172:175], v[212:215], v[64:67]
	v_mfma_f32_16x16x32_bf16 v[92:95], v[152:155], v[192:195], v[92:95]
	v_mfma_f32_16x16x32_bf16 v[88:91], v[176:179], v[192:195], v[88:91]
	v_mfma_f32_16x16x32_bf16 v[84:87], v[152:155], v[200:203], v[84:87]
	v_mfma_f32_16x16x32_bf16 v[80:83], v[176:179], v[200:203], v[80:83]
	v_mfma_f32_16x16x32_bf16 v[76:79], v[152:155], v[208:211], v[76:79]
	v_mfma_f32_16x16x32_bf16 v[72:75], v[176:179], v[208:211], v[72:75]
	v_mfma_f32_16x16x32_bf16 v[68:71], v[152:155], v[216:219], v[68:71]
	v_mfma_f32_16x16x32_bf16 v[64:67], v[176:179], v[216:219], v[64:67]
	s_setprio 0
	s_barrier
	s_add_i32 s44, s80, s2
	v_lshl_add_u64 v[184:185], v[184:185], 0, s[14:15]
	s_mov_b32 m0, s44
	ds_read_b128 v[180:183], v190 offset:49152
	ds_read_b128 v[192:195], v190 offset:50176
	ds_read_b128 v[196:199], v190 offset:51200
	ds_read_b128 v[200:203], v190 offset:52224
	ds_read_b128 v[204:207], v190 offset:53248
	ds_read_b128 v[208:211], v190 offset:54272
	ds_read_b128 v[212:215], v190 offset:55296
	ds_read_b128 v[216:219], v190 offset:56320
	global_load_lds_dwordx4 v[184:185], off
	s_add_i32 m0, s44, 0x2000
	s_add_u32 s42, s42, 0x80080
	v_lshl_add_u64 v[184:185], v[220:221], 0, s[14:15]
	s_addc_u32 s43, s43, 0
	s_add_i32 s44, s81, s2
	global_load_lds_dwordx4 v[184:185], off
	v_lshl_add_u64 v[184:185], s[42:43], 0, v[158:159]
	s_mov_b32 m0, s44
	s_nop 0
	global_load_lds_dwordx4 v[184:185], off
	v_lshl_add_u64 v[184:185], s[42:43], 0, v[162:163]
	s_add_i32 m0, s44, 0x2000
	s_nop 0
	global_load_lds_dwordx4 v[184:185], off
	s_waitcnt vmcnt(6)
	s_waitcnt lgkmcnt(0)
	s_setprio 3
	s_barrier
	v_mfma_f32_16x16x32_bf16 v[60:63], v[132:135], v[180:183], v[60:63]
	v_mfma_f32_16x16x32_bf16 v[56:59], v[140:143], v[180:183], v[56:59]
	v_mfma_f32_16x16x32_bf16 v[52:55], v[132:135], v[196:199], v[52:55]
	v_mfma_f32_16x16x32_bf16 v[48:51], v[140:143], v[196:199], v[48:51]
	v_mfma_f32_16x16x32_bf16 v[44:47], v[132:135], v[204:207], v[44:47]
	v_mfma_f32_16x16x32_bf16 v[40:43], v[140:143], v[204:207], v[40:43]
	v_mfma_f32_16x16x32_bf16 v[36:39], v[132:135], v[212:215], v[36:39]
	v_mfma_f32_16x16x32_bf16 v[32:35], v[140:143], v[212:215], v[32:35]
	v_mfma_f32_16x16x32_bf16 v[60:63], v[136:139], v[192:195], v[60:63]
	v_mfma_f32_16x16x32_bf16 v[56:59], v[144:147], v[192:195], v[56:59]
	v_mfma_f32_16x16x32_bf16 v[52:55], v[136:139], v[200:203], v[52:55]
	v_mfma_f32_16x16x32_bf16 v[48:51], v[144:147], v[200:203], v[48:51]
	v_mfma_f32_16x16x32_bf16 v[44:47], v[136:139], v[208:211], v[44:47]
	v_mfma_f32_16x16x32_bf16 v[40:43], v[144:147], v[208:211], v[40:43]
	v_mfma_f32_16x16x32_bf16 v[36:39], v[136:139], v[216:219], v[36:39]
	v_mfma_f32_16x16x32_bf16 v[32:35], v[144:147], v[216:219], v[32:35]
	s_setprio 0
	s_setprio 3
	v_mfma_f32_16x16x32_bf16 v[28:31], v[148:151], v[180:183], v[28:31]
	v_mfma_f32_16x16x32_bf16 v[24:27], v[172:175], v[180:183], v[24:27]
	v_mfma_f32_16x16x32_bf16 v[20:23], v[148:151], v[196:199], v[20:23]
	v_mfma_f32_16x16x32_bf16 v[16:19], v[172:175], v[196:199], v[16:19]
	v_mfma_f32_16x16x32_bf16 v[12:15], v[148:151], v[204:207], v[12:15]
	v_mfma_f32_16x16x32_bf16 v[8:11], v[172:175], v[204:207], v[8:11]
	v_mfma_f32_16x16x32_bf16 v[4:7], v[148:151], v[212:215], v[4:7]
	v_mfma_f32_16x16x32_bf16 v[0:3], v[172:175], v[212:215], v[0:3]
	v_mfma_f32_16x16x32_bf16 v[28:31], v[152:155], v[192:195], v[28:31]
	v_mfma_f32_16x16x32_bf16 v[24:27], v[176:179], v[192:195], v[24:27]
	v_mfma_f32_16x16x32_bf16 v[20:23], v[152:155], v[200:203], v[20:23]
	v_mfma_f32_16x16x32_bf16 v[16:19], v[176:179], v[200:203], v[16:19]
	v_mfma_f32_16x16x32_bf16 v[12:15], v[152:155], v[208:211], v[12:15]
	v_mfma_f32_16x16x32_bf16 v[8:11], v[176:179], v[208:211], v[8:11]
	v_mfma_f32_16x16x32_bf16 v[4:7], v[152:155], v[216:219], v[4:7]
	v_mfma_f32_16x16x32_bf16 v[0:3], v[176:179], v[216:219], v[0:3]
	s_setprio 0
	s_barrier
	s_add_i32 s79, s79, 2
	s_add_u32 s40, s40, 0x100
	s_addc_u32 s41, s41, 0
	s_cmp_gt_u32 s79, 13
	s_cbranch_scc0 .LBB0_511
	s_and_b64 vcc, exec, s[18:19]
	s_cbranch_vccz .LBB0_514
	s_barrier

;     __device__ bool next(int i, Unit& u) const { if (!b.next(i >> 1, u)) return false; u.half = i & 1; u.koff = (i & 1) * kbytes; return true; }
; #define PG8_STAGE(bufoff, gbase, voff) do { _Pragma("unroll") for (int _i = 0; _i < 2; ++_i) \
;         __builtin_amdgcn_global_load_lds((const unsigned*)((const char*)(gbase) + (voff)[_i]), (LAS unsigned*)(lds + (bufoff) + ldsw + _i * 8192), 16, 0, 0); } while (0)
; #define PG8_LDA(dst, b, h) do { _Pragma("unroll") for (int m = 0; m < 4; ++m) _Pragma("unroll") for (int k = 0; k < 2; ++k) dst[m][k] = *(const LAS bf16x8*)(lds + PG8_SA(b, h) + aoff + m * 2048 + k * 1024); } while (0)
; #define PG8_LDB(dst, b, h) do { _Pragma("unroll") for (int n = 0; n < 2; ++n) _Pragma("unroll") for (int k = 0; k < 2; ++k) dst[n][k] = *(const LAS bf16x8*)(lds + PG8_SB(b, h) + boff + n * 2048 + k * 1024); } while (0)
; #define PG8_WAIT_V(n) asm volatile("s_waitcnt vmcnt(" #n ")" ::: "memory")
; #define PG8_WAIT_L(n) asm volatile("s_waitcnt lgkmcnt(" #n ")" ::: "memory")
; #define PG8_BAR __builtin_amdgcn_s_barrier()
; #define PG8_SCHED __builtin_amdgcn_sched_barrier(0)
; template <class Epi, class Sched>
; __device__ __forceinline__ void gemm_phase(LAS unsigned char* lds, const Gemm g, const Sched& S, const Epi& E, int tid_in) {
;     ...
;         const bool has_next = S.next(ui + 1, nxt);
;         const char* nA = has_next ? (const char*)g.A + (size_t)nxt.pm * tstep + nxt.koff : cA; const char* nB = has_next ? (const char*)g.Bt + (size_t)nxt.pn * tstep + nxt.koff : cB;
;         for (int t = 0; t < nt; t += 2) {
;             const bool last = (t == nt - 2);
;             const char* a1 = cA + (size_t)(t + 1) * kstep;
;             const char* a2 = last ? nA : cA + (size_t)(t + 2) * kstep; const char* b2 = last ? nB : cB + (size_t)(t + 2) * kstep;
;             const char* a3 = a2 + kstep; const char* b3 = b2 + kstep;
;             PG8_LDB(B0, 0, 0); PG8_LDB(B1, 0, 1); PG8_SCHED; PG8_LDA(At, 0, 0); PG8_STAGE(PG8_SA(1, 0), a1, voffA); PG8_STAGE(PG8_SA(1, 1), a1 + hstep, voffA);
;             PG8_WAIT_V(8); PG8_WAIT_L(0); PG8_BAR; PG8_MMA(0, 0, At, B0); PG8_MMA(0, 1, At, B1); PG8_BAR; PG8_SCHED;
;             PG8_LDA(At, 0, 1); PG8_STAGE(PG8_SB(0, 0), b2, voffB); PG8_STAGE(PG8_SB(0, 1), b2 + hstep, voffB);
;             PG8_WAIT_V(6); PG8_WAIT_L(0); PG8_BAR; PG8_MMA(1, 0, At, B0); PG8_MMA(1, 1, At, B1); PG8_BAR; PG8_SCHED;
.LBB0_619:
	s_ashr_i32 s25, s24, 31
	s_lshl_b64 s[26:27], s[24:25], 20
	s_add_u32 s26, s8, s26
	s_addc_u32 s27, s9, s27
	s_and_b64 s[28:29], s[4:5], exec
	s_cselect_b32 s25, s27, s35
	s_cselect_b32 s31, s26, s34
	s_ashr_i32 s23, s22, 31
	s_lshl_b64 s[28:29], s[22:23], 20
	s_add_u32 s28, s68, s28
	s_addc_u32 s29, s69, s29
	s_and_b64 s[38:39], s[4:5], exec
	s_cselect_b32 s23, s29, s37
	s_cselect_b32 s49, s28, s36
	s_add_u32 s51, s36, 0x100
	s_addc_u32 s70, s37, 0
	v_lshl_add_u64 v[144:145], s[34:35], 0, v[136:137]
	v_lshl_add_u64 v[146:147], s[34:35], 0, v[138:139]
	s_mov_b32 s71, -2
	s_mov_b64 s[36:37], 0
	s_waitcnt lgkmcnt(0)
	ds_read_b128 v[156:159], v151
	ds_read_b128 v[160:163], v151 offset:1024
	ds_read_b128 v[164:167], v151 offset:2048
	ds_read_b128 v[168:171], v151 offset:3072
	ds_read_b128 v[172:175], v152
	ds_read_b128 v[176:179], v152 offset:1024
	ds_read_b128 v[180:183], v152 offset:2048
	ds_read_b128 v[188:191], v152 offset:3072
	s_add_u32 s38, s34, s36
	s_addc_u32 s39, s35, s37
	s_add_u32 s40, s38, 0x100
	s_addc_u32 s41, s39, 0
	s_add_u32 s38, s51, s36
	s_addc_u32 s39, s70, s37
	s_cmpk_eq_i32 s36, 0xf00
	s_cselect_b32 s39, s23, s39
	s_cselect_b32 s38, s49, s38
	s_cselect_b32 s41, s25, s41
	s_cselect_b32 s40, s31, s40
	v_lshl_add_u64 v[184:185], v[144:145], 0, s[36:37]
	v_lshl_add_u64 v[224:225], v[184:185], 0, s[16:17]
	s_add_i32 m0, s3, 0x8000
	ds_read_b128 v[192:195], v153
	ds_read_b128 v[196:199], v153 offset:1024
	ds_read_b128 v[200:203], v153 offset:2048
	ds_read_b128 v[204:207], v153 offset:3072
	ds_read_b128 v[208:211], v153 offset:4096
	ds_read_b128 v[212:215], v153 offset:5120
	ds_read_b128 v[216:219], v153 offset:6144
	ds_read_b128 v[220:223], v153 offset:7168
	global_load_lds_dwordx4 v[224:225], off
	v_lshl_add_u64 v[224:225], v[146:147], 0, s[36:37]
	v_lshl_add_u64 v[226:227], v[224:225], 0, s[16:17]
	s_add_i32 m0, s3, 0xa000
	v_lshl_add_u64 v[184:185], v[184:185], 0, s[18:19]
	global_load_lds_dwordx4 v[226:227], off
	s_add_i32 m0, s3, 0xc000
	s_nop 0
	global_load_lds_dwordx4 v[184:185], off
	v_lshl_add_u64 v[184:185], v[224:225], 0, s[18:19]
	s_add_i32 m0, s3, 0xe000
	s_nop 0
	global_load_lds_dwordx4 v[184:185], off
	s_waitcnt vmcnt(8)
	s_waitcnt lgkmcnt(0)
	s_setprio 3
	s_barrier
	v_mfma_f32_16x16x32_bf16 v[124:127], v[156:159], v[192:195], 0
	v_mfma_f32_16x16x32_bf16 v[120:123], v[164:167], v[192:195], 0
	v_mfma_f32_16x16x32_bf16 v[108:111], v[156:159], v[200:203], 0
	v_mfma_f32_16x16x32_bf16 v[104:107], v[164:167], v[200:203], 0
	v_mfma_f32_16x16x32_bf16 v[92:95], v[156:159], v[208:211], 0
	v_mfma_f32_16x16x32_bf16 v[88:91], v[164:167], v[208:211], 0
	v_mfma_f32_16x16x32_bf16 v[76:79], v[156:159], v[216:219], 0
	v_mfma_f32_16x16x32_bf16 v[72:75], v[164:167], v[216:219], 0
	v_mfma_f32_16x16x32_bf16 v[124:127], v[160:163], v[196:199], v[124:127]
	v_mfma_f32_16x16x32_bf16 v[120:123], v[168:171], v[196:199], v[120:123]
	v_mfma_f32_16x16x32_bf16 v[108:111], v[160:163], v[204:207], v[108:111]
	v_mfma_f32_16x16x32_bf16 v[104:107], v[168:171], v[204:207], v[104:107]
	v_mfma_f32_16x16x32_bf16 v[92:95], v[160:163], v[212:215], v[92:95]
	v_mfma_f32_16x16x32_bf16 v[88:91], v[168:171], v[212:215], v[88:91]
	v_mfma_f32_16x16x32_bf16 v[76:79], v[160:163], v[220:223], v[76:79]
	v_mfma_f32_16x16x32_bf16 v[72:75], v[168:171], v[220:223], v[72:75]
	s_setprio 0
	s_setprio 3
	v_mfma_f32_16x16x32_bf16 v[116:119], v[172:175], v[192:195], 0
	v_mfma_f32_16x16x32_bf16 v[112:115], v[180:183], v[192:195], 0
	v_mfma_f32_16x16x32_bf16 v[100:103], v[172:175], v[200:203], 0
	v_mfma_f32_16x16x32_bf16 v[96:99], v[180:183], v[200:203], 0
	v_mfma_f32_16x16x32_bf16 v[84:87], v[172:175], v[208:211], 0
	v_mfma_f32_16x16x32_bf16 v[80:83], v[180:183], v[208:211], 0
	v_mfma_f32_16x16x32_bf16 v[68:71], v[172:175], v[216:219], 0
	v_mfma_f32_16x16x32_bf16 v[64:67], v[180:183], v[216:219], 0
	v_mfma_f32_16x16x32_bf16 v[116:119], v[176:179], v[196:199], v[116:119]
	v_mfma_f32_16x16x32_bf16 v[112:115], v[188:191], v[196:199], v[112:115]
	v_mfma_f32_16x16x32_bf16 v[100:103], v[176:179], v[204:207], v[100:103]
	v_mfma_f32_16x16x32_bf16 v[96:99], v[188:191], v[204:207], v[96:99]
	v_mfma_f32_16x16x32_bf16 v[84:87], v[176:179], v[212:215], v[84:87]
	v_mfma_f32_16x16x32_bf16 v[80:83], v[188:191], v[212:215], v[80:83]
	v_mfma_f32_16x16x32_bf16 v[68:71], v[176:179], v[220:223], v[68:71]
	v_mfma_f32_16x16x32_bf16 v[64:67], v[188:191], v[220:223], v[64:67]
	s_setprio 0
	s_barrier
	s_add_i32 s72, s46, s2
	v_lshl_add_u64 v[184:185], s[38:39], 0, v[130:131]
	s_mov_b32 m0, s72
	ds_read_b128 v[192:195], v153 offset:16384
	ds_read_b128 v[196:199], v153 offset:17408
	ds_read_b128 v[200:203], v153 offset:18432
	ds_read_b128 v[204:207], v153 offset:19456
	ds_read_b128 v[208:211], v153 offset:20480
	ds_read_b128 v[212:215], v153 offset:21504
	ds_read_b128 v[216:219], v153 offset:22528
	ds_read_b128 v[220:223], v153 offset:23552
	global_load_lds_dwordx4 v[184:185], off
	s_add_i32 m0, s72, 0x2000
	s_add_u32 s72, s38, 0x80000
	v_lshl_add_u64 v[224:225], s[38:39], 0, v[134:135]
	s_addc_u32 s73, s39, 0
	s_add_i32 s74, s47, s2
	global_load_lds_dwordx4 v[224:225], off
	v_lshl_add_u64 v[226:227], s[72:73], 0, v[130:131]
	s_mov_b32 m0, s74
	s_nop 0
	global_load_lds_dwordx4 v[226:227], off
	v_lshl_add_u64 v[226:227], s[72:73], 0, v[134:135]
	s_add_i32 m0, s74, 0x2000
	s_nop 0
	global_load_lds_dwordx4 v[226:227], off
	s_waitcnt vmcnt(6)
	s_waitcnt lgkmcnt(0)
	s_setprio 3
	s_barrier
; #define PG8_STAGE(bufoff, gbase, voff) do { _Pragma("unroll") for (int _i = 0; _i < 2; ++_i) \
;         __builtin_amdgcn_global_load_lds((const unsigned*)((const char*)(gbase) + (voff)[_i]), (LAS unsigned*)(lds + (bufoff) + ldsw + _i * 8192), 16, 0, 0); } while (0)
; #define PG8_LDA(dst, b, h) do { _Pragma("unroll") for (int m = 0; m < 4; ++m) _Pragma("unroll") for (int k = 0; k < 2; ++k) dst[m][k] = *(const LAS bf16x8*)(lds + PG8_SA(b, h) + aoff + m * 2048 + k * 1024); } while (0)
; #define PG8_LDB(dst, b, h) do { _Pragma("unroll") for (int n = 0; n < 2; ++n) _Pragma("unroll") for (int k = 0; k < 2; ++k) dst[n][k] = *(const LAS bf16x8*)(lds + PG8_SB(b, h) + boff + n * 2048 + k * 1024); } while (0)
; #define PG8_MMA(ai, bj, At, Bt) do { __builtin_amdgcn_s_setprio(3); _Pragma("unroll") for (int m = 0; m < 4; ++m) _Pragma("unroll") for (int n = 0; n < 2; ++n) _Pragma("unroll") for (int k = 0; k < 2; ++k) \
;         acc[ai][bj][m][n] = __builtin_amdgcn_mfma_f32_16x16x32_bf16(Bt[n][k], At[m][k], acc[ai][bj][m][n], 0, 0, 0); __builtin_amdgcn_s_setprio(0); } while (0)
; #define PG8_WAIT_V(n) asm volatile("s_waitcnt vmcnt(" #n ")" ::: "memory")
; #define PG8_WAIT_L(n) asm volatile("s_waitcnt lgkmcnt(" #n ")" ::: "memory")
; #define PG8_BAR __builtin_amdgcn_s_barrier()
; #define PG8_SCHED __builtin_amdgcn_sched_barrier(0)
; template <class Epi, class Sched>
; __device__ __forceinline__ void gemm_phase(LAS unsigned char* lds, const Gemm g, const Sched& S, const Epi& E, int tid_in) {
;     ...
;             PG8_WAIT_V(6); PG8_WAIT_L(0); PG8_BAR; PG8_MMA(1, 0, At, B0); PG8_MMA(1, 1, At, B1); PG8_BAR; PG8_SCHED;
;             PG8_LDB(B0, 1, 0); PG8_LDB(B1, 1, 1); PG8_SCHED; PG8_LDA(At, 1, 0); PG8_STAGE(PG8_SA(0, 0), a2, voffA); PG8_STAGE(PG8_SA(0, 1), a2 + hstep, voffA);
;             PG8_WAIT_V(8); PG8_WAIT_L(0); PG8_BAR; PG8_MMA(0, 0, At, B0); PG8_MMA(0, 1, At, B1); PG8_BAR; PG8_SCHED;
	v_mfma_f32_16x16x32_bf16 v[60:63], v[156:159], v[192:195], 0
	v_mfma_f32_16x16x32_bf16 v[56:59], v[164:167], v[192:195], 0
	v_mfma_f32_16x16x32_bf16 v[44:47], v[156:159], v[200:203], 0
	v_mfma_f32_16x16x32_bf16 v[40:43], v[164:167], v[200:203], 0
	v_mfma_f32_16x16x32_bf16 v[28:31], v[156:159], v[208:211], 0
	v_mfma_f32_16x16x32_bf16 v[24:27], v[164:167], v[208:211], 0
	v_mfma_f32_16x16x32_bf16 v[12:15], v[156:159], v[216:219], 0
	v_mfma_f32_16x16x32_bf16 v[8:11], v[164:167], v[216:219], 0
	v_mfma_f32_16x16x32_bf16 v[60:63], v[160:163], v[196:199], v[60:63]
	v_mfma_f32_16x16x32_bf16 v[56:59], v[168:171], v[196:199], v[56:59]
	v_mfma_f32_16x16x32_bf16 v[44:47], v[160:163], v[204:207], v[44:47]
	v_mfma_f32_16x16x32_bf16 v[40:43], v[168:171], v[204:207], v[40:43]
	v_mfma_f32_16x16x32_bf16 v[28:31], v[160:163], v[212:215], v[28:31]
	v_mfma_f32_16x16x32_bf16 v[24:27], v[168:171], v[212:215], v[24:27]
	v_mfma_f32_16x16x32_bf16 v[12:15], v[160:163], v[220:223], v[12:15]
	v_mfma_f32_16x16x32_bf16 v[8:11], v[168:171], v[220:223], v[8:11]
	s_setprio 0
	s_setprio 3
	v_mfma_f32_16x16x32_bf16 v[52:55], v[172:175], v[192:195], 0
	v_mfma_f32_16x16x32_bf16 v[48:51], v[180:183], v[192:195], 0
	v_mfma_f32_16x16x32_bf16 v[36:39], v[172:175], v[200:203], 0
	v_mfma_f32_16x16x32_bf16 v[32:35], v[180:183], v[200:203], 0
	v_mfma_f32_16x16x32_bf16 v[20:23], v[172:175], v[208:211], 0
	v_mfma_f32_16x16x32_bf16 v[16:19], v[180:183], v[208:211], 0
	v_mfma_f32_16x16x32_bf16 v[4:7], v[172:175], v[216:219], 0
	v_mfma_f32_16x16x32_bf16 v[0:3], v[180:183], v[216:219], 0
	v_mfma_f32_16x16x32_bf16 v[52:55], v[176:179], v[196:199], v[52:55]
	v_mfma_f32_16x16x32_bf16 v[48:51], v[188:191], v[196:199], v[48:51]
	v_mfma_f32_16x16x32_bf16 v[36:39], v[176:179], v[204:207], v[36:39]
	v_mfma_f32_16x16x32_bf16 v[32:35], v[188:191], v[204:207], v[32:35]
	v_mfma_f32_16x16x32_bf16 v[20:23], v[176:179], v[212:215], v[20:23]
	v_mfma_f32_16x16x32_bf16 v[16:19], v[188:191], v[212:215], v[16:19]
	v_mfma_f32_16x16x32_bf16 v[4:7], v[176:179], v[220:223], v[4:7]
	v_mfma_f32_16x16x32_bf16 v[0:3], v[188:191], v[220:223], v[0:3]
	s_setprio 0
	s_barrier
	s_add_i32 s72, 0, 0x18000
	v_add_u32_e32 v155, s72, v149
	s_add_i32 s73, 0, 0x1c000
	ds_read_b128 v[156:159], v155
	ds_read_b128 v[160:163], v155 offset:1024
	ds_read_b128 v[164:167], v155 offset:2048
	ds_read_b128 v[168:171], v155 offset:3072
	v_add_u32_e32 v155, s73, v149
	ds_read_b128 v[172:175], v155
	ds_read_b128 v[176:179], v155 offset:1024
	ds_read_b128 v[180:183], v155 offset:2048
	ds_read_b128 v[188:191], v155 offset:3072
	s_mov_b32 m0, s3
	v_lshl_add_u64 v[226:227], s[40:41], 0, v[128:129]
	ds_read_b128 v[192:195], v153 offset:32768
	ds_read_b128 v[196:199], v153 offset:33792
	ds_read_b128 v[200:203], v153 offset:34816
	ds_read_b128 v[204:207], v153 offset:35840
	ds_read_b128 v[208:211], v153 offset:36864
	ds_read_b128 v[212:215], v153 offset:37888
	ds_read_b128 v[216:219], v153 offset:38912
	ds_read_b128 v[220:223], v153 offset:39936
	global_load_lds_dwordx4 v[226:227], off
	v_lshl_add_u64 v[226:227], s[40:41], 0, v[132:133]
	s_add_u32 s40, s40, 0x80000
	s_mov_b32 m0, s42
	s_addc_u32 s41, s41, 0
	global_load_lds_dwordx4 v[226:227], off
	v_lshl_add_u64 v[226:227], s[40:41], 0, v[128:129]
	s_mov_b32 m0, s43
	s_nop 0
	global_load_lds_dwordx4 v[226:227], off
	v_lshl_add_u64 v[226:227], s[40:41], 0, v[132:133]
	s_mov_b32 m0, s44
	s_nop 0
	global_load_lds_dwordx4 v[226:227], off
	s_waitcnt vmcnt(8)
	s_waitcnt lgkmcnt(0)
	s_setprio 3
	s_barrier
	v_mfma_f32_16x16x32_bf16 v[124:127], v[156:159], v[192:195], v[124:127]
	v_mfma_f32_16x16x32_bf16 v[120:123], v[164:167], v[192:195], v[120:123]
	v_mfma_f32_16x16x32_bf16 v[108:111], v[156:159], v[200:203], v[108:111]
	v_mfma_f32_16x16x32_bf16 v[104:107], v[164:167], v[200:203], v[104:107]
	v_mfma_f32_16x16x32_bf16 v[92:95], v[156:159], v[208:211], v[92:95]
	v_mfma_f32_16x16x32_bf16 v[88:91], v[164:167], v[208:211], v[88:91]
	v_mfma_f32_16x16x32_bf16 v[76:79], v[156:159], v[216:219], v[76:79]
	v_mfma_f32_16x16x32_bf16 v[72:75], v[164:167], v[216:219], v[72:75]
	v_mfma_f32_16x16x32_bf16 v[124:127], v[160:163], v[196:199], v[124:127]
	v_mfma_f32_16x16x32_bf16 v[120:123], v[168:171], v[196:199], v[120:123]
	v_mfma_f32_16x16x32_bf16 v[108:111], v[160:163], v[204:207], v[108:111]
	v_mfma_f32_16x16x32_bf16 v[104:107], v[168:171], v[204:207], v[104:107]
	v_mfma_f32_16x16x32_bf16 v[92:95], v[160:163], v[212:215], v[92:95]
	v_mfma_f32_16x16x32_bf16 v[88:91], v[168:171], v[212:215], v[88:91]
	v_mfma_f32_16x16x32_bf16 v[76:79], v[160:163], v[220:223], v[76:79]
	v_mfma_f32_16x16x32_bf16 v[72:75], v[168:171], v[220:223], v[72:75]
	s_setprio 0
	s_setprio 3
	v_mfma_f32_16x16x32_bf16 v[116:119], v[172:175], v[192:195], v[116:119]
	v_mfma_f32_16x16x32_bf16 v[112:115], v[180:183], v[192:195], v[112:115]
	v_mfma_f32_16x16x32_bf16 v[100:103], v[172:175], v[200:203], v[100:103]
	v_mfma_f32_16x16x32_bf16 v[96:99], v[180:183], v[200:203], v[96:99]
	v_mfma_f32_16x16x32_bf16 v[84:87], v[172:175], v[208:211], v[84:87]
	v_mfma_f32_16x16x32_bf16 v[80:83], v[180:183], v[208:211], v[80:83]
	v_mfma_f32_16x16x32_bf16 v[68:71], v[172:175], v[216:219], v[68:71]
	v_mfma_f32_16x16x32_bf16 v[64:67], v[180:183], v[216:219], v[64:67]
	v_mfma_f32_16x16x32_bf16 v[116:119], v[176:179], v[196:199], v[116:119]
	v_mfma_f32_16x16x32_bf16 v[112:115], v[188:191], v[196:199], v[112:115]
	v_mfma_f32_16x16x32_bf16 v[100:103], v[176:179], v[204:207], v[100:103]
	v_mfma_f32_16x16x32_bf16 v[96:99], v[188:191], v[204:207], v[96:99]
	v_mfma_f32_16x16x32_bf16 v[84:87], v[176:179], v[212:215], v[84:87]
	v_mfma_f32_16x16x32_bf16 v[80:83], v[188:191], v[212:215], v[80:83]
	v_mfma_f32_16x16x32_bf16 v[68:71], v[176:179], v[220:223], v[68:71]
	v_mfma_f32_16x16x32_bf16 v[64:67], v[188:191], v[220:223], v[64:67]
	s_setprio 0
	s_barrier
; #define PG8_STAGE(bufoff, gbase, voff) do { _Pragma("unroll") for (int _i = 0; _i < 2; ++_i) \
;         __builtin_amdgcn_global_load_lds((const unsigned*)((const char*)(gbase) + (voff)[_i]), (LAS unsigned*)(lds + (bufoff) + ldsw + _i * 8192), 16, 0, 0); } while (0)
; #define PG8_LDA(dst, b, h) do { _Pragma("unroll") for (int m = 0; m < 4; ++m) _Pragma("unroll") for (int k = 0; k < 2; ++k) dst[m][k] = *(const LAS bf16x8*)(lds + PG8_SA(b, h) + aoff + m * 2048 + k * 1024); } while (0)
; #define PG8_LDB(dst, b, h) do { _Pragma("unroll") for (int n = 0; n < 2; ++n) _Pragma("unroll") for (int k = 0; k < 2; ++k) dst[n][k] = *(const LAS bf16x8*)(lds + PG8_SB(b, h) + boff + n * 2048 + k * 1024); } while (0)
; #define PG8_MMA(ai, bj, At, Bt) do { __builtin_amdgcn_s_setprio(3); _Pragma("unroll") for (int m = 0; m < 4; ++m) _Pragma("unroll") for (int n = 0; n < 2; ++n) _Pragma("unroll") for (int k = 0; k < 2; ++k) \
;         acc[ai][bj][m][n] = __builtin_amdgcn_mfma_f32_16x16x32_bf16(Bt[n][k], At[m][k], acc[ai][bj][m][n], 0, 0, 0); __builtin_amdgcn_s_setprio(0); } while (0)
; #define PG8_WAIT_V(n) asm volatile("s_waitcnt vmcnt(" #n ")" ::: "memory")
; #define PG8_WAIT_L(n) asm volatile("s_waitcnt lgkmcnt(" #n ")" ::: "memory")
; #define PG8_BAR __builtin_amdgcn_s_barrier()
; #define PG8_SCHED __builtin_amdgcn_sched_barrier(0)
; template <class Epi, class Sched>
; __device__ __forceinline__ void gemm_phase(LAS unsigned char* lds, const Gemm g, const Sched& S, const Epi& E, int tid_in) {
;     ...
;             const bool last = (t == nt - 2);
;             const char* a1 = cA + (size_t)(t + 1) * kstep;
;             const char* a2 = last ? nA : cA + (size_t)(t + 2) * kstep; const char* b2 = last ? nB : cB + (size_t)(t + 2) * kstep;
;             const char* a3 = a2 + kstep; const char* b3 = b2 + kstep;
;             PG8_LDB(B0, 0, 0); PG8_LDB(B1, 0, 1); PG8_SCHED; PG8_LDA(At, 0, 0); PG8_STAGE(PG8_SA(1, 0), a1, voffA); PG8_STAGE(PG8_SA(1, 1), a1 + hstep, voffA);
;             PG8_WAIT_V(8); PG8_WAIT_L(0); PG8_BAR; PG8_MMA(0, 0, At, B0); PG8_MMA(0, 1, At, B1); PG8_BAR; PG8_SCHED;
;     ...
;             PG8_LDA(At, 1, 1); PG8_STAGE(PG8_SB(1, 0), b3, voffB); PG8_STAGE(PG8_SB(1, 1), b3 + hstep, voffB);
;             PG8_WAIT_V(6); PG8_WAIT_L(0); PG8_BAR; PG8_MMA(1, 0, At, B0); PG8_MMA(1, 1, At, B1); PG8_BAR; PG8_SCHED;
	s_add_i32 s40, s72, s2
	v_lshl_add_u64 v[184:185], v[184:185], 0, s[16:17]
	s_mov_b32 m0, s40
	ds_read_b128 v[192:195], v153 offset:49152
	ds_read_b128 v[196:199], v153 offset:50176
	ds_read_b128 v[200:203], v153 offset:51200
	ds_read_b128 v[204:207], v153 offset:52224
	ds_read_b128 v[208:211], v153 offset:53248
	ds_read_b128 v[212:215], v153 offset:54272
	ds_read_b128 v[216:219], v153 offset:55296
	ds_read_b128 v[220:223], v153 offset:56320
	global_load_lds_dwordx4 v[184:185], off
	s_add_i32 m0, s40, 0x2000
	s_add_u32 s38, s38, 0x80080
	v_lshl_add_u64 v[184:185], v[224:225], 0, s[16:17]
	s_addc_u32 s39, s39, 0
	s_add_i32 s40, s73, s2
	global_load_lds_dwordx4 v[184:185], off
	v_lshl_add_u64 v[184:185], s[38:39], 0, v[130:131]
	s_mov_b32 m0, s40
	s_nop 0
	global_load_lds_dwordx4 v[184:185], off
	v_lshl_add_u64 v[184:185], s[38:39], 0, v[134:135]
	s_add_i32 m0, s40, 0x2000
	s_nop 0
	global_load_lds_dwordx4 v[184:185], off
	s_waitcnt vmcnt(6)
	s_waitcnt lgkmcnt(0)
	s_setprio 3
	s_barrier
	v_mfma_f32_16x16x32_bf16 v[60:63], v[156:159], v[192:195], v[60:63]
	v_mfma_f32_16x16x32_bf16 v[56:59], v[164:167], v[192:195], v[56:59]
	v_mfma_f32_16x16x32_bf16 v[44:47], v[156:159], v[200:203], v[44:47]
	v_mfma_f32_16x16x32_bf16 v[40:43], v[164:167], v[200:203], v[40:43]
	v_mfma_f32_16x16x32_bf16 v[28:31], v[156:159], v[208:211], v[28:31]
	v_mfma_f32_16x16x32_bf16 v[24:27], v[164:167], v[208:211], v[24:27]
	v_mfma_f32_16x16x32_bf16 v[12:15], v[156:159], v[216:219], v[12:15]
	v_mfma_f32_16x16x32_bf16 v[8:11], v[164:167], v[216:219], v[8:11]
	v_mfma_f32_16x16x32_bf16 v[60:63], v[160:163], v[196:199], v[60:63]
	v_mfma_f32_16x16x32_bf16 v[56:59], v[168:171], v[196:199], v[56:59]
	v_mfma_f32_16x16x32_bf16 v[44:47], v[160:163], v[204:207], v[44:47]
	v_mfma_f32_16x16x32_bf16 v[40:43], v[168:171], v[204:207], v[40:43]
	v_mfma_f32_16x16x32_bf16 v[28:31], v[160:163], v[212:215], v[28:31]
	v_mfma_f32_16x16x32_bf16 v[24:27], v[168:171], v[212:215], v[24:27]
	v_mfma_f32_16x16x32_bf16 v[12:15], v[160:163], v[220:223], v[12:15]
	v_mfma_f32_16x16x32_bf16 v[8:11], v[168:171], v[220:223], v[8:11]
	s_setprio 0
	s_setprio 3
	v_mfma_f32_16x16x32_bf16 v[52:55], v[172:175], v[192:195], v[52:55]
	v_mfma_f32_16x16x32_bf16 v[48:51], v[180:183], v[192:195], v[48:51]
	v_mfma_f32_16x16x32_bf16 v[36:39], v[172:175], v[200:203], v[36:39]
	v_mfma_f32_16x16x32_bf16 v[32:35], v[180:183], v[200:203], v[32:35]
	v_mfma_f32_16x16x32_bf16 v[20:23], v[172:175], v[208:211], v[20:23]
	v_mfma_f32_16x16x32_bf16 v[16:19], v[180:183], v[208:211], v[16:19]
	v_mfma_f32_16x16x32_bf16 v[4:7], v[172:175], v[216:219], v[4:7]
	v_mfma_f32_16x16x32_bf16 v[0:3], v[180:183], v[216:219], v[0:3]
	v_mfma_f32_16x16x32_bf16 v[52:55], v[176:179], v[196:199], v[52:55]
	v_mfma_f32_16x16x32_bf16 v[48:51], v[188:191], v[196:199], v[48:51]
	v_mfma_f32_16x16x32_bf16 v[36:39], v[176:179], v[204:207], v[36:39]
	v_mfma_f32_16x16x32_bf16 v[32:35], v[188:191], v[204:207], v[32:35]
	v_mfma_f32_16x16x32_bf16 v[20:23], v[176:179], v[212:215], v[20:23]
	v_mfma_f32_16x16x32_bf16 v[16:19], v[188:191], v[212:215], v[16:19]
	v_mfma_f32_16x16x32_bf16 v[4:7], v[176:179], v[220:223], v[4:7]
	v_mfma_f32_16x16x32_bf16 v[0:3], v[188:191], v[220:223], v[0:3]
	s_setprio 0
	s_barrier
	s_add_i32 s71, s71, 2
	s_add_u32 s36, s36, 0x100
	s_addc_u32 s37, s37, 0
	s_cmp_gt_u32 s71, 29
	s_cbranch_scc0 .LBB0_620
	s_branch .Lpeel_exit_1
.LBB0_620:
	ds_read_b128 v[156:159], v151
	ds_read_b128 v[160:163], v151 offset:1024
	ds_read_b128 v[164:167], v151 offset:2048
	ds_read_b128 v[168:171], v151 offset:3072
	ds_read_b128 v[172:175], v152
	ds_read_b128 v[176:179], v152 offset:1024
	ds_read_b128 v[180:183], v152 offset:2048
	ds_read_b128 v[188:191], v152 offset:3072
	s_add_u32 s38, s34, s36
	s_addc_u32 s39, s35, s37
	s_add_u32 s40, s38, 0x100
	s_addc_u32 s41, s39, 0
	s_add_u32 s38, s51, s36
	s_addc_u32 s39, s70, s37
	s_cmpk_eq_i32 s36, 0xf00
	s_cselect_b32 s39, s23, s39
	s_cselect_b32 s38, s49, s38
	s_cselect_b32 s41, s25, s41
	s_cselect_b32 s40, s31, s40
	v_lshl_add_u64 v[184:185], v[144:145], 0, s[36:37]
	v_lshl_add_u64 v[224:225], v[184:185], 0, s[16:17]
	s_add_i32 m0, s3, 0x8000
	ds_read_b128 v[192:195], v153
	ds_read_b128 v[196:199], v153 offset:1024
	ds_read_b128 v[200:203], v153 offset:2048
	ds_read_b128 v[204:207], v153 offset:3072
	ds_read_b128 v[208:211], v153 offset:4096
	ds_read_b128 v[212:215], v153 offset:5120
	ds_read_b128 v[216:219], v153 offset:6144
	ds_read_b128 v[220:223], v153 offset:7168
	global_load_lds_dwordx4 v[224:225], off
	v_lshl_add_u64 v[224:225], v[146:147], 0, s[36:37]
	v_lshl_add_u64 v[226:227], v[224:225], 0, s[16:17]
	s_add_i32 m0, s3, 0xa000
	v_lshl_add_u64 v[184:185], v[184:185], 0, s[18:19]
	global_load_lds_dwordx4 v[226:227], off
	s_add_i32 m0, s3, 0xc000
	s_nop 0
	global_load_lds_dwordx4 v[184:185], off
	v_lshl_add_u64 v[184:185], v[224:225], 0, s[18:19]
	s_add_i32 m0, s3, 0xe000
	s_nop 0
	global_load_lds_dwordx4 v[184:185], off
	s_waitcnt vmcnt(8)
	s_waitcnt lgkmcnt(0)
	s_setprio 3
	s_barrier
; #define PG8_STAGE(bufoff, gbase, voff) do { _Pragma("unroll") for (int _i = 0; _i < 2; ++_i) \
;         __builtin_amdgcn_global_load_lds((const unsigned*)((const char*)(gbase) + (voff)[_i]), (LAS unsigned*)(lds + (bufoff) + ldsw + _i * 8192), 16, 0, 0); } while (0)
; #define PG8_LDA(dst, b, h) do { _Pragma("unroll") for (int m = 0; m < 4; ++m) _Pragma("unroll") for (int k = 0; k < 2; ++k) dst[m][k] = *(const LAS bf16x8*)(lds + PG8_SA(b, h) + aoff + m * 2048 + k * 1024); } while (0)
; #define PG8_MMA(ai, bj, At, Bt) do { __builtin_amdgcn_s_setprio(3); _Pragma("unroll") for (int m = 0; m < 4; ++m) _Pragma("unroll") for (int n = 0; n < 2; ++n) _Pragma("unroll") for (int k = 0; k < 2; ++k) \
;         acc[ai][bj][m][n] = __builtin_amdgcn_mfma_f32_16x16x32_bf16(Bt[n][k], At[m][k], acc[ai][bj][m][n], 0, 0, 0); __builtin_amdgcn_s_setprio(0); } while (0)
; #define PG8_WAIT_V(n) asm volatile("s_waitcnt vmcnt(" #n ")" ::: "memory")
; #define PG8_WAIT_L(n) asm volatile("s_waitcnt lgkmcnt(" #n ")" ::: "memory")
; #define PG8_BAR __builtin_amdgcn_s_barrier()
; #define PG8_SCHED __builtin_amdgcn_sched_barrier(0)
; template <class Epi, class Sched>
; __device__ __forceinline__ void gemm_phase(LAS unsigned char* lds, const Gemm g, const Sched& S, const Epi& E, int tid_in) {
;     ...
;             PG8_WAIT_V(8); PG8_WAIT_L(0); PG8_BAR; PG8_MMA(0, 0, At, B0); PG8_MMA(0, 1, At, B1); PG8_BAR; PG8_SCHED;
;             PG8_LDA(At, 0, 1); PG8_STAGE(PG8_SB(0, 0), b2, voffB); PG8_STAGE(PG8_SB(0, 1), b2 + hstep, voffB);
;             PG8_WAIT_V(6); PG8_WAIT_L(0); PG8_BAR; PG8_MMA(1, 0, At, B0); PG8_MMA(1, 1, At, B1); PG8_BAR; PG8_SCHED;
	v_mfma_f32_16x16x32_bf16 v[124:127], v[156:159], v[192:195], v[124:127]
	v_mfma_f32_16x16x32_bf16 v[120:123], v[164:167], v[192:195], v[120:123]
	v_mfma_f32_16x16x32_bf16 v[108:111], v[156:159], v[200:203], v[108:111]
	v_mfma_f32_16x16x32_bf16 v[104:107], v[164:167], v[200:203], v[104:107]
	v_mfma_f32_16x16x32_bf16 v[92:95], v[156:159], v[208:211], v[92:95]
	v_mfma_f32_16x16x32_bf16 v[88:91], v[164:167], v[208:211], v[88:91]
	v_mfma_f32_16x16x32_bf16 v[76:79], v[156:159], v[216:219], v[76:79]
	v_mfma_f32_16x16x32_bf16 v[72:75], v[164:167], v[216:219], v[72:75]
	v_mfma_f32_16x16x32_bf16 v[124:127], v[160:163], v[196:199], v[124:127]
	v_mfma_f32_16x16x32_bf16 v[120:123], v[168:171], v[196:199], v[120:123]
	v_mfma_f32_16x16x32_bf16 v[108:111], v[160:163], v[204:207], v[108:111]
	v_mfma_f32_16x16x32_bf16 v[104:107], v[168:171], v[204:207], v[104:107]
	v_mfma_f32_16x16x32_bf16 v[92:95], v[160:163], v[212:215], v[92:95]
	v_mfma_f32_16x16x32_bf16 v[88:91], v[168:171], v[212:215], v[88:91]
	v_mfma_f32_16x16x32_bf16 v[76:79], v[160:163], v[220:223], v[76:79]
	v_mfma_f32_16x16x32_bf16 v[72:75], v[168:171], v[220:223], v[72:75]
	s_setprio 0
	s_setprio 3
	v_mfma_f32_16x16x32_bf16 v[116:119], v[172:175], v[192:195], v[116:119]
	v_mfma_f32_16x16x32_bf16 v[112:115], v[180:183], v[192:195], v[112:115]
	v_mfma_f32_16x16x32_bf16 v[100:103], v[172:175], v[200:203], v[100:103]
	v_mfma_f32_16x16x32_bf16 v[96:99], v[180:183], v[200:203], v[96:99]
	v_mfma_f32_16x16x32_bf16 v[84:87], v[172:175], v[208:211], v[84:87]
	v_mfma_f32_16x16x32_bf16 v[80:83], v[180:183], v[208:211], v[80:83]
	v_mfma_f32_16x16x32_bf16 v[68:71], v[172:175], v[216:219], v[68:71]
	v_mfma_f32_16x16x32_bf16 v[64:67], v[180:183], v[216:219], v[64:67]
	v_mfma_f32_16x16x32_bf16 v[116:119], v[176:179], v[196:199], v[116:119]
	v_mfma_f32_16x16x32_bf16 v[112:115], v[188:191], v[196:199], v[112:115]
	v_mfma_f32_16x16x32_bf16 v[100:103], v[176:179], v[204:207], v[100:103]
	v_mfma_f32_16x16x32_bf16 v[96:99], v[188:191], v[204:207], v[96:99]
	v_mfma_f32_16x16x32_bf16 v[84:87], v[176:179], v[212:215], v[84:87]
	v_mfma_f32_16x16x32_bf16 v[80:83], v[188:191], v[212:215], v[80:83]
	v_mfma_f32_16x16x32_bf16 v[68:71], v[176:179], v[220:223], v[68:71]
	v_mfma_f32_16x16x32_bf16 v[64:67], v[188:191], v[220:223], v[64:67]
	s_setprio 0
	s_barrier
	s_add_i32 s72, s46, s2
	v_lshl_add_u64 v[184:185], s[38:39], 0, v[130:131]
	s_mov_b32 m0, s72
	ds_read_b128 v[192:195], v153 offset:16384
	ds_read_b128 v[196:199], v153 offset:17408
	ds_read_b128 v[200:203], v153 offset:18432
	ds_read_b128 v[204:207], v153 offset:19456
	ds_read_b128 v[208:211], v153 offset:20480
	ds_read_b128 v[212:215], v153 offset:21504
	ds_read_b128 v[216:219], v153 offset:22528
	ds_read_b128 v[220:223], v153 offset:23552
	global_load_lds_dwordx4 v[184:185], off
	s_add_i32 m0, s72, 0x2000
	s_add_u32 s72, s38, 0x80000
	v_lshl_add_u64 v[224:225], s[38:39], 0, v[134:135]
	s_addc_u32 s73, s39, 0
	s_add_i32 s74, s47, s2
	global_load_lds_dwordx4 v[224:225], off
	v_lshl_add_u64 v[226:227], s[72:73], 0, v[130:131]
	s_mov_b32 m0, s74
	s_nop 0
	global_load_lds_dwordx4 v[226:227], off
	v_lshl_add_u64 v[226:227], s[72:73], 0, v[134:135]
	s_add_i32 m0, s74, 0x2000
	s_nop 0
	global_load_lds_dwordx4 v[226:227], off
	s_waitcnt vmcnt(6)
	s_waitcnt lgkmcnt(0)
	s_setprio 3
	s_barrier
	v_mfma_f32_16x16x32_bf16 v[60:63], v[156:159], v[192:195], v[60:63]
	v_mfma_f32_16x16x32_bf16 v[56:59], v[164:167], v[192:195], v[56:59]
	v_mfma_f32_16x16x32_bf16 v[44:47], v[156:159], v[200:203], v[44:47]
	v_mfma_f32_16x16x32_bf16 v[40:43], v[164:167], v[200:203], v[40:43]
	v_mfma_f32_16x16x32_bf16 v[28:31], v[156:159], v[208:211], v[28:31]
	v_mfma_f32_16x16x32_bf16 v[24:27], v[164:167], v[208:211], v[24:27]
	v_mfma_f32_16x16x32_bf16 v[12:15], v[156:159], v[216:219], v[12:15]
	v_mfma_f32_16x16x32_bf16 v[8:11], v[164:167], v[216:219], v[8:11]
	v_mfma_f32_16x16x32_bf16 v[60:63], v[160:163], v[196:199], v[60:63]
	v_mfma_f32_16x16x32_bf16 v[56:59], v[168:171], v[196:199], v[56:59]
	v_mfma_f32_16x16x32_bf16 v[44:47], v[160:163], v[204:207], v[44:47]
	v_mfma_f32_16x16x32_bf16 v[40:43], v[168:171], v[204:207], v[40:43]
	v_mfma_f32_16x16x32_bf16 v[28:31], v[160:163], v[212:215], v[28:31]
	v_mfma_f32_16x16x32_bf16 v[24:27], v[168:171], v[212:215], v[24:27]
	v_mfma_f32_16x16x32_bf16 v[12:15], v[160:163], v[220:223], v[12:15]
	v_mfma_f32_16x16x32_bf16 v[8:11], v[168:171], v[220:223], v[8:11]
	s_setprio 0
	s_setprio 3
	v_mfma_f32_16x16x32_bf16 v[52:55], v[172:175], v[192:195], v[52:55]
	v_mfma_f32_16x16x32_bf16 v[48:51], v[180:183], v[192:195], v[48:51]
	v_mfma_f32_16x16x32_bf16 v[36:39], v[172:175], v[200:203], v[36:39]
	v_mfma_f32_16x16x32_bf16 v[32:35], v[180:183], v[200:203], v[32:35]
	v_mfma_f32_16x16x32_bf16 v[20:23], v[172:175], v[208:211], v[20:23]
	v_mfma_f32_16x16x32_bf16 v[16:19], v[180:183], v[208:211], v[16:19]
	v_mfma_f32_16x16x32_bf16 v[4:7], v[172:175], v[216:219], v[4:7]
	v_mfma_f32_16x16x32_bf16 v[0:3], v[180:183], v[216:219], v[0:3]
	v_mfma_f32_16x16x32_bf16 v[52:55], v[176:179], v[196:199], v[52:55]
	v_mfma_f32_16x16x32_bf16 v[48:51], v[188:191], v[196:199], v[48:51]
	v_mfma_f32_16x16x32_bf16 v[36:39], v[176:179], v[204:207], v[36:39]
	v_mfma_f32_16x16x32_bf16 v[32:35], v[188:191], v[204:207], v[32:35]
	v_mfma_f32_16x16x32_bf16 v[20:23], v[176:179], v[212:215], v[20:23]
	v_mfma_f32_16x16x32_bf16 v[16:19], v[188:191], v[212:215], v[16:19]
	v_mfma_f32_16x16x32_bf16 v[4:7], v[176:179], v[220:223], v[4:7]
	v_mfma_f32_16x16x32_bf16 v[0:3], v[188:191], v[220:223], v[0:3]
	s_setprio 0
	s_barrier
; #define PG8_STAGE(bufoff, gbase, voff) do { _Pragma("unroll") for (int _i = 0; _i < 2; ++_i) \
;         __builtin_amdgcn_global_load_lds((const unsigned*)((const char*)(gbase) + (voff)[_i]), (LAS unsigned*)(lds + (bufoff) + ldsw + _i * 8192), 16, 0, 0); } while (0)
; #define PG8_LDA(dst, b, h) do { _Pragma("unroll") for (int m = 0; m < 4; ++m) _Pragma("unroll") for (int k = 0; k < 2; ++k) dst[m][k] = *(const LAS bf16x8*)(lds + PG8_SA(b, h) + aoff + m * 2048 + k * 1024); } while (0)
; #define PG8_LDB(dst, b, h) do { _Pragma("unroll") for (int n = 0; n < 2; ++n) _Pragma("unroll") for (int k = 0; k < 2; ++k) dst[n][k] = *(const LAS bf16x8*)(lds + PG8_SB(b, h) + boff + n * 2048 + k * 1024); } while (0)
; #define PG8_MMA(ai, bj, At, Bt) do { __builtin_amdgcn_s_setprio(3); _Pragma("unroll") for (int m = 0; m < 4; ++m) _Pragma("unroll") for (int n = 0; n < 2; ++n) _Pragma("unroll") for (int k = 0; k < 2; ++k) \
;         acc[ai][bj][m][n] = __builtin_amdgcn_mfma_f32_16x16x32_bf16(Bt[n][k], At[m][k], acc[ai][bj][m][n], 0, 0, 0); __builtin_amdgcn_s_setprio(0); } while (0)
; #define PG8_WAIT_V(n) asm volatile("s_waitcnt vmcnt(" #n ")" ::: "memory")
; #define PG8_WAIT_L(n) asm volatile("s_waitcnt lgkmcnt(" #n ")" ::: "memory")
; #define PG8_BAR __builtin_amdgcn_s_barrier()
; #define PG8_SCHED __builtin_amdgcn_sched_barrier(0)
; template <class Epi, class Sched>
; __device__ __forceinline__ void gemm_phase(LAS unsigned char* lds, const Gemm g, const Sched& S, const Epi& E, int tid_in) {
;     ...
;             PG8_LDB(B0, 1, 0); PG8_LDB(B1, 1, 1); PG8_SCHED; PG8_LDA(At, 1, 0); PG8_STAGE(PG8_SA(0, 0), a2, voffA); PG8_STAGE(PG8_SA(0, 1), a2 + hstep, voffA);
;             PG8_WAIT_V(8); PG8_WAIT_L(0); PG8_BAR; PG8_MMA(0, 0, At, B0); PG8_MMA(0, 1, At, B1); PG8_BAR; PG8_SCHED;
;             PG8_LDA(At, 1, 1); PG8_STAGE(PG8_SB(1, 0), b3, voffB); PG8_STAGE(PG8_SB(1, 1), b3 + hstep, voffB);
;             PG8_WAIT_V(6); PG8_WAIT_L(0); PG8_BAR; PG8_MMA(1, 0, At, B0); PG8_MMA(1, 1, At, B1); PG8_BAR; PG8_SCHED;
;         }
	s_add_i32 s72, 0, 0x18000
	v_add_u32_e32 v155, s72, v149
	s_add_i32 s73, 0, 0x1c000
	ds_read_b128 v[156:159], v155
	ds_read_b128 v[160:163], v155 offset:1024
	ds_read_b128 v[164:167], v155 offset:2048
	ds_read_b128 v[168:171], v155 offset:3072
	v_add_u32_e32 v155, s73, v149
	ds_read_b128 v[172:175], v155
	ds_read_b128 v[176:179], v155 offset:1024
	ds_read_b128 v[180:183], v155 offset:2048
	ds_read_b128 v[188:191], v155 offset:3072
	s_mov_b32 m0, s3
	v_lshl_add_u64 v[226:227], s[40:41], 0, v[128:129]
	ds_read_b128 v[192:195], v153 offset:32768
	ds_read_b128 v[196:199], v153 offset:33792
	ds_read_b128 v[200:203], v153 offset:34816
	ds_read_b128 v[204:207], v153 offset:35840
	ds_read_b128 v[208:211], v153 offset:36864
	ds_read_b128 v[212:215], v153 offset:37888
	ds_read_b128 v[216:219], v153 offset:38912
	ds_read_b128 v[220:223], v153 offset:39936
	global_load_lds_dwordx4 v[226:227], off
	v_lshl_add_u64 v[226:227], s[40:41], 0, v[132:133]
	s_add_u32 s40, s40, 0x80000
	s_mov_b32 m0, s42
	s_addc_u32 s41, s41, 0
	global_load_lds_dwordx4 v[226:227], off
	v_lshl_add_u64 v[226:227], s[40:41], 0, v[128:129]
	s_mov_b32 m0, s43
	s_nop 0
	global_load_lds_dwordx4 v[226:227], off
	v_lshl_add_u64 v[226:227], s[40:41], 0, v[132:133]
	s_mov_b32 m0, s44
	s_nop 0
	global_load_lds_dwordx4 v[226:227], off
	s_waitcnt vmcnt(8)
	s_waitcnt lgkmcnt(0)
	s_setprio 3
	s_barrier
	v_mfma_f32_16x16x32_bf16 v[124:127], v[156:159], v[192:195], v[124:127]
	v_mfma_f32_16x16x32_bf16 v[120:123], v[164:167], v[192:195], v[120:123]
	v_mfma_f32_16x16x32_bf16 v[108:111], v[156:159], v[200:203], v[108:111]
	v_mfma_f32_16x16x32_bf16 v[104:107], v[164:167], v[200:203], v[104:107]
	v_mfma_f32_16x16x32_bf16 v[92:95], v[156:159], v[208:211], v[92:95]
	v_mfma_f32_16x16x32_bf16 v[88:91], v[164:167], v[208:211], v[88:91]
	v_mfma_f32_16x16x32_bf16 v[76:79], v[156:159], v[216:219], v[76:79]
	v_mfma_f32_16x16x32_bf16 v[72:75], v[164:167], v[216:219], v[72:75]
	v_mfma_f32_16x16x32_bf16 v[124:127], v[160:163], v[196:199], v[124:127]
	v_mfma_f32_16x16x32_bf16 v[120:123], v[168:171], v[196:199], v[120:123]
	v_mfma_f32_16x16x32_bf16 v[108:111], v[160:163], v[204:207], v[108:111]
	v_mfma_f32_16x16x32_bf16 v[104:107], v[168:171], v[204:207], v[104:107]
	v_mfma_f32_16x16x32_bf16 v[92:95], v[160:163], v[212:215], v[92:95]
	v_mfma_f32_16x16x32_bf16 v[88:91], v[168:171], v[212:215], v[88:91]
	v_mfma_f32_16x16x32_bf16 v[76:79], v[160:163], v[220:223], v[76:79]
	v_mfma_f32_16x16x32_bf16 v[72:75], v[168:171], v[220:223], v[72:75]
	s_setprio 0
	s_setprio 3
	v_mfma_f32_16x16x32_bf16 v[116:119], v[172:175], v[192:195], v[116:119]
	v_mfma_f32_16x16x32_bf16 v[112:115], v[180:183], v[192:195], v[112:115]
	v_mfma_f32_16x16x32_bf16 v[100:103], v[172:175], v[200:203], v[100:103]
	v_mfma_f32_16x16x32_bf16 v[96:99], v[180:183], v[200:203], v[96:99]
	v_mfma_f32_16x16x32_bf16 v[84:87], v[172:175], v[208:211], v[84:87]
	v_mfma_f32_16x16x32_bf16 v[80:83], v[180:183], v[208:211], v[80:83]
	v_mfma_f32_16x16x32_bf16 v[68:71], v[172:175], v[216:219], v[68:71]
	v_mfma_f32_16x16x32_bf16 v[64:67], v[180:183], v[216:219], v[64:67]
	v_mfma_f32_16x16x32_bf16 v[116:119], v[176:179], v[196:199], v[116:119]
	v_mfma_f32_16x16x32_bf16 v[112:115], v[188:191], v[196:199], v[112:115]
	v_mfma_f32_16x16x32_bf16 v[100:103], v[176:179], v[204:207], v[100:103]
	v_mfma_f32_16x16x32_bf16 v[96:99], v[188:191], v[204:207], v[96:99]
	v_mfma_f32_16x16x32_bf16 v[84:87], v[176:179], v[212:215], v[84:87]
	v_mfma_f32_16x16x32_bf16 v[80:83], v[188:191], v[212:215], v[80:83]
	v_mfma_f32_16x16x32_bf16 v[68:71], v[176:179], v[220:223], v[68:71]
	v_mfma_f32_16x16x32_bf16 v[64:67], v[188:191], v[220:223], v[64:67]
	s_setprio 0
	s_barrier
	s_add_i32 s40, s72, s2
	v_lshl_add_u64 v[184:185], v[184:185], 0, s[16:17]
	s_mov_b32 m0, s40
	ds_read_b128 v[192:195], v153 offset:49152
	ds_read_b128 v[196:199], v153 offset:50176
	ds_read_b128 v[200:203], v153 offset:51200
	ds_read_b128 v[204:207], v153 offset:52224
	ds_read_b128 v[208:211], v153 offset:53248
	ds_read_b128 v[212:215], v153 offset:54272
	ds_read_b128 v[216:219], v153 offset:55296
	ds_read_b128 v[220:223], v153 offset:56320
	global_load_lds_dwordx4 v[184:185], off
	s_add_i32 m0, s40, 0x2000
	s_add_u32 s38, s38, 0x80080
	v_lshl_add_u64 v[184:185], v[224:225], 0, s[16:17]
	s_addc_u32 s39, s39, 0
	s_add_i32 s40, s73, s2
	global_load_lds_dwordx4 v[184:185], off
	v_lshl_add_u64 v[184:185], s[38:39], 0, v[130:131]
	s_mov_b32 m0, s40
	s_nop 0
	global_load_lds_dwordx4 v[184:185], off
	v_lshl_add_u64 v[184:185], s[38:39], 0, v[134:135]
	s_add_i32 m0, s40, 0x2000
	s_nop 0
	global_load_lds_dwordx4 v[184:185], off
	s_waitcnt vmcnt(6)
	s_waitcnt lgkmcnt(0)
	s_setprio 3
	s_barrier
	v_mfma_f32_16x16x32_bf16 v[60:63], v[156:159], v[192:195], v[60:63]
	v_mfma_f32_16x16x32_bf16 v[56:59], v[164:167], v[192:195], v[56:59]
	v_mfma_f32_16x16x32_bf16 v[44:47], v[156:159], v[200:203], v[44:47]
	v_mfma_f32_16x16x32_bf16 v[40:43], v[164:167], v[200:203], v[40:43]
	v_mfma_f32_16x16x32_bf16 v[28:31], v[156:159], v[208:211], v[28:31]
	v_mfma_f32_16x16x32_bf16 v[24:27], v[164:167], v[208:211], v[24:27]
	v_mfma_f32_16x16x32_bf16 v[12:15], v[156:159], v[216:219], v[12:15]
	v_mfma_f32_16x16x32_bf16 v[8:11], v[164:167], v[216:219], v[8:11]
	v_mfma_f32_16x16x32_bf16 v[60:63], v[160:163], v[196:199], v[60:63]
	v_mfma_f32_16x16x32_bf16 v[56:59], v[168:171], v[196:199], v[56:59]
	v_mfma_f32_16x16x32_bf16 v[44:47], v[160:163], v[204:207], v[44:47]
	v_mfma_f32_16x16x32_bf16 v[40:43], v[168:171], v[204:207], v[40:43]
	v_mfma_f32_16x16x32_bf16 v[28:31], v[160:163], v[212:215], v[28:31]
	v_mfma_f32_16x16x32_bf16 v[24:27], v[168:171], v[212:215], v[24:27]
	v_mfma_f32_16x16x32_bf16 v[12:15], v[160:163], v[220:223], v[12:15]
	v_mfma_f32_16x16x32_bf16 v[8:11], v[168:171], v[220:223], v[8:11]
	s_setprio 0
	s_setprio 3
	v_mfma_f32_16x16x32_bf16 v[52:55], v[172:175], v[192:195], v[52:55]
	v_mfma_f32_16x16x32_bf16 v[48:51], v[180:183], v[192:195], v[48:51]
	v_mfma_f32_16x16x32_bf16 v[36:39], v[172:175], v[200:203], v[36:39]
	v_mfma_f32_16x16x32_bf16 v[32:35], v[180:183], v[200:203], v[32:35]
	v_mfma_f32_16x16x32_bf16 v[20:23], v[172:175], v[208:211], v[20:23]
	v_mfma_f32_16x16x32_bf16 v[16:19], v[180:183], v[208:211], v[16:19]
	v_mfma_f32_16x16x32_bf16 v[4:7], v[172:175], v[216:219], v[4:7]
	v_mfma_f32_16x16x32_bf16 v[0:3], v[180:183], v[216:219], v[0:3]
	v_mfma_f32_16x16x32_bf16 v[52:55], v[176:179], v[196:199], v[52:55]
	v_mfma_f32_16x16x32_bf16 v[48:51], v[188:191], v[196:199], v[48:51]
	v_mfma_f32_16x16x32_bf16 v[36:39], v[176:179], v[204:207], v[36:39]
	v_mfma_f32_16x16x32_bf16 v[32:35], v[188:191], v[204:207], v[32:35]
	v_mfma_f32_16x16x32_bf16 v[20:23], v[176:179], v[212:215], v[20:23]
	v_mfma_f32_16x16x32_bf16 v[16:19], v[188:191], v[212:215], v[16:19]
	v_mfma_f32_16x16x32_bf16 v[4:7], v[176:179], v[220:223], v[4:7]
	v_mfma_f32_16x16x32_bf16 v[0:3], v[188:191], v[220:223], v[0:3]
	s_setprio 0
	s_barrier
	s_add_i32 s71, s71, 2
	s_add_u32 s36, s36, 0x100
	s_addc_u32 s37, s37, 0
	s_cmp_gt_u32 s71, 29
	s_cbranch_scc0 .LBB0_620

;     __device__ bool next(int i, Unit& u) const { if (!b.next(i >> 1, u)) return false; u.half = i & 1; u.koff = (i & 1) * kbytes; return true; }
; #define PG8_STAGE(bufoff, gbase, voff) do { _Pragma("unroll") for (int _i = 0; _i < 2; ++_i) \
;         __builtin_amdgcn_global_load_lds((const unsigned*)((const char*)(gbase) + (voff)[_i]), (LAS unsigned*)(lds + (bufoff) + ldsw + _i * 8192), 16, 0, 0); } while (0)
; #define PG8_LDA(dst, b, h) do { _Pragma("unroll") for (int m = 0; m < 4; ++m) _Pragma("unroll") for (int k = 0; k < 2; ++k) dst[m][k] = *(const LAS bf16x8*)(lds + PG8_SA(b, h) + aoff + m * 2048 + k * 1024); } while (0)
; #define PG8_LDB(dst, b, h) do { _Pragma("unroll") for (int n = 0; n < 2; ++n) _Pragma("unroll") for (int k = 0; k < 2; ++k) dst[n][k] = *(const LAS bf16x8*)(lds + PG8_SB(b, h) + boff + n * 2048 + k * 1024); } while (0)
; #define PG8_WAIT_V(n) asm volatile("s_waitcnt vmcnt(" #n ")" ::: "memory")
; #define PG8_WAIT_L(n) asm volatile("s_waitcnt lgkmcnt(" #n ")" ::: "memory")
; #define PG8_BAR __builtin_amdgcn_s_barrier()
; #define PG8_SCHED __builtin_amdgcn_sched_barrier(0)
; template <class Epi, class Sched>
; __device__ __forceinline__ void gemm_phase(LAS unsigned char* lds, const Gemm g, const Sched& S, const Epi& E, int tid_in) {
;     ...
;         const bool has_next = S.next(ui + 1, nxt);
;         const char* nA = has_next ? (const char*)g.A + (size_t)nxt.pm * tstep + nxt.koff : cA; const char* nB = has_next ? (const char*)g.Bt + (size_t)nxt.pn * tstep + nxt.koff : cB;
;         for (int t = 0; t < nt; t += 2) {
;             const bool last = (t == nt - 2);
;             const char* a1 = cA + (size_t)(t + 1) * kstep;
;             const char* a2 = last ? nA : cA + (size_t)(t + 2) * kstep; const char* b2 = last ? nB : cB + (size_t)(t + 2) * kstep;
;             const char* a3 = a2 + kstep; const char* b3 = b2 + kstep;
;             PG8_LDB(B0, 0, 0); PG8_LDB(B1, 0, 1); PG8_SCHED; PG8_LDA(At, 0, 0); PG8_STAGE(PG8_SA(1, 0), a1, voffA); PG8_STAGE(PG8_SA(1, 1), a1 + hstep, voffA);
;             PG8_WAIT_V(8); PG8_WAIT_L(0); PG8_BAR; PG8_MMA(0, 0, At, B0); PG8_MMA(0, 1, At, B1); PG8_BAR; PG8_SCHED;
;             PG8_LDA(At, 0, 1); PG8_STAGE(PG8_SB(0, 0), b2, voffB); PG8_STAGE(PG8_SB(0, 1), b2 + hstep, voffB);
;             PG8_WAIT_V(6); PG8_WAIT_L(0); PG8_BAR; PG8_MMA(1, 0, At, B0); PG8_MMA(1, 1, At, B1); PG8_BAR; PG8_SCHED;
.LBB0_762:
	s_ashr_i32 s21, s20, 31
	s_lshl_b64 s[22:23], s[20:21], 20
	s_add_u32 s22, s58, s22
	s_addc_u32 s23, s59, s23
	s_and_b64 s[24:25], s[4:5], exec
	s_cselect_b32 s21, s23, s29
	s_cselect_b32 s48, s22, s28
	s_ashr_i32 s19, s18, 31
	s_lshl_b64 s[24:25], s[18:19], 20
	s_add_u32 s24, s2, s24
	s_addc_u32 s25, s3, s25
	s_and_b64 s[34:35], s[4:5], exec
	s_cselect_b32 s19, s25, s31
	s_cselect_b32 s49, s24, s30
	s_add_u32 s51, s30, 0x100
	v_lshl_add_u64 v[144:145], s[28:29], 0, v[136:137]
	v_lshl_add_u64 v[146:147], s[28:29], 0, v[138:139]
	s_addc_u32 s68, s31, 0
	s_mov_b32 s69, -2
	s_mov_b64 s[30:31], 0
	ds_read_b128 v[154:157], v151
	ds_read_b128 v[158:161], v151 offset:1024
	ds_read_b128 v[162:165], v151 offset:2048
	ds_read_b128 v[166:169], v151 offset:3072
	ds_read_b128 v[170:173], v152
	ds_read_b128 v[174:177], v152 offset:1024
	ds_read_b128 v[178:181], v152 offset:2048
	ds_read_b128 v[182:185], v152 offset:3072
	s_add_u32 s34, s28, s30
	s_addc_u32 s35, s29, s31
	s_add_u32 s36, s34, 0x100
	s_addc_u32 s37, s35, 0
	s_add_u32 s34, s51, s30
	s_addc_u32 s35, s68, s31
	s_cmpk_eq_i32 s30, 0xf00
	s_cselect_b32 s35, s19, s35
	s_cselect_b32 s34, s49, s34
	s_cselect_b32 s37, s21, s37
	s_cselect_b32 s36, s48, s36
	v_lshl_add_u64 v[220:221], v[146:147], 0, s[30:31]
	v_lshl_add_u64 v[222:223], v[220:221], 0, s[8:9]
	s_add_i32 m0, s27, 0x8000
	ds_read_b128 v[188:191], v153
	ds_read_b128 v[192:195], v153 offset:1024
	ds_read_b128 v[196:199], v153 offset:2048
	ds_read_b128 v[200:203], v153 offset:3072
	ds_read_b128 v[204:207], v153 offset:4096
	ds_read_b128 v[208:211], v153 offset:5120
	ds_read_b128 v[212:215], v153 offset:6144
	ds_read_b128 v[216:219], v153 offset:7168
	global_load_lds_dwordx4 v[222:223], off
	v_lshl_add_u64 v[222:223], v[144:145], 0, s[30:31]
	v_lshl_add_u64 v[224:225], v[222:223], 0, s[8:9]
	s_add_i32 m0, s27, 0xa000
	v_lshl_add_u64 v[220:221], v[220:221], 0, s[14:15]
	global_load_lds_dwordx4 v[224:225], off
	s_add_i32 m0, s27, 0xc000
	s_nop 0
	global_load_lds_dwordx4 v[220:221], off
	v_lshl_add_u64 v[220:221], v[222:223], 0, s[14:15]
	s_add_i32 m0, s27, 0xe000
	s_nop 0
	global_load_lds_dwordx4 v[220:221], off
	s_waitcnt vmcnt(8)
	s_waitcnt lgkmcnt(0)
	s_setprio 3
	s_barrier
	v_mfma_f32_16x16x32_bf16 v[124:127], v[154:157], v[188:191], 0
	v_mfma_f32_16x16x32_bf16 v[120:123], v[162:165], v[188:191], 0
	v_mfma_f32_16x16x32_bf16 v[108:111], v[154:157], v[196:199], 0
	v_mfma_f32_16x16x32_bf16 v[104:107], v[162:165], v[196:199], 0
	v_mfma_f32_16x16x32_bf16 v[92:95], v[154:157], v[204:207], 0
	v_mfma_f32_16x16x32_bf16 v[88:91], v[162:165], v[204:207], 0
	v_mfma_f32_16x16x32_bf16 v[76:79], v[154:157], v[212:215], 0
	v_mfma_f32_16x16x32_bf16 v[72:75], v[162:165], v[212:215], 0
	v_mfma_f32_16x16x32_bf16 v[124:127], v[158:161], v[192:195], v[124:127]
	v_mfma_f32_16x16x32_bf16 v[120:123], v[166:169], v[192:195], v[120:123]
	v_mfma_f32_16x16x32_bf16 v[108:111], v[158:161], v[200:203], v[108:111]
	v_mfma_f32_16x16x32_bf16 v[104:107], v[166:169], v[200:203], v[104:107]
	v_mfma_f32_16x16x32_bf16 v[92:95], v[158:161], v[208:211], v[92:95]
	v_mfma_f32_16x16x32_bf16 v[88:91], v[166:169], v[208:211], v[88:91]
	v_mfma_f32_16x16x32_bf16 v[76:79], v[158:161], v[216:219], v[76:79]
	v_mfma_f32_16x16x32_bf16 v[72:75], v[166:169], v[216:219], v[72:75]
	s_setprio 0
	s_setprio 3
	v_mfma_f32_16x16x32_bf16 v[116:119], v[170:173], v[188:191], 0
	v_mfma_f32_16x16x32_bf16 v[112:115], v[178:181], v[188:191], 0
	v_mfma_f32_16x16x32_bf16 v[100:103], v[170:173], v[196:199], 0
	v_mfma_f32_16x16x32_bf16 v[96:99], v[178:181], v[196:199], 0
	v_mfma_f32_16x16x32_bf16 v[84:87], v[170:173], v[204:207], 0
	v_mfma_f32_16x16x32_bf16 v[80:83], v[178:181], v[204:207], 0
	v_mfma_f32_16x16x32_bf16 v[68:71], v[170:173], v[212:215], 0
	v_mfma_f32_16x16x32_bf16 v[64:67], v[178:181], v[212:215], 0
	v_mfma_f32_16x16x32_bf16 v[116:119], v[174:177], v[192:195], v[116:119]
	v_mfma_f32_16x16x32_bf16 v[112:115], v[182:185], v[192:195], v[112:115]
	v_mfma_f32_16x16x32_bf16 v[100:103], v[174:177], v[200:203], v[100:103]
	v_mfma_f32_16x16x32_bf16 v[96:99], v[182:185], v[200:203], v[96:99]
	v_mfma_f32_16x16x32_bf16 v[84:87], v[174:177], v[208:211], v[84:87]
	v_mfma_f32_16x16x32_bf16 v[80:83], v[182:185], v[208:211], v[80:83]
	v_mfma_f32_16x16x32_bf16 v[68:71], v[174:177], v[216:219], v[68:71]
	v_mfma_f32_16x16x32_bf16 v[64:67], v[182:185], v[216:219], v[64:67]
	s_setprio 0
	s_barrier
	s_add_i32 s70, s44, s38
	v_lshl_add_u64 v[220:221], s[34:35], 0, v[132:133]
	s_mov_b32 m0, s70
	ds_read_b128 v[188:191], v153 offset:16384
	ds_read_b128 v[192:195], v153 offset:17408
	ds_read_b128 v[196:199], v153 offset:18432
	ds_read_b128 v[200:203], v153 offset:19456
	ds_read_b128 v[204:207], v153 offset:20480
	ds_read_b128 v[208:211], v153 offset:21504
	ds_read_b128 v[212:215], v153 offset:22528
	ds_read_b128 v[216:219], v153 offset:23552
	global_load_lds_dwordx4 v[220:221], off
	s_add_i32 m0, s70, 0x2000
	s_add_u32 s70, s34, 0x80000
	v_lshl_add_u64 v[222:223], s[34:35], 0, v[128:129]
	s_addc_u32 s71, s35, 0
	s_add_i32 s72, s45, s38
	global_load_lds_dwordx4 v[222:223], off
	v_lshl_add_u64 v[224:225], s[70:71], 0, v[132:133]
	s_mov_b32 m0, s72
	s_nop 0
	global_load_lds_dwordx4 v[224:225], off
	v_lshl_add_u64 v[224:225], s[70:71], 0, v[128:129]
	s_add_i32 m0, s72, 0x2000
	s_nop 0
	global_load_lds_dwordx4 v[224:225], off
	s_waitcnt vmcnt(6)
	s_waitcnt lgkmcnt(0)
	s_setprio 3
	s_barrier
; #define PG8_STAGE(bufoff, gbase, voff) do { _Pragma("unroll") for (int _i = 0; _i < 2; ++_i) \
;         __builtin_amdgcn_global_load_lds((const unsigned*)((const char*)(gbase) + (voff)[_i]), (LAS unsigned*)(lds + (bufoff) + ldsw + _i * 8192), 16, 0, 0); } while (0)
; #define PG8_LDA(dst, b, h) do { _Pragma("unroll") for (int m = 0; m < 4; ++m) _Pragma("unroll") for (int k = 0; k < 2; ++k) dst[m][k] = *(const LAS bf16x8*)(lds + PG8_SA(b, h) + aoff + m * 2048 + k * 1024); } while (0)
; #define PG8_LDB(dst, b, h) do { _Pragma("unroll") for (int n = 0; n < 2; ++n) _Pragma("unroll") for (int k = 0; k < 2; ++k) dst[n][k] = *(const LAS bf16x8*)(lds + PG8_SB(b, h) + boff + n * 2048 + k * 1024); } while (0)
; #define PG8_MMA(ai, bj, At, Bt) do { __builtin_amdgcn_s_setprio(3); _Pragma("unroll") for (int m = 0; m < 4; ++m) _Pragma("unroll") for (int n = 0; n < 2; ++n) _Pragma("unroll") for (int k = 0; k < 2; ++k) \
;         acc[ai][bj][m][n] = __builtin_amdgcn_mfma_f32_16x16x32_bf16(Bt[n][k], At[m][k], acc[ai][bj][m][n], 0, 0, 0); __builtin_amdgcn_s_setprio(0); } while (0)
; #define PG8_WAIT_V(n) asm volatile("s_waitcnt vmcnt(" #n ")" ::: "memory")
; #define PG8_WAIT_L(n) asm volatile("s_waitcnt lgkmcnt(" #n ")" ::: "memory")
; #define PG8_BAR __builtin_amdgcn_s_barrier()
; #define PG8_SCHED __builtin_amdgcn_sched_barrier(0)
; template <class Epi, class Sched>
; __device__ __forceinline__ void gemm_phase(LAS unsigned char* lds, const Gemm g, const Sched& S, const Epi& E, int tid_in) {
;     ...
;             PG8_WAIT_V(6); PG8_WAIT_L(0); PG8_BAR; PG8_MMA(1, 0, At, B0); PG8_MMA(1, 1, At, B1); PG8_BAR; PG8_SCHED;
;             PG8_LDB(B0, 1, 0); PG8_LDB(B1, 1, 1); PG8_SCHED; PG8_LDA(At, 1, 0); PG8_STAGE(PG8_SA(0, 0), a2, voffA); PG8_STAGE(PG8_SA(0, 1), a2 + hstep, voffA);
;             PG8_WAIT_V(8); PG8_WAIT_L(0); PG8_BAR; PG8_MMA(0, 0, At, B0); PG8_MMA(0, 1, At, B1); PG8_BAR; PG8_SCHED;
	v_mfma_f32_16x16x32_bf16 v[60:63], v[154:157], v[188:191], 0
	v_mfma_f32_16x16x32_bf16 v[56:59], v[162:165], v[188:191], 0
	v_mfma_f32_16x16x32_bf16 v[44:47], v[154:157], v[196:199], 0
	v_mfma_f32_16x16x32_bf16 v[40:43], v[162:165], v[196:199], 0
	v_mfma_f32_16x16x32_bf16 v[28:31], v[154:157], v[204:207], 0
	v_mfma_f32_16x16x32_bf16 v[24:27], v[162:165], v[204:207], 0
	v_mfma_f32_16x16x32_bf16 v[12:15], v[154:157], v[212:215], 0
	v_mfma_f32_16x16x32_bf16 v[8:11], v[162:165], v[212:215], 0
	v_mfma_f32_16x16x32_bf16 v[60:63], v[158:161], v[192:195], v[60:63]
	v_mfma_f32_16x16x32_bf16 v[56:59], v[166:169], v[192:195], v[56:59]
	v_mfma_f32_16x16x32_bf16 v[44:47], v[158:161], v[200:203], v[44:47]
	v_mfma_f32_16x16x32_bf16 v[40:43], v[166:169], v[200:203], v[40:43]
	v_mfma_f32_16x16x32_bf16 v[28:31], v[158:161], v[208:211], v[28:31]
	v_mfma_f32_16x16x32_bf16 v[24:27], v[166:169], v[208:211], v[24:27]
	v_mfma_f32_16x16x32_bf16 v[12:15], v[158:161], v[216:219], v[12:15]
	v_mfma_f32_16x16x32_bf16 v[8:11], v[166:169], v[216:219], v[8:11]
	s_setprio 0
	s_setprio 3
	v_mfma_f32_16x16x32_bf16 v[52:55], v[170:173], v[188:191], 0
	v_mfma_f32_16x16x32_bf16 v[48:51], v[178:181], v[188:191], 0
	v_mfma_f32_16x16x32_bf16 v[36:39], v[170:173], v[196:199], 0
	v_mfma_f32_16x16x32_bf16 v[32:35], v[178:181], v[196:199], 0
	v_mfma_f32_16x16x32_bf16 v[20:23], v[170:173], v[204:207], 0
	v_mfma_f32_16x16x32_bf16 v[16:19], v[178:181], v[204:207], 0
	v_mfma_f32_16x16x32_bf16 v[4:7], v[170:173], v[212:215], 0
	v_mfma_f32_16x16x32_bf16 v[0:3], v[178:181], v[212:215], 0
	v_mfma_f32_16x16x32_bf16 v[52:55], v[174:177], v[192:195], v[52:55]
	v_mfma_f32_16x16x32_bf16 v[48:51], v[182:185], v[192:195], v[48:51]
	v_mfma_f32_16x16x32_bf16 v[36:39], v[174:177], v[200:203], v[36:39]
	v_mfma_f32_16x16x32_bf16 v[32:35], v[182:185], v[200:203], v[32:35]
	v_mfma_f32_16x16x32_bf16 v[20:23], v[174:177], v[208:211], v[20:23]
	v_mfma_f32_16x16x32_bf16 v[16:19], v[182:185], v[208:211], v[16:19]
	v_mfma_f32_16x16x32_bf16 v[4:7], v[174:177], v[216:219], v[4:7]
	v_mfma_f32_16x16x32_bf16 v[0:3], v[182:185], v[216:219], v[0:3]
	s_setprio 0
	s_barrier
	s_add_i32 s70, 0, 0x18000
	s_add_i32 s71, 0, 0x1c000
	v_add_u32_e32 v166, s70, v149
	v_add_u32_e32 v182, s71, v149
	ds_read_b128 v[154:157], v166
	ds_read_b128 v[158:161], v166 offset:1024
	ds_read_b128 v[162:165], v166 offset:2048
	ds_read_b128 v[166:169], v166 offset:3072
	ds_read_b128 v[170:173], v182
	ds_read_b128 v[174:177], v182 offset:1024
	ds_read_b128 v[178:181], v182 offset:2048
	ds_read_b128 v[182:185], v182 offset:3072
	s_mov_b32 m0, s27
	v_lshl_add_u64 v[224:225], s[36:37], 0, v[134:135]
	ds_read_b128 v[188:191], v153 offset:32768
	ds_read_b128 v[192:195], v153 offset:33792
	ds_read_b128 v[196:199], v153 offset:34816
	ds_read_b128 v[200:203], v153 offset:35840
	ds_read_b128 v[204:207], v153 offset:36864
	ds_read_b128 v[208:211], v153 offset:37888
	ds_read_b128 v[212:215], v153 offset:38912
	ds_read_b128 v[216:219], v153 offset:39936
	global_load_lds_dwordx4 v[224:225], off
	v_lshl_add_u64 v[224:225], s[36:37], 0, v[130:131]
	s_add_u32 s36, s36, 0x80000
	s_mov_b32 m0, s40
	s_addc_u32 s37, s37, 0
	global_load_lds_dwordx4 v[224:225], off
	v_lshl_add_u64 v[224:225], s[36:37], 0, v[134:135]
	s_mov_b32 m0, s41
	s_nop 0
	global_load_lds_dwordx4 v[224:225], off
	v_lshl_add_u64 v[224:225], s[36:37], 0, v[130:131]
	s_mov_b32 m0, s42
	s_nop 0
	global_load_lds_dwordx4 v[224:225], off
	s_waitcnt vmcnt(8)
	s_waitcnt lgkmcnt(0)
	s_setprio 3
	s_barrier
	v_mfma_f32_16x16x32_bf16 v[124:127], v[154:157], v[188:191], v[124:127]
	v_mfma_f32_16x16x32_bf16 v[120:123], v[162:165], v[188:191], v[120:123]
	v_mfma_f32_16x16x32_bf16 v[108:111], v[154:157], v[196:199], v[108:111]
	v_mfma_f32_16x16x32_bf16 v[104:107], v[162:165], v[196:199], v[104:107]
	v_mfma_f32_16x16x32_bf16 v[92:95], v[154:157], v[204:207], v[92:95]
	v_mfma_f32_16x16x32_bf16 v[88:91], v[162:165], v[204:207], v[88:91]
	v_mfma_f32_16x16x32_bf16 v[76:79], v[154:157], v[212:215], v[76:79]
	v_mfma_f32_16x16x32_bf16 v[72:75], v[162:165], v[212:215], v[72:75]
	v_mfma_f32_16x16x32_bf16 v[124:127], v[158:161], v[192:195], v[124:127]
	v_mfma_f32_16x16x32_bf16 v[120:123], v[166:169], v[192:195], v[120:123]
	v_mfma_f32_16x16x32_bf16 v[108:111], v[158:161], v[200:203], v[108:111]
	v_mfma_f32_16x16x32_bf16 v[104:107], v[166:169], v[200:203], v[104:107]
	v_mfma_f32_16x16x32_bf16 v[92:95], v[158:161], v[208:211], v[92:95]
	v_mfma_f32_16x16x32_bf16 v[88:91], v[166:169], v[208:211], v[88:91]
	v_mfma_f32_16x16x32_bf16 v[76:79], v[158:161], v[216:219], v[76:79]
	v_mfma_f32_16x16x32_bf16 v[72:75], v[166:169], v[216:219], v[72:75]
	s_setprio 0
	s_setprio 3
	v_mfma_f32_16x16x32_bf16 v[116:119], v[170:173], v[188:191], v[116:119]
	v_mfma_f32_16x16x32_bf16 v[112:115], v[178:181], v[188:191], v[112:115]
	v_mfma_f32_16x16x32_bf16 v[100:103], v[170:173], v[196:199], v[100:103]
	v_mfma_f32_16x16x32_bf16 v[96:99], v[178:181], v[196:199], v[96:99]
	v_mfma_f32_16x16x32_bf16 v[84:87], v[170:173], v[204:207], v[84:87]
	v_mfma_f32_16x16x32_bf16 v[80:83], v[178:181], v[204:207], v[80:83]
	v_mfma_f32_16x16x32_bf16 v[68:71], v[170:173], v[212:215], v[68:71]
	v_mfma_f32_16x16x32_bf16 v[64:67], v[178:181], v[212:215], v[64:67]
	v_mfma_f32_16x16x32_bf16 v[116:119], v[174:177], v[192:195], v[116:119]
	v_mfma_f32_16x16x32_bf16 v[112:115], v[182:185], v[192:195], v[112:115]
	v_mfma_f32_16x16x32_bf16 v[100:103], v[174:177], v[200:203], v[100:103]
	v_mfma_f32_16x16x32_bf16 v[96:99], v[182:185], v[200:203], v[96:99]
	v_mfma_f32_16x16x32_bf16 v[84:87], v[174:177], v[208:211], v[84:87]
	v_mfma_f32_16x16x32_bf16 v[80:83], v[182:185], v[208:211], v[80:83]
	v_mfma_f32_16x16x32_bf16 v[68:71], v[174:177], v[216:219], v[68:71]
	v_mfma_f32_16x16x32_bf16 v[64:67], v[182:185], v[216:219], v[64:67]
	s_setprio 0
	s_barrier
; #define PG8_STAGE(bufoff, gbase, voff) do { _Pragma("unroll") for (int _i = 0; _i < 2; ++_i) \
;         __builtin_amdgcn_global_load_lds((const unsigned*)((const char*)(gbase) + (voff)[_i]), (LAS unsigned*)(lds + (bufoff) + ldsw + _i * 8192), 16, 0, 0); } while (0)
; #define PG8_LDA(dst, b, h) do { _Pragma("unroll") for (int m = 0; m < 4; ++m) _Pragma("unroll") for (int k = 0; k < 2; ++k) dst[m][k] = *(const LAS bf16x8*)(lds + PG8_SA(b, h) + aoff + m * 2048 + k * 1024); } while (0)
; #define PG8_LDB(dst, b, h) do { _Pragma("unroll") for (int n = 0; n < 2; ++n) _Pragma("unroll") for (int k = 0; k < 2; ++k) dst[n][k] = *(const LAS bf16x8*)(lds + PG8_SB(b, h) + boff + n * 2048 + k * 1024); } while (0)
; #define PG8_MMA(ai, bj, At, Bt) do { __builtin_amdgcn_s_setprio(3); _Pragma("unroll") for (int m = 0; m < 4; ++m) _Pragma("unroll") for (int n = 0; n < 2; ++n) _Pragma("unroll") for (int k = 0; k < 2; ++k) \
;         acc[ai][bj][m][n] = __builtin_amdgcn_mfma_f32_16x16x32_bf16(Bt[n][k], At[m][k], acc[ai][bj][m][n], 0, 0, 0); __builtin_amdgcn_s_setprio(0); } while (0)
; #define PG8_WAIT_V(n) asm volatile("s_waitcnt vmcnt(" #n ")" ::: "memory")
; #define PG8_WAIT_L(n) asm volatile("s_waitcnt lgkmcnt(" #n ")" ::: "memory")
; #define PG8_BAR __builtin_amdgcn_s_barrier()
; #define PG8_SCHED __builtin_amdgcn_sched_barrier(0)
; template <class Epi, class Sched>
; __device__ __forceinline__ void gemm_phase(LAS unsigned char* lds, const Gemm g, const Sched& S, const Epi& E, int tid_in) {
;     ...
;             const bool last = (t == nt - 2);
;             const char* a1 = cA + (size_t)(t + 1) * kstep;
;             const char* a2 = last ? nA : cA + (size_t)(t + 2) * kstep; const char* b2 = last ? nB : cB + (size_t)(t + 2) * kstep;
;             const char* a3 = a2 + kstep; const char* b3 = b2 + kstep;
;             PG8_LDB(B0, 0, 0); PG8_LDB(B1, 0, 1); PG8_SCHED; PG8_LDA(At, 0, 0); PG8_STAGE(PG8_SA(1, 0), a1, voffA); PG8_STAGE(PG8_SA(1, 1), a1 + hstep, voffA);
;             PG8_WAIT_V(8); PG8_WAIT_L(0); PG8_BAR; PG8_MMA(0, 0, At, B0); PG8_MMA(0, 1, At, B1); PG8_BAR; PG8_SCHED;
;     ...
;             PG8_LDA(At, 1, 1); PG8_STAGE(PG8_SB(1, 0), b3, voffB); PG8_STAGE(PG8_SB(1, 1), b3 + hstep, voffB);
;             PG8_WAIT_V(6); PG8_WAIT_L(0); PG8_BAR; PG8_MMA(1, 0, At, B0); PG8_MMA(1, 1, At, B1); PG8_BAR; PG8_SCHED;
	s_add_i32 s36, s70, s38
	v_lshl_add_u64 v[220:221], v[220:221], 0, s[8:9]
	s_mov_b32 m0, s36
	ds_read_b128 v[188:191], v153 offset:49152
	ds_read_b128 v[192:195], v153 offset:50176
	ds_read_b128 v[196:199], v153 offset:51200
	ds_read_b128 v[200:203], v153 offset:52224
	ds_read_b128 v[204:207], v153 offset:53248
	ds_read_b128 v[208:211], v153 offset:54272
	ds_read_b128 v[212:215], v153 offset:55296
	ds_read_b128 v[216:219], v153 offset:56320
	global_load_lds_dwordx4 v[220:221], off
	s_add_i32 m0, s36, 0x2000
	s_add_u32 s34, s34, 0x80080
	v_lshl_add_u64 v[220:221], v[222:223], 0, s[8:9]
	s_addc_u32 s35, s35, 0
	s_add_i32 s36, s71, s38
	global_load_lds_dwordx4 v[220:221], off
	v_lshl_add_u64 v[220:221], s[34:35], 0, v[132:133]
	s_mov_b32 m0, s36
	s_nop 0
	global_load_lds_dwordx4 v[220:221], off
	v_lshl_add_u64 v[220:221], s[34:35], 0, v[128:129]
	s_add_i32 m0, s36, 0x2000
	s_nop 0
	global_load_lds_dwordx4 v[220:221], off
	s_waitcnt vmcnt(6)
	s_waitcnt lgkmcnt(0)
	s_setprio 3
	s_barrier
	v_mfma_f32_16x16x32_bf16 v[60:63], v[154:157], v[188:191], v[60:63]
	v_mfma_f32_16x16x32_bf16 v[56:59], v[162:165], v[188:191], v[56:59]
	v_mfma_f32_16x16x32_bf16 v[44:47], v[154:157], v[196:199], v[44:47]
	v_mfma_f32_16x16x32_bf16 v[40:43], v[162:165], v[196:199], v[40:43]
	v_mfma_f32_16x16x32_bf16 v[28:31], v[154:157], v[204:207], v[28:31]
	v_mfma_f32_16x16x32_bf16 v[24:27], v[162:165], v[204:207], v[24:27]
	v_mfma_f32_16x16x32_bf16 v[12:15], v[154:157], v[212:215], v[12:15]
	v_mfma_f32_16x16x32_bf16 v[8:11], v[162:165], v[212:215], v[8:11]
	v_mfma_f32_16x16x32_bf16 v[60:63], v[158:161], v[192:195], v[60:63]
	v_mfma_f32_16x16x32_bf16 v[56:59], v[166:169], v[192:195], v[56:59]
	v_mfma_f32_16x16x32_bf16 v[44:47], v[158:161], v[200:203], v[44:47]
	v_mfma_f32_16x16x32_bf16 v[40:43], v[166:169], v[200:203], v[40:43]
	v_mfma_f32_16x16x32_bf16 v[28:31], v[158:161], v[208:211], v[28:31]
	v_mfma_f32_16x16x32_bf16 v[24:27], v[166:169], v[208:211], v[24:27]
	v_mfma_f32_16x16x32_bf16 v[12:15], v[158:161], v[216:219], v[12:15]
	v_mfma_f32_16x16x32_bf16 v[8:11], v[166:169], v[216:219], v[8:11]
	s_setprio 0
	s_setprio 3
	v_mfma_f32_16x16x32_bf16 v[52:55], v[170:173], v[188:191], v[52:55]
	v_mfma_f32_16x16x32_bf16 v[48:51], v[178:181], v[188:191], v[48:51]
	v_mfma_f32_16x16x32_bf16 v[36:39], v[170:173], v[196:199], v[36:39]
	v_mfma_f32_16x16x32_bf16 v[32:35], v[178:181], v[196:199], v[32:35]
	v_mfma_f32_16x16x32_bf16 v[20:23], v[170:173], v[204:207], v[20:23]
	v_mfma_f32_16x16x32_bf16 v[16:19], v[178:181], v[204:207], v[16:19]
	v_mfma_f32_16x16x32_bf16 v[4:7], v[170:173], v[212:215], v[4:7]
	v_mfma_f32_16x16x32_bf16 v[0:3], v[178:181], v[212:215], v[0:3]
	v_mfma_f32_16x16x32_bf16 v[52:55], v[174:177], v[192:195], v[52:55]
	v_mfma_f32_16x16x32_bf16 v[48:51], v[182:185], v[192:195], v[48:51]
	v_mfma_f32_16x16x32_bf16 v[36:39], v[174:177], v[200:203], v[36:39]
	v_mfma_f32_16x16x32_bf16 v[32:35], v[182:185], v[200:203], v[32:35]
	v_mfma_f32_16x16x32_bf16 v[20:23], v[174:177], v[208:211], v[20:23]
	v_mfma_f32_16x16x32_bf16 v[16:19], v[182:185], v[208:211], v[16:19]
	v_mfma_f32_16x16x32_bf16 v[4:7], v[174:177], v[216:219], v[4:7]
	v_mfma_f32_16x16x32_bf16 v[0:3], v[182:185], v[216:219], v[0:3]
	s_setprio 0
	s_barrier
	s_add_i32 s69, s69, 2
	s_add_u32 s30, s30, 0x100
	s_addc_u32 s31, s31, 0
	s_cmp_gt_u32 s69, 29
	s_cbranch_scc0 .LBB0_763
	s_branch .Lpeel_exit_2
.LBB0_763:
	ds_read_b128 v[154:157], v151
	ds_read_b128 v[158:161], v151 offset:1024
	ds_read_b128 v[162:165], v151 offset:2048
	ds_read_b128 v[166:169], v151 offset:3072
	ds_read_b128 v[170:173], v152
	ds_read_b128 v[174:177], v152 offset:1024
	ds_read_b128 v[178:181], v152 offset:2048
	ds_read_b128 v[182:185], v152 offset:3072
	s_add_u32 s34, s28, s30
	s_addc_u32 s35, s29, s31
	s_add_u32 s36, s34, 0x100
	s_addc_u32 s37, s35, 0
	s_add_u32 s34, s51, s30
	s_addc_u32 s35, s68, s31
	s_cmpk_eq_i32 s30, 0xf00
	s_cselect_b32 s35, s19, s35
	s_cselect_b32 s34, s49, s34
	s_cselect_b32 s37, s21, s37
	s_cselect_b32 s36, s48, s36
	v_lshl_add_u64 v[220:221], v[146:147], 0, s[30:31]
	v_lshl_add_u64 v[222:223], v[220:221], 0, s[8:9]
	s_add_i32 m0, s27, 0x8000
	ds_read_b128 v[188:191], v153
	ds_read_b128 v[192:195], v153 offset:1024
	ds_read_b128 v[196:199], v153 offset:2048
	ds_read_b128 v[200:203], v153 offset:3072
	ds_read_b128 v[204:207], v153 offset:4096
	ds_read_b128 v[208:211], v153 offset:5120
	ds_read_b128 v[212:215], v153 offset:6144
	ds_read_b128 v[216:219], v153 offset:7168
	global_load_lds_dwordx4 v[222:223], off
	v_lshl_add_u64 v[222:223], v[144:145], 0, s[30:31]
	v_lshl_add_u64 v[224:225], v[222:223], 0, s[8:9]
	s_add_i32 m0, s27, 0xa000
	v_lshl_add_u64 v[220:221], v[220:221], 0, s[14:15]
	global_load_lds_dwordx4 v[224:225], off
	s_add_i32 m0, s27, 0xc000
	s_nop 0
	global_load_lds_dwordx4 v[220:221], off
	v_lshl_add_u64 v[220:221], v[222:223], 0, s[14:15]
	s_add_i32 m0, s27, 0xe000
	s_nop 0
	global_load_lds_dwordx4 v[220:221], off
	s_waitcnt vmcnt(8)
	s_waitcnt lgkmcnt(0)
	s_setprio 3
	s_barrier
; #define PG8_STAGE(bufoff, gbase, voff) do { _Pragma("unroll") for (int _i = 0; _i < 2; ++_i) \
;         __builtin_amdgcn_global_load_lds((const unsigned*)((const char*)(gbase) + (voff)[_i]), (LAS unsigned*)(lds + (bufoff) + ldsw + _i * 8192), 16, 0, 0); } while (0)
; #define PG8_LDA(dst, b, h) do { _Pragma("unroll") for (int m = 0; m < 4; ++m) _Pragma("unroll") for (int k = 0; k < 2; ++k) dst[m][k] = *(const LAS bf16x8*)(lds + PG8_SA(b, h) + aoff + m * 2048 + k * 1024); } while (0)
; #define PG8_MMA(ai, bj, At, Bt) do { __builtin_amdgcn_s_setprio(3); _Pragma("unroll") for (int m = 0; m < 4; ++m) _Pragma("unroll") for (int n = 0; n < 2; ++n) _Pragma("unroll") for (int k = 0; k < 2; ++k) \
;         acc[ai][bj][m][n] = __builtin_amdgcn_mfma_f32_16x16x32_bf16(Bt[n][k], At[m][k], acc[ai][bj][m][n], 0, 0, 0); __builtin_amdgcn_s_setprio(0); } while (0)
; #define PG8_WAIT_V(n) asm volatile("s_waitcnt vmcnt(" #n ")" ::: "memory")
; #define PG8_WAIT_L(n) asm volatile("s_waitcnt lgkmcnt(" #n ")" ::: "memory")
; #define PG8_BAR __builtin_amdgcn_s_barrier()
; #define PG8_SCHED __builtin_amdgcn_sched_barrier(0)
; template <class Epi, class Sched>
; __device__ __forceinline__ void gemm_phase(LAS unsigned char* lds, const Gemm g, const Sched& S, const Epi& E, int tid_in) {
;     ...
;             PG8_WAIT_V(8); PG8_WAIT_L(0); PG8_BAR; PG8_MMA(0, 0, At, B0); PG8_MMA(0, 1, At, B1); PG8_BAR; PG8_SCHED;
;             PG8_LDA(At, 0, 1); PG8_STAGE(PG8_SB(0, 0), b2, voffB); PG8_STAGE(PG8_SB(0, 1), b2 + hstep, voffB);
;             PG8_WAIT_V(6); PG8_WAIT_L(0); PG8_BAR; PG8_MMA(1, 0, At, B0); PG8_MMA(1, 1, At, B1); PG8_BAR; PG8_SCHED;
	v_mfma_f32_16x16x32_bf16 v[124:127], v[154:157], v[188:191], v[124:127]
	v_mfma_f32_16x16x32_bf16 v[120:123], v[162:165], v[188:191], v[120:123]
	v_mfma_f32_16x16x32_bf16 v[108:111], v[154:157], v[196:199], v[108:111]
	v_mfma_f32_16x16x32_bf16 v[104:107], v[162:165], v[196:199], v[104:107]
	v_mfma_f32_16x16x32_bf16 v[92:95], v[154:157], v[204:207], v[92:95]
	v_mfma_f32_16x16x32_bf16 v[88:91], v[162:165], v[204:207], v[88:91]
	v_mfma_f32_16x16x32_bf16 v[76:79], v[154:157], v[212:215], v[76:79]
	v_mfma_f32_16x16x32_bf16 v[72:75], v[162:165], v[212:215], v[72:75]
	v_mfma_f32_16x16x32_bf16 v[124:127], v[158:161], v[192:195], v[124:127]
	v_mfma_f32_16x16x32_bf16 v[120:123], v[166:169], v[192:195], v[120:123]
	v_mfma_f32_16x16x32_bf16 v[108:111], v[158:161], v[200:203], v[108:111]
	v_mfma_f32_16x16x32_bf16 v[104:107], v[166:169], v[200:203], v[104:107]
	v_mfma_f32_16x16x32_bf16 v[92:95], v[158:161], v[208:211], v[92:95]
	v_mfma_f32_16x16x32_bf16 v[88:91], v[166:169], v[208:211], v[88:91]
	v_mfma_f32_16x16x32_bf16 v[76:79], v[158:161], v[216:219], v[76:79]
	v_mfma_f32_16x16x32_bf16 v[72:75], v[166:169], v[216:219], v[72:75]
	s_setprio 0
	s_setprio 3
	v_mfma_f32_16x16x32_bf16 v[116:119], v[170:173], v[188:191], v[116:119]
	v_mfma_f32_16x16x32_bf16 v[112:115], v[178:181], v[188:191], v[112:115]
	v_mfma_f32_16x16x32_bf16 v[100:103], v[170:173], v[196:199], v[100:103]
	v_mfma_f32_16x16x32_bf16 v[96:99], v[178:181], v[196:199], v[96:99]
	v_mfma_f32_16x16x32_bf16 v[84:87], v[170:173], v[204:207], v[84:87]
	v_mfma_f32_16x16x32_bf16 v[80:83], v[178:181], v[204:207], v[80:83]
	v_mfma_f32_16x16x32_bf16 v[68:71], v[170:173], v[212:215], v[68:71]
	v_mfma_f32_16x16x32_bf16 v[64:67], v[178:181], v[212:215], v[64:67]
	v_mfma_f32_16x16x32_bf16 v[116:119], v[174:177], v[192:195], v[116:119]
	v_mfma_f32_16x16x32_bf16 v[112:115], v[182:185], v[192:195], v[112:115]
	v_mfma_f32_16x16x32_bf16 v[100:103], v[174:177], v[200:203], v[100:103]
	v_mfma_f32_16x16x32_bf16 v[96:99], v[182:185], v[200:203], v[96:99]
	v_mfma_f32_16x16x32_bf16 v[84:87], v[174:177], v[208:211], v[84:87]
	v_mfma_f32_16x16x32_bf16 v[80:83], v[182:185], v[208:211], v[80:83]
	v_mfma_f32_16x16x32_bf16 v[68:71], v[174:177], v[216:219], v[68:71]
	v_mfma_f32_16x16x32_bf16 v[64:67], v[182:185], v[216:219], v[64:67]
	s_setprio 0
	s_barrier
	s_add_i32 s70, s44, s38
	v_lshl_add_u64 v[220:221], s[34:35], 0, v[132:133]
	s_mov_b32 m0, s70
	ds_read_b128 v[188:191], v153 offset:16384
	ds_read_b128 v[192:195], v153 offset:17408
	ds_read_b128 v[196:199], v153 offset:18432
	ds_read_b128 v[200:203], v153 offset:19456
	ds_read_b128 v[204:207], v153 offset:20480
	ds_read_b128 v[208:211], v153 offset:21504
	ds_read_b128 v[212:215], v153 offset:22528
	ds_read_b128 v[216:219], v153 offset:23552
	global_load_lds_dwordx4 v[220:221], off
	s_add_i32 m0, s70, 0x2000
	s_add_u32 s70, s34, 0x80000
	v_lshl_add_u64 v[222:223], s[34:35], 0, v[128:129]
	s_addc_u32 s71, s35, 0
	s_add_i32 s72, s45, s38
	global_load_lds_dwordx4 v[222:223], off
	v_lshl_add_u64 v[224:225], s[70:71], 0, v[132:133]
	s_mov_b32 m0, s72
	s_nop 0
	global_load_lds_dwordx4 v[224:225], off
	v_lshl_add_u64 v[224:225], s[70:71], 0, v[128:129]
	s_add_i32 m0, s72, 0x2000
	s_nop 0
	global_load_lds_dwordx4 v[224:225], off
	s_waitcnt vmcnt(6)
	s_waitcnt lgkmcnt(0)
	s_setprio 3
	s_barrier
	v_mfma_f32_16x16x32_bf16 v[60:63], v[154:157], v[188:191], v[60:63]
	v_mfma_f32_16x16x32_bf16 v[56:59], v[162:165], v[188:191], v[56:59]
	v_mfma_f32_16x16x32_bf16 v[44:47], v[154:157], v[196:199], v[44:47]
	v_mfma_f32_16x16x32_bf16 v[40:43], v[162:165], v[196:199], v[40:43]
	v_mfma_f32_16x16x32_bf16 v[28:31], v[154:157], v[204:207], v[28:31]
	v_mfma_f32_16x16x32_bf16 v[24:27], v[162:165], v[204:207], v[24:27]
	v_mfma_f32_16x16x32_bf16 v[12:15], v[154:157], v[212:215], v[12:15]
	v_mfma_f32_16x16x32_bf16 v[8:11], v[162:165], v[212:215], v[8:11]
	v_mfma_f32_16x16x32_bf16 v[60:63], v[158:161], v[192:195], v[60:63]
	v_mfma_f32_16x16x32_bf16 v[56:59], v[166:169], v[192:195], v[56:59]
	v_mfma_f32_16x16x32_bf16 v[44:47], v[158:161], v[200:203], v[44:47]
	v_mfma_f32_16x16x32_bf16 v[40:43], v[166:169], v[200:203], v[40:43]
	v_mfma_f32_16x16x32_bf16 v[28:31], v[158:161], v[208:211], v[28:31]
	v_mfma_f32_16x16x32_bf16 v[24:27], v[166:169], v[208:211], v[24:27]
	v_mfma_f32_16x16x32_bf16 v[12:15], v[158:161], v[216:219], v[12:15]
	v_mfma_f32_16x16x32_bf16 v[8:11], v[166:169], v[216:219], v[8:11]
	s_setprio 0
	s_setprio 3
	v_mfma_f32_16x16x32_bf16 v[52:55], v[170:173], v[188:191], v[52:55]
	v_mfma_f32_16x16x32_bf16 v[48:51], v[178:181], v[188:191], v[48:51]
	v_mfma_f32_16x16x32_bf16 v[36:39], v[170:173], v[196:199], v[36:39]
	v_mfma_f32_16x16x32_bf16 v[32:35], v[178:181], v[196:199], v[32:35]
	v_mfma_f32_16x16x32_bf16 v[20:23], v[170:173], v[204:207], v[20:23]
	v_mfma_f32_16x16x32_bf16 v[16:19], v[178:181], v[204:207], v[16:19]
	v_mfma_f32_16x16x32_bf16 v[4:7], v[170:173], v[212:215], v[4:7]
	v_mfma_f32_16x16x32_bf16 v[0:3], v[178:181], v[212:215], v[0:3]
	v_mfma_f32_16x16x32_bf16 v[52:55], v[174:177], v[192:195], v[52:55]
	v_mfma_f32_16x16x32_bf16 v[48:51], v[182:185], v[192:195], v[48:51]
	v_mfma_f32_16x16x32_bf16 v[36:39], v[174:177], v[200:203], v[36:39]
	v_mfma_f32_16x16x32_bf16 v[32:35], v[182:185], v[200:203], v[32:35]
	v_mfma_f32_16x16x32_bf16 v[20:23], v[174:177], v[208:211], v[20:23]
	v_mfma_f32_16x16x32_bf16 v[16:19], v[182:185], v[208:211], v[16:19]
	v_mfma_f32_16x16x32_bf16 v[4:7], v[174:177], v[216:219], v[4:7]
	v_mfma_f32_16x16x32_bf16 v[0:3], v[182:185], v[216:219], v[0:3]
	s_setprio 0
	s_barrier
; #define PG8_STAGE(bufoff, gbase, voff) do { _Pragma("unroll") for (int _i = 0; _i < 2; ++_i) \
;         __builtin_amdgcn_global_load_lds((const unsigned*)((const char*)(gbase) + (voff)[_i]), (LAS unsigned*)(lds + (bufoff) + ldsw + _i * 8192), 16, 0, 0); } while (0)
; #define PG8_LDA(dst, b, h) do { _Pragma("unroll") for (int m = 0; m < 4; ++m) _Pragma("unroll") for (int k = 0; k < 2; ++k) dst[m][k] = *(const LAS bf16x8*)(lds + PG8_SA(b, h) + aoff + m * 2048 + k * 1024); } while (0)
; #define PG8_LDB(dst, b, h) do { _Pragma("unroll") for (int n = 0; n < 2; ++n) _Pragma("unroll") for (int k = 0; k < 2; ++k) dst[n][k] = *(const LAS bf16x8*)(lds + PG8_SB(b, h) + boff + n * 2048 + k * 1024); } while (0)
; #define PG8_MMA(ai, bj, At, Bt) do { __builtin_amdgcn_s_setprio(3); _Pragma("unroll") for (int m = 0; m < 4; ++m) _Pragma("unroll") for (int n = 0; n < 2; ++n) _Pragma("unroll") for (int k = 0; k < 2; ++k) \
;         acc[ai][bj][m][n] = __builtin_amdgcn_mfma_f32_16x16x32_bf16(Bt[n][k], At[m][k], acc[ai][bj][m][n], 0, 0, 0); __builtin_amdgcn_s_setprio(0); } while (0)
; #define PG8_WAIT_V(n) asm volatile("s_waitcnt vmcnt(" #n ")" ::: "memory")
; #define PG8_WAIT_L(n) asm volatile("s_waitcnt lgkmcnt(" #n ")" ::: "memory")
; #define PG8_BAR __builtin_amdgcn_s_barrier()
; #define PG8_SCHED __builtin_amdgcn_sched_barrier(0)
; template <class Epi, class Sched>
; __device__ __forceinline__ void gemm_phase(LAS unsigned char* lds, const Gemm g, const Sched& S, const Epi& E, int tid_in) {
;     ...
;             PG8_LDB(B0, 1, 0); PG8_LDB(B1, 1, 1); PG8_SCHED; PG8_LDA(At, 1, 0); PG8_STAGE(PG8_SA(0, 0), a2, voffA); PG8_STAGE(PG8_SA(0, 1), a2 + hstep, voffA);
;             PG8_WAIT_V(8); PG8_WAIT_L(0); PG8_BAR; PG8_MMA(0, 0, At, B0); PG8_MMA(0, 1, At, B1); PG8_BAR; PG8_SCHED;
;             PG8_LDA(At, 1, 1); PG8_STAGE(PG8_SB(1, 0), b3, voffB); PG8_STAGE(PG8_SB(1, 1), b3 + hstep, voffB);
;             PG8_WAIT_V(6); PG8_WAIT_L(0); PG8_BAR; PG8_MMA(1, 0, At, B0); PG8_MMA(1, 1, At, B1); PG8_BAR; PG8_SCHED;
;         }
	s_add_i32 s70, 0, 0x18000
	s_add_i32 s71, 0, 0x1c000
	v_add_u32_e32 v166, s70, v149
	v_add_u32_e32 v182, s71, v149
	ds_read_b128 v[154:157], v166
	ds_read_b128 v[158:161], v166 offset:1024
	ds_read_b128 v[162:165], v166 offset:2048
	ds_read_b128 v[166:169], v166 offset:3072
	ds_read_b128 v[170:173], v182
	ds_read_b128 v[174:177], v182 offset:1024
	ds_read_b128 v[178:181], v182 offset:2048
	ds_read_b128 v[182:185], v182 offset:3072
	s_mov_b32 m0, s27
	v_lshl_add_u64 v[224:225], s[36:37], 0, v[134:135]
	ds_read_b128 v[188:191], v153 offset:32768
	ds_read_b128 v[192:195], v153 offset:33792
	ds_read_b128 v[196:199], v153 offset:34816
	ds_read_b128 v[200:203], v153 offset:35840
	ds_read_b128 v[204:207], v153 offset:36864
	ds_read_b128 v[208:211], v153 offset:37888
	ds_read_b128 v[212:215], v153 offset:38912
	ds_read_b128 v[216:219], v153 offset:39936
	global_load_lds_dwordx4 v[224:225], off
	v_lshl_add_u64 v[224:225], s[36:37], 0, v[130:131]
	s_add_u32 s36, s36, 0x80000
	s_mov_b32 m0, s40
	s_addc_u32 s37, s37, 0
	global_load_lds_dwordx4 v[224:225], off
	v_lshl_add_u64 v[224:225], s[36:37], 0, v[134:135]
	s_mov_b32 m0, s41
	s_nop 0
	global_load_lds_dwordx4 v[224:225], off
	v_lshl_add_u64 v[224:225], s[36:37], 0, v[130:131]
	s_mov_b32 m0, s42
	s_nop 0
	global_load_lds_dwordx4 v[224:225], off
	s_waitcnt vmcnt(8)
	s_waitcnt lgkmcnt(0)
	s_setprio 3
	s_barrier
	v_mfma_f32_16x16x32_bf16 v[124:127], v[154:157], v[188:191], v[124:127]
	v_mfma_f32_16x16x32_bf16 v[120:123], v[162:165], v[188:191], v[120:123]
	v_mfma_f32_16x16x32_bf16 v[108:111], v[154:157], v[196:199], v[108:111]
	v_mfma_f32_16x16x32_bf16 v[104:107], v[162:165], v[196:199], v[104:107]
	v_mfma_f32_16x16x32_bf16 v[92:95], v[154:157], v[204:207], v[92:95]
	v_mfma_f32_16x16x32_bf16 v[88:91], v[162:165], v[204:207], v[88:91]
	v_mfma_f32_16x16x32_bf16 v[76:79], v[154:157], v[212:215], v[76:79]
	v_mfma_f32_16x16x32_bf16 v[72:75], v[162:165], v[212:215], v[72:75]
	v_mfma_f32_16x16x32_bf16 v[124:127], v[158:161], v[192:195], v[124:127]
	v_mfma_f32_16x16x32_bf16 v[120:123], v[166:169], v[192:195], v[120:123]
	v_mfma_f32_16x16x32_bf16 v[108:111], v[158:161], v[200:203], v[108:111]
	v_mfma_f32_16x16x32_bf16 v[104:107], v[166:169], v[200:203], v[104:107]
	v_mfma_f32_16x16x32_bf16 v[92:95], v[158:161], v[208:211], v[92:95]
	v_mfma_f32_16x16x32_bf16 v[88:91], v[166:169], v[208:211], v[88:91]
	v_mfma_f32_16x16x32_bf16 v[76:79], v[158:161], v[216:219], v[76:79]
	v_mfma_f32_16x16x32_bf16 v[72:75], v[166:169], v[216:219], v[72:75]
	s_setprio 0
	s_setprio 3
	v_mfma_f32_16x16x32_bf16 v[116:119], v[170:173], v[188:191], v[116:119]
	v_mfma_f32_16x16x32_bf16 v[112:115], v[178:181], v[188:191], v[112:115]
	v_mfma_f32_16x16x32_bf16 v[100:103], v[170:173], v[196:199], v[100:103]
	v_mfma_f32_16x16x32_bf16 v[96:99], v[178:181], v[196:199], v[96:99]
	v_mfma_f32_16x16x32_bf16 v[84:87], v[170:173], v[204:207], v[84:87]
	v_mfma_f32_16x16x32_bf16 v[80:83], v[178:181], v[204:207], v[80:83]
	v_mfma_f32_16x16x32_bf16 v[68:71], v[170:173], v[212:215], v[68:71]
	v_mfma_f32_16x16x32_bf16 v[64:67], v[178:181], v[212:215], v[64:67]
	v_mfma_f32_16x16x32_bf16 v[116:119], v[174:177], v[192:195], v[116:119]
	v_mfma_f32_16x16x32_bf16 v[112:115], v[182:185], v[192:195], v[112:115]
	v_mfma_f32_16x16x32_bf16 v[100:103], v[174:177], v[200:203], v[100:103]
	v_mfma_f32_16x16x32_bf16 v[96:99], v[182:185], v[200:203], v[96:99]
	v_mfma_f32_16x16x32_bf16 v[84:87], v[174:177], v[208:211], v[84:87]
	v_mfma_f32_16x16x32_bf16 v[80:83], v[182:185], v[208:211], v[80:83]
	v_mfma_f32_16x16x32_bf16 v[68:71], v[174:177], v[216:219], v[68:71]
	v_mfma_f32_16x16x32_bf16 v[64:67], v[182:185], v[216:219], v[64:67]
	s_setprio 0
	s_barrier
	s_add_i32 s36, s70, s38
	v_lshl_add_u64 v[220:221], v[220:221], 0, s[8:9]
	s_mov_b32 m0, s36
	ds_read_b128 v[188:191], v153 offset:49152
	ds_read_b128 v[192:195], v153 offset:50176
	ds_read_b128 v[196:199], v153 offset:51200
	ds_read_b128 v[200:203], v153 offset:52224
	ds_read_b128 v[204:207], v153 offset:53248
	ds_read_b128 v[208:211], v153 offset:54272
	ds_read_b128 v[212:215], v153 offset:55296
	ds_read_b128 v[216:219], v153 offset:56320
	global_load_lds_dwordx4 v[220:221], off
	s_add_i32 m0, s36, 0x2000
	s_add_u32 s34, s34, 0x80080
	v_lshl_add_u64 v[220:221], v[222:223], 0, s[8:9]
	s_addc_u32 s35, s35, 0
	s_add_i32 s36, s71, s38
	global_load_lds_dwordx4 v[220:221], off
	v_lshl_add_u64 v[220:221], s[34:35], 0, v[132:133]
	s_mov_b32 m0, s36
	s_nop 0
	global_load_lds_dwordx4 v[220:221], off
	v_lshl_add_u64 v[220:221], s[34:35], 0, v[128:129]
	s_add_i32 m0, s36, 0x2000
	s_nop 0
	global_load_lds_dwordx4 v[220:221], off
	s_waitcnt vmcnt(6)
	s_waitcnt lgkmcnt(0)
	s_setprio 3
	s_barrier
	v_mfma_f32_16x16x32_bf16 v[60:63], v[154:157], v[188:191], v[60:63]
	v_mfma_f32_16x16x32_bf16 v[56:59], v[162:165], v[188:191], v[56:59]
	v_mfma_f32_16x16x32_bf16 v[44:47], v[154:157], v[196:199], v[44:47]
	v_mfma_f32_16x16x32_bf16 v[40:43], v[162:165], v[196:199], v[40:43]
	v_mfma_f32_16x16x32_bf16 v[28:31], v[154:157], v[204:207], v[28:31]
	v_mfma_f32_16x16x32_bf16 v[24:27], v[162:165], v[204:207], v[24:27]
	v_mfma_f32_16x16x32_bf16 v[12:15], v[154:157], v[212:215], v[12:15]
	v_mfma_f32_16x16x32_bf16 v[8:11], v[162:165], v[212:215], v[8:11]
	v_mfma_f32_16x16x32_bf16 v[60:63], v[158:161], v[192:195], v[60:63]
	v_mfma_f32_16x16x32_bf16 v[56:59], v[166:169], v[192:195], v[56:59]
	v_mfma_f32_16x16x32_bf16 v[44:47], v[158:161], v[200:203], v[44:47]
	v_mfma_f32_16x16x32_bf16 v[40:43], v[166:169], v[200:203], v[40:43]
	v_mfma_f32_16x16x32_bf16 v[28:31], v[158:161], v[208:211], v[28:31]
	v_mfma_f32_16x16x32_bf16 v[24:27], v[166:169], v[208:211], v[24:27]
	v_mfma_f32_16x16x32_bf16 v[12:15], v[158:161], v[216:219], v[12:15]
	v_mfma_f32_16x16x32_bf16 v[8:11], v[166:169], v[216:219], v[8:11]
	s_setprio 0
	s_setprio 3
	v_mfma_f32_16x16x32_bf16 v[52:55], v[170:173], v[188:191], v[52:55]
	v_mfma_f32_16x16x32_bf16 v[48:51], v[178:181], v[188:191], v[48:51]
	v_mfma_f32_16x16x32_bf16 v[36:39], v[170:173], v[196:199], v[36:39]
	v_mfma_f32_16x16x32_bf16 v[32:35], v[178:181], v[196:199], v[32:35]
	v_mfma_f32_16x16x32_bf16 v[20:23], v[170:173], v[204:207], v[20:23]
	v_mfma_f32_16x16x32_bf16 v[16:19], v[178:181], v[204:207], v[16:19]
	v_mfma_f32_16x16x32_bf16 v[4:7], v[170:173], v[212:215], v[4:7]
	v_mfma_f32_16x16x32_bf16 v[0:3], v[178:181], v[212:215], v[0:3]
	v_mfma_f32_16x16x32_bf16 v[52:55], v[174:177], v[192:195], v[52:55]
	v_mfma_f32_16x16x32_bf16 v[48:51], v[182:185], v[192:195], v[48:51]
	v_mfma_f32_16x16x32_bf16 v[36:39], v[174:177], v[200:203], v[36:39]
	v_mfma_f32_16x16x32_bf16 v[32:35], v[182:185], v[200:203], v[32:35]
	v_mfma_f32_16x16x32_bf16 v[20:23], v[174:177], v[208:211], v[20:23]
	v_mfma_f32_16x16x32_bf16 v[16:19], v[182:185], v[208:211], v[16:19]
	v_mfma_f32_16x16x32_bf16 v[4:7], v[174:177], v[216:219], v[4:7]
	v_mfma_f32_16x16x32_bf16 v[0:3], v[182:185], v[216:219], v[0:3]
	s_setprio 0
	s_barrier
	s_add_i32 s69, s69, 2
	s_add_u32 s30, s30, 0x100
	s_addc_u32 s31, s31, 0
	s_cmp_gt_u32 s69, 29
	s_cbranch_scc0 .LBB0_763

; #define PG8_STAGE(bufoff, gbase, voff) do { _Pragma("unroll") for (int _i = 0; _i < 2; ++_i) \
;         __builtin_amdgcn_global_load_lds((const unsigned*)((const char*)(gbase) + (voff)[_i]), (LAS unsigned*)(lds + (bufoff) + ldsw + _i * 8192), 16, 0, 0); } while (0)
; #define PG8_LDA(dst, b, h) do { _Pragma("unroll") for (int m = 0; m < 4; ++m) _Pragma("unroll") for (int k = 0; k < 2; ++k) dst[m][k] = *(const LAS bf16x8*)(lds + PG8_SA(b, h) + aoff + m * 2048 + k * 1024); } while (0)
; #define PG8_LDB(dst, b, h) do { _Pragma("unroll") for (int n = 0; n < 2; ++n) _Pragma("unroll") for (int k = 0; k < 2; ++k) dst[n][k] = *(const LAS bf16x8*)(lds + PG8_SB(b, h) + boff + n * 2048 + k * 1024); } while (0)
; #define PG8_MMA(ai, bj, At, Bt) do { __builtin_amdgcn_s_setprio(3); _Pragma("unroll") for (int m = 0; m < 4; ++m) _Pragma("unroll") for (int n = 0; n < 2; ++n) _Pragma("unroll") for (int k = 0; k < 2; ++k) \
;         acc[ai][bj][m][n] = __builtin_amdgcn_mfma_f32_16x16x32_bf16(Bt[n][k], At[m][k], acc[ai][bj][m][n], 0, 0, 0); __builtin_amdgcn_s_setprio(0); } while (0)
; #define PG8_WAIT_V(n) asm volatile("s_waitcnt vmcnt(" #n ")" ::: "memory")
; template <class Epi, class Sched>
; __device__ __forceinline__ void gemm_phase(LAS unsigned char* lds, const Gemm g, const Sched& S, const Epi& E, int tid_in) {
;     ...
;         const char* nA = has_next ? (const char*)g.A + (size_t)nxt.pm * tstep + nxt.koff : cA; const char* nB = has_next ? (const char*)g.Bt + (size_t)nxt.pn * tstep + nxt.koff : cB;
;         for (int t = 0; t < nt; t += 2) {
;             const bool last = (t == nt - 2);
;             const char* a1 = cA + (size_t)(t + 1) * kstep;
;             const char* a2 = last ? nA : cA + (size_t)(t + 2) * kstep; const char* b2 = last ? nB : cB + (size_t)(t + 2) * kstep;
;             const char* a3 = a2 + kstep; const char* b3 = b2 + kstep;
;             PG8_LDB(B0, 0, 0); PG8_LDB(B1, 0, 1); PG8_SCHED; PG8_LDA(At, 0, 0); PG8_STAGE(PG8_SA(1, 0), a1, voffA); PG8_STAGE(PG8_SA(1, 1), a1 + hstep, voffA);
;             PG8_WAIT_V(8); PG8_WAIT_L(0); PG8_BAR; PG8_MMA(0, 0, At, B0); PG8_MMA(0, 1, At, B1); PG8_BAR; PG8_SCHED;
;             PG8_LDA(At, 0, 1); PG8_STAGE(PG8_SB(0, 0), b2, voffB); PG8_STAGE(PG8_SB(0, 1), b2 + hstep, voffB);
;             PG8_WAIT_V(6); PG8_WAIT_L(0); PG8_BAR; PG8_MMA(1, 0, At, B0); PG8_MMA(1, 1, At, B1); PG8_BAR; PG8_SCHED;
.LBB0_841:
	s_add_u32 s46, s28, 0x100
	s_addc_u32 s47, s29, 0
	v_lshl_add_u64 v[144:145], s[26:27], 0, v[136:137]
	v_lshl_add_u64 v[146:147], s[26:27], 0, v[138:139]
	s_mov_b32 s48, -2
	s_mov_b64 s[28:29], 0
	s_waitcnt lgkmcnt(0)
	ds_read_b128 v[156:159], v151
	ds_read_b128 v[160:163], v151 offset:1024
	ds_read_b128 v[164:167], v151 offset:2048
	ds_read_b128 v[168:171], v151 offset:3072
	ds_read_b128 v[172:175], v152
	ds_read_b128 v[176:179], v152 offset:1024
	ds_read_b128 v[180:183], v152 offset:2048
	ds_read_b128 v[188:191], v152 offset:3072
	s_add_u32 s30, s26, s28
	s_addc_u32 s31, s27, s29
	s_add_u32 s34, s30, 0x100
	s_addc_u32 s35, s31, 0
	s_add_u32 s30, s46, s28
	s_addc_u32 s31, s47, s29
	s_cmpk_eq_i32 s28, 0x2b00
	s_cselect_b32 s31, s25, s31
	s_cselect_b32 s30, s24, s30
	s_cselect_b32 s35, s7, s35
	s_cselect_b32 s34, s6, s34
	v_lshl_add_u64 v[184:185], v[144:145], 0, s[28:29]
	v_lshl_add_u64 v[224:225], v[184:185], 0, s[18:19]
	s_add_i32 m0, s3, 0x8000
	ds_read_b128 v[192:195], v153
	ds_read_b128 v[196:199], v153 offset:1024
	ds_read_b128 v[200:203], v153 offset:2048
	ds_read_b128 v[204:207], v153 offset:3072
	ds_read_b128 v[208:211], v153 offset:4096
	ds_read_b128 v[212:215], v153 offset:5120
	ds_read_b128 v[216:219], v153 offset:6144
	ds_read_b128 v[220:223], v153 offset:7168
	global_load_lds_dwordx4 v[224:225], off
	v_lshl_add_u64 v[224:225], v[146:147], 0, s[28:29]
	v_lshl_add_u64 v[226:227], v[224:225], 0, s[18:19]
	s_add_i32 m0, s3, 0xa000
	v_lshl_add_u64 v[184:185], v[184:185], 0, s[20:21]
	global_load_lds_dwordx4 v[226:227], off
	s_add_i32 m0, s3, 0xc000
	s_nop 0
	global_load_lds_dwordx4 v[184:185], off
	v_lshl_add_u64 v[184:185], v[224:225], 0, s[20:21]
	s_add_i32 m0, s3, 0xe000
	s_nop 0
	global_load_lds_dwordx4 v[184:185], off
	s_waitcnt vmcnt(8)
	s_waitcnt lgkmcnt(0)
	s_setprio 3
	s_barrier
	v_mfma_f32_16x16x32_bf16 v[124:127], v[156:159], v[192:195], 0
	v_mfma_f32_16x16x32_bf16 v[120:123], v[164:167], v[192:195], 0
	v_mfma_f32_16x16x32_bf16 v[108:111], v[156:159], v[200:203], 0
	v_mfma_f32_16x16x32_bf16 v[104:107], v[164:167], v[200:203], 0
	v_mfma_f32_16x16x32_bf16 v[92:95], v[156:159], v[208:211], 0
	v_mfma_f32_16x16x32_bf16 v[88:91], v[164:167], v[208:211], 0
	v_mfma_f32_16x16x32_bf16 v[76:79], v[156:159], v[216:219], 0
	v_mfma_f32_16x16x32_bf16 v[72:75], v[164:167], v[216:219], 0
	v_mfma_f32_16x16x32_bf16 v[124:127], v[160:163], v[196:199], v[124:127]
	v_mfma_f32_16x16x32_bf16 v[120:123], v[168:171], v[196:199], v[120:123]
	v_mfma_f32_16x16x32_bf16 v[108:111], v[160:163], v[204:207], v[108:111]
	v_mfma_f32_16x16x32_bf16 v[104:107], v[168:171], v[204:207], v[104:107]
	v_mfma_f32_16x16x32_bf16 v[92:95], v[160:163], v[212:215], v[92:95]
	v_mfma_f32_16x16x32_bf16 v[88:91], v[168:171], v[212:215], v[88:91]
	v_mfma_f32_16x16x32_bf16 v[76:79], v[160:163], v[220:223], v[76:79]
	v_mfma_f32_16x16x32_bf16 v[72:75], v[168:171], v[220:223], v[72:75]
	s_setprio 0
	s_setprio 3
	v_mfma_f32_16x16x32_bf16 v[116:119], v[172:175], v[192:195], 0
	v_mfma_f32_16x16x32_bf16 v[112:115], v[180:183], v[192:195], 0
	v_mfma_f32_16x16x32_bf16 v[100:103], v[172:175], v[200:203], 0
	v_mfma_f32_16x16x32_bf16 v[96:99], v[180:183], v[200:203], 0
	v_mfma_f32_16x16x32_bf16 v[84:87], v[172:175], v[208:211], 0
	v_mfma_f32_16x16x32_bf16 v[80:83], v[180:183], v[208:211], 0
	v_mfma_f32_16x16x32_bf16 v[68:71], v[172:175], v[216:219], 0
	v_mfma_f32_16x16x32_bf16 v[64:67], v[180:183], v[216:219], 0
	v_mfma_f32_16x16x32_bf16 v[116:119], v[176:179], v[196:199], v[116:119]
	v_mfma_f32_16x16x32_bf16 v[112:115], v[188:191], v[196:199], v[112:115]
	v_mfma_f32_16x16x32_bf16 v[100:103], v[176:179], v[204:207], v[100:103]
	v_mfma_f32_16x16x32_bf16 v[96:99], v[188:191], v[204:207], v[96:99]
	v_mfma_f32_16x16x32_bf16 v[84:87], v[176:179], v[212:215], v[84:87]
	v_mfma_f32_16x16x32_bf16 v[80:83], v[188:191], v[212:215], v[80:83]
	v_mfma_f32_16x16x32_bf16 v[68:71], v[176:179], v[220:223], v[68:71]
	v_mfma_f32_16x16x32_bf16 v[64:67], v[188:191], v[220:223], v[64:67]
	s_setprio 0
	s_barrier
	s_add_i32 s49, s40, s2
	v_lshl_add_u64 v[184:185], s[30:31], 0, v[130:131]
	s_mov_b32 m0, s49
	ds_read_b128 v[192:195], v153 offset:16384
	ds_read_b128 v[196:199], v153 offset:17408
	ds_read_b128 v[200:203], v153 offset:18432
	ds_read_b128 v[204:207], v153 offset:19456
	ds_read_b128 v[208:211], v153 offset:20480
	ds_read_b128 v[212:215], v153 offset:21504
	ds_read_b128 v[216:219], v153 offset:22528
	ds_read_b128 v[220:223], v153 offset:23552
	global_load_lds_dwordx4 v[184:185], off
	s_add_i32 m0, s49, 0x2000
	s_add_u32 s68, s30, 0x160000
	v_lshl_add_u64 v[224:225], s[30:31], 0, v[134:135]
	s_addc_u32 s69, s31, 0
	s_add_i32 s49, s41, s2
	global_load_lds_dwordx4 v[224:225], off
	v_lshl_add_u64 v[226:227], s[68:69], 0, v[130:131]
	s_mov_b32 m0, s49
	s_nop 0
	global_load_lds_dwordx4 v[226:227], off
	v_lshl_add_u64 v[226:227], s[68:69], 0, v[134:135]
	s_add_i32 m0, s49, 0x2000
	s_nop 0
	global_load_lds_dwordx4 v[226:227], off
	s_waitcnt vmcnt(6)
	s_waitcnt lgkmcnt(0)
	s_setprio 3
	s_barrier
; #define PG8_STAGE(bufoff, gbase, voff) do { _Pragma("unroll") for (int _i = 0; _i < 2; ++_i) \
;         __builtin_amdgcn_global_load_lds((const unsigned*)((const char*)(gbase) + (voff)[_i]), (LAS unsigned*)(lds + (bufoff) + ldsw + _i * 8192), 16, 0, 0); } while (0)
; #define PG8_LDA(dst, b, h) do { _Pragma("unroll") for (int m = 0; m < 4; ++m) _Pragma("unroll") for (int k = 0; k < 2; ++k) dst[m][k] = *(const LAS bf16x8*)(lds + PG8_SA(b, h) + aoff + m * 2048 + k * 1024); } while (0)
; #define PG8_LDB(dst, b, h) do { _Pragma("unroll") for (int n = 0; n < 2; ++n) _Pragma("unroll") for (int k = 0; k < 2; ++k) dst[n][k] = *(const LAS bf16x8*)(lds + PG8_SB(b, h) + boff + n * 2048 + k * 1024); } while (0)
; #define PG8_MMA(ai, bj, At, Bt) do { __builtin_amdgcn_s_setprio(3); _Pragma("unroll") for (int m = 0; m < 4; ++m) _Pragma("unroll") for (int n = 0; n < 2; ++n) _Pragma("unroll") for (int k = 0; k < 2; ++k) \
;         acc[ai][bj][m][n] = __builtin_amdgcn_mfma_f32_16x16x32_bf16(Bt[n][k], At[m][k], acc[ai][bj][m][n], 0, 0, 0); __builtin_amdgcn_s_setprio(0); } while (0)
; #define PG8_WAIT_V(n) asm volatile("s_waitcnt vmcnt(" #n ")" ::: "memory")
; #define PG8_WAIT_L(n) asm volatile("s_waitcnt lgkmcnt(" #n ")" ::: "memory")
; #define PG8_BAR __builtin_amdgcn_s_barrier()
; #define PG8_SCHED __builtin_amdgcn_sched_barrier(0)
; template <class Epi, class Sched>
; __device__ __forceinline__ void gemm_phase(LAS unsigned char* lds, const Gemm g, const Sched& S, const Epi& E, int tid_in) {
;     ...
;             PG8_WAIT_V(6); PG8_WAIT_L(0); PG8_BAR; PG8_MMA(1, 0, At, B0); PG8_MMA(1, 1, At, B1); PG8_BAR; PG8_SCHED;
;             PG8_LDB(B0, 1, 0); PG8_LDB(B1, 1, 1); PG8_SCHED; PG8_LDA(At, 1, 0); PG8_STAGE(PG8_SA(0, 0), a2, voffA); PG8_STAGE(PG8_SA(0, 1), a2 + hstep, voffA);
;             PG8_WAIT_V(8); PG8_WAIT_L(0); PG8_BAR; PG8_MMA(0, 0, At, B0); PG8_MMA(0, 1, At, B1); PG8_BAR; PG8_SCHED;
	v_mfma_f32_16x16x32_bf16 v[60:63], v[156:159], v[192:195], 0
	v_mfma_f32_16x16x32_bf16 v[56:59], v[164:167], v[192:195], 0
	v_mfma_f32_16x16x32_bf16 v[44:47], v[156:159], v[200:203], 0
	v_mfma_f32_16x16x32_bf16 v[40:43], v[164:167], v[200:203], 0
	v_mfma_f32_16x16x32_bf16 v[28:31], v[156:159], v[208:211], 0
	v_mfma_f32_16x16x32_bf16 v[24:27], v[164:167], v[208:211], 0
	v_mfma_f32_16x16x32_bf16 v[12:15], v[156:159], v[216:219], 0
	v_mfma_f32_16x16x32_bf16 v[8:11], v[164:167], v[216:219], 0
	v_mfma_f32_16x16x32_bf16 v[60:63], v[160:163], v[196:199], v[60:63]
	v_mfma_f32_16x16x32_bf16 v[56:59], v[168:171], v[196:199], v[56:59]
	v_mfma_f32_16x16x32_bf16 v[44:47], v[160:163], v[204:207], v[44:47]
	v_mfma_f32_16x16x32_bf16 v[40:43], v[168:171], v[204:207], v[40:43]
	v_mfma_f32_16x16x32_bf16 v[28:31], v[160:163], v[212:215], v[28:31]
	v_mfma_f32_16x16x32_bf16 v[24:27], v[168:171], v[212:215], v[24:27]
	v_mfma_f32_16x16x32_bf16 v[12:15], v[160:163], v[220:223], v[12:15]
	v_mfma_f32_16x16x32_bf16 v[8:11], v[168:171], v[220:223], v[8:11]
	s_setprio 0
	s_setprio 3
	v_mfma_f32_16x16x32_bf16 v[52:55], v[172:175], v[192:195], 0
	v_mfma_f32_16x16x32_bf16 v[48:51], v[180:183], v[192:195], 0
	v_mfma_f32_16x16x32_bf16 v[36:39], v[172:175], v[200:203], 0
	v_mfma_f32_16x16x32_bf16 v[32:35], v[180:183], v[200:203], 0
	v_mfma_f32_16x16x32_bf16 v[20:23], v[172:175], v[208:211], 0
	v_mfma_f32_16x16x32_bf16 v[16:19], v[180:183], v[208:211], 0
	v_mfma_f32_16x16x32_bf16 v[4:7], v[172:175], v[216:219], 0
	v_mfma_f32_16x16x32_bf16 v[0:3], v[180:183], v[216:219], 0
	v_mfma_f32_16x16x32_bf16 v[52:55], v[176:179], v[196:199], v[52:55]
	v_mfma_f32_16x16x32_bf16 v[48:51], v[188:191], v[196:199], v[48:51]
	v_mfma_f32_16x16x32_bf16 v[36:39], v[176:179], v[204:207], v[36:39]
	v_mfma_f32_16x16x32_bf16 v[32:35], v[188:191], v[204:207], v[32:35]
	v_mfma_f32_16x16x32_bf16 v[20:23], v[176:179], v[212:215], v[20:23]
	v_mfma_f32_16x16x32_bf16 v[16:19], v[188:191], v[212:215], v[16:19]
	v_mfma_f32_16x16x32_bf16 v[4:7], v[176:179], v[220:223], v[4:7]
	v_mfma_f32_16x16x32_bf16 v[0:3], v[188:191], v[220:223], v[0:3]
	s_setprio 0
	s_barrier
	s_add_i32 s49, 0, 0x18000
	v_add_u32_e32 v155, s49, v149
	s_add_i32 s51, 0, 0x1c000
	ds_read_b128 v[156:159], v155
	ds_read_b128 v[160:163], v155 offset:1024
	ds_read_b128 v[164:167], v155 offset:2048
	ds_read_b128 v[168:171], v155 offset:3072
	v_add_u32_e32 v155, s51, v149
	ds_read_b128 v[172:175], v155
	ds_read_b128 v[176:179], v155 offset:1024
	ds_read_b128 v[180:183], v155 offset:2048
	ds_read_b128 v[188:191], v155 offset:3072
	s_mov_b32 m0, s3
	v_lshl_add_u64 v[226:227], s[34:35], 0, v[128:129]
	ds_read_b128 v[192:195], v153 offset:32768
	ds_read_b128 v[196:199], v153 offset:33792
	ds_read_b128 v[200:203], v153 offset:34816
	ds_read_b128 v[204:207], v153 offset:35840
	ds_read_b128 v[208:211], v153 offset:36864
	ds_read_b128 v[212:215], v153 offset:37888
	ds_read_b128 v[216:219], v153 offset:38912
	ds_read_b128 v[220:223], v153 offset:39936
	global_load_lds_dwordx4 v[226:227], off
	v_lshl_add_u64 v[226:227], s[34:35], 0, v[132:133]
	s_add_u32 s34, s34, 0x160000
	s_mov_b32 m0, s36
	s_addc_u32 s35, s35, 0
	global_load_lds_dwordx4 v[226:227], off
	v_lshl_add_u64 v[226:227], s[34:35], 0, v[128:129]
	s_mov_b32 m0, s37
	s_nop 0
	global_load_lds_dwordx4 v[226:227], off
	v_lshl_add_u64 v[226:227], s[34:35], 0, v[132:133]
	s_mov_b32 m0, s38
	s_nop 0
	global_load_lds_dwordx4 v[226:227], off
	s_waitcnt vmcnt(8)
	s_waitcnt lgkmcnt(0)
	s_setprio 3
	s_barrier
	v_mfma_f32_16x16x32_bf16 v[124:127], v[156:159], v[192:195], v[124:127]
	v_mfma_f32_16x16x32_bf16 v[120:123], v[164:167], v[192:195], v[120:123]
	v_mfma_f32_16x16x32_bf16 v[108:111], v[156:159], v[200:203], v[108:111]
	v_mfma_f32_16x16x32_bf16 v[104:107], v[164:167], v[200:203], v[104:107]
	v_mfma_f32_16x16x32_bf16 v[92:95], v[156:159], v[208:211], v[92:95]
	v_mfma_f32_16x16x32_bf16 v[88:91], v[164:167], v[208:211], v[88:91]
	v_mfma_f32_16x16x32_bf16 v[76:79], v[156:159], v[216:219], v[76:79]
	v_mfma_f32_16x16x32_bf16 v[72:75], v[164:167], v[216:219], v[72:75]
	v_mfma_f32_16x16x32_bf16 v[124:127], v[160:163], v[196:199], v[124:127]
	v_mfma_f32_16x16x32_bf16 v[120:123], v[168:171], v[196:199], v[120:123]
	v_mfma_f32_16x16x32_bf16 v[108:111], v[160:163], v[204:207], v[108:111]
	v_mfma_f32_16x16x32_bf16 v[104:107], v[168:171], v[204:207], v[104:107]
	v_mfma_f32_16x16x32_bf16 v[92:95], v[160:163], v[212:215], v[92:95]
	v_mfma_f32_16x16x32_bf16 v[88:91], v[168:171], v[212:215], v[88:91]
	v_mfma_f32_16x16x32_bf16 v[76:79], v[160:163], v[220:223], v[76:79]
	v_mfma_f32_16x16x32_bf16 v[72:75], v[168:171], v[220:223], v[72:75]
	s_setprio 0
	s_setprio 3
	v_mfma_f32_16x16x32_bf16 v[116:119], v[172:175], v[192:195], v[116:119]
	v_mfma_f32_16x16x32_bf16 v[112:115], v[180:183], v[192:195], v[112:115]
	v_mfma_f32_16x16x32_bf16 v[100:103], v[172:175], v[200:203], v[100:103]
	v_mfma_f32_16x16x32_bf16 v[96:99], v[180:183], v[200:203], v[96:99]
	v_mfma_f32_16x16x32_bf16 v[84:87], v[172:175], v[208:211], v[84:87]
	v_mfma_f32_16x16x32_bf16 v[80:83], v[180:183], v[208:211], v[80:83]
	v_mfma_f32_16x16x32_bf16 v[68:71], v[172:175], v[216:219], v[68:71]
	v_mfma_f32_16x16x32_bf16 v[64:67], v[180:183], v[216:219], v[64:67]
	v_mfma_f32_16x16x32_bf16 v[116:119], v[176:179], v[196:199], v[116:119]
	v_mfma_f32_16x16x32_bf16 v[112:115], v[188:191], v[196:199], v[112:115]
	v_mfma_f32_16x16x32_bf16 v[100:103], v[176:179], v[204:207], v[100:103]
	v_mfma_f32_16x16x32_bf16 v[96:99], v[188:191], v[204:207], v[96:99]
	v_mfma_f32_16x16x32_bf16 v[84:87], v[176:179], v[212:215], v[84:87]
	v_mfma_f32_16x16x32_bf16 v[80:83], v[188:191], v[212:215], v[80:83]
	v_mfma_f32_16x16x32_bf16 v[68:71], v[176:179], v[220:223], v[68:71]
	v_mfma_f32_16x16x32_bf16 v[64:67], v[188:191], v[220:223], v[64:67]
	s_setprio 0
	s_barrier
; #define PG8_STAGE(bufoff, gbase, voff) do { _Pragma("unroll") for (int _i = 0; _i < 2; ++_i) \
;         __builtin_amdgcn_global_load_lds((const unsigned*)((const char*)(gbase) + (voff)[_i]), (LAS unsigned*)(lds + (bufoff) + ldsw + _i * 8192), 16, 0, 0); } while (0)
; #define PG8_LDA(dst, b, h) do { _Pragma("unroll") for (int m = 0; m < 4; ++m) _Pragma("unroll") for (int k = 0; k < 2; ++k) dst[m][k] = *(const LAS bf16x8*)(lds + PG8_SA(b, h) + aoff + m * 2048 + k * 1024); } while (0)
; #define PG8_LDB(dst, b, h) do { _Pragma("unroll") for (int n = 0; n < 2; ++n) _Pragma("unroll") for (int k = 0; k < 2; ++k) dst[n][k] = *(const LAS bf16x8*)(lds + PG8_SB(b, h) + boff + n * 2048 + k * 1024); } while (0)
; #define PG8_MMA(ai, bj, At, Bt) do { __builtin_amdgcn_s_setprio(3); _Pragma("unroll") for (int m = 0; m < 4; ++m) _Pragma("unroll") for (int n = 0; n < 2; ++n) _Pragma("unroll") for (int k = 0; k < 2; ++k) \
;         acc[ai][bj][m][n] = __builtin_amdgcn_mfma_f32_16x16x32_bf16(Bt[n][k], At[m][k], acc[ai][bj][m][n], 0, 0, 0); __builtin_amdgcn_s_setprio(0); } while (0)
; #define PG8_WAIT_V(n) asm volatile("s_waitcnt vmcnt(" #n ")" ::: "memory")
; #define PG8_WAIT_L(n) asm volatile("s_waitcnt lgkmcnt(" #n ")" ::: "memory")
; #define PG8_BAR __builtin_amdgcn_s_barrier()
; #define PG8_SCHED __builtin_amdgcn_sched_barrier(0)
; template <class Epi, class Sched>
; __device__ __forceinline__ void gemm_phase(LAS unsigned char* lds, const Gemm g, const Sched& S, const Epi& E, int tid_in) {
;     ...
;             const bool last = (t == nt - 2);
;             const char* a1 = cA + (size_t)(t + 1) * kstep;
;             const char* a2 = last ? nA : cA + (size_t)(t + 2) * kstep; const char* b2 = last ? nB : cB + (size_t)(t + 2) * kstep;
;             const char* a3 = a2 + kstep; const char* b3 = b2 + kstep;
;             PG8_LDB(B0, 0, 0); PG8_LDB(B1, 0, 1); PG8_SCHED; PG8_LDA(At, 0, 0); PG8_STAGE(PG8_SA(1, 0), a1, voffA); PG8_STAGE(PG8_SA(1, 1), a1 + hstep, voffA);
;             PG8_WAIT_V(8); PG8_WAIT_L(0); PG8_BAR; PG8_MMA(0, 0, At, B0); PG8_MMA(0, 1, At, B1); PG8_BAR; PG8_SCHED;
;     ...
;             PG8_LDA(At, 1, 1); PG8_STAGE(PG8_SB(1, 0), b3, voffB); PG8_STAGE(PG8_SB(1, 1), b3 + hstep, voffB);
;             PG8_WAIT_V(6); PG8_WAIT_L(0); PG8_BAR; PG8_MMA(1, 0, At, B0); PG8_MMA(1, 1, At, B1); PG8_BAR; PG8_SCHED;
	s_add_i32 s34, s49, s2
	v_lshl_add_u64 v[184:185], v[184:185], 0, s[18:19]
	s_mov_b32 m0, s34
	ds_read_b128 v[192:195], v153 offset:49152
	ds_read_b128 v[196:199], v153 offset:50176
	ds_read_b128 v[200:203], v153 offset:51200
	ds_read_b128 v[204:207], v153 offset:52224
	ds_read_b128 v[208:211], v153 offset:53248
	ds_read_b128 v[212:215], v153 offset:54272
	ds_read_b128 v[216:219], v153 offset:55296
	ds_read_b128 v[220:223], v153 offset:56320
	global_load_lds_dwordx4 v[184:185], off
	s_add_i32 m0, s34, 0x2000
	s_add_u32 s30, s30, 0x160080
	v_lshl_add_u64 v[184:185], v[224:225], 0, s[18:19]
	s_addc_u32 s31, s31, 0
	s_add_i32 s34, s51, s2
	global_load_lds_dwordx4 v[184:185], off
	v_lshl_add_u64 v[184:185], s[30:31], 0, v[130:131]
	s_mov_b32 m0, s34
	s_nop 0
	global_load_lds_dwordx4 v[184:185], off
	v_lshl_add_u64 v[184:185], s[30:31], 0, v[134:135]
	s_add_i32 m0, s34, 0x2000
	s_nop 0
	global_load_lds_dwordx4 v[184:185], off
	s_waitcnt vmcnt(6)
	s_waitcnt lgkmcnt(0)
	s_setprio 3
	s_barrier
	v_mfma_f32_16x16x32_bf16 v[60:63], v[156:159], v[192:195], v[60:63]
	v_mfma_f32_16x16x32_bf16 v[56:59], v[164:167], v[192:195], v[56:59]
	v_mfma_f32_16x16x32_bf16 v[44:47], v[156:159], v[200:203], v[44:47]
	v_mfma_f32_16x16x32_bf16 v[40:43], v[164:167], v[200:203], v[40:43]
	v_mfma_f32_16x16x32_bf16 v[28:31], v[156:159], v[208:211], v[28:31]
	v_mfma_f32_16x16x32_bf16 v[24:27], v[164:167], v[208:211], v[24:27]
	v_mfma_f32_16x16x32_bf16 v[12:15], v[156:159], v[216:219], v[12:15]
	v_mfma_f32_16x16x32_bf16 v[8:11], v[164:167], v[216:219], v[8:11]
	v_mfma_f32_16x16x32_bf16 v[60:63], v[160:163], v[196:199], v[60:63]
	v_mfma_f32_16x16x32_bf16 v[56:59], v[168:171], v[196:199], v[56:59]
	v_mfma_f32_16x16x32_bf16 v[44:47], v[160:163], v[204:207], v[44:47]
	v_mfma_f32_16x16x32_bf16 v[40:43], v[168:171], v[204:207], v[40:43]
	v_mfma_f32_16x16x32_bf16 v[28:31], v[160:163], v[212:215], v[28:31]
	v_mfma_f32_16x16x32_bf16 v[24:27], v[168:171], v[212:215], v[24:27]
	v_mfma_f32_16x16x32_bf16 v[12:15], v[160:163], v[220:223], v[12:15]
	v_mfma_f32_16x16x32_bf16 v[8:11], v[168:171], v[220:223], v[8:11]
	s_setprio 0
	s_setprio 3
	v_mfma_f32_16x16x32_bf16 v[52:55], v[172:175], v[192:195], v[52:55]
	v_mfma_f32_16x16x32_bf16 v[48:51], v[180:183], v[192:195], v[48:51]
	v_mfma_f32_16x16x32_bf16 v[36:39], v[172:175], v[200:203], v[36:39]
	v_mfma_f32_16x16x32_bf16 v[32:35], v[180:183], v[200:203], v[32:35]
	v_mfma_f32_16x16x32_bf16 v[20:23], v[172:175], v[208:211], v[20:23]
	v_mfma_f32_16x16x32_bf16 v[16:19], v[180:183], v[208:211], v[16:19]
	v_mfma_f32_16x16x32_bf16 v[4:7], v[172:175], v[216:219], v[4:7]
	v_mfma_f32_16x16x32_bf16 v[0:3], v[180:183], v[216:219], v[0:3]
	v_mfma_f32_16x16x32_bf16 v[52:55], v[176:179], v[196:199], v[52:55]
	v_mfma_f32_16x16x32_bf16 v[48:51], v[188:191], v[196:199], v[48:51]
	v_mfma_f32_16x16x32_bf16 v[36:39], v[176:179], v[204:207], v[36:39]
	v_mfma_f32_16x16x32_bf16 v[32:35], v[188:191], v[204:207], v[32:35]
	v_mfma_f32_16x16x32_bf16 v[20:23], v[176:179], v[212:215], v[20:23]
	v_mfma_f32_16x16x32_bf16 v[16:19], v[188:191], v[212:215], v[16:19]
	v_mfma_f32_16x16x32_bf16 v[4:7], v[176:179], v[220:223], v[4:7]
	v_mfma_f32_16x16x32_bf16 v[0:3], v[188:191], v[220:223], v[0:3]
	s_setprio 0
	s_barrier
	s_add_i32 s48, s48, 2
	s_add_u32 s28, s28, 0x100
	s_addc_u32 s29, s29, 0
	s_cmpk_gt_u32 s48, 0x55
	s_cbranch_scc0 .LBB0_842
	s_branch .Lpeel_exit_3
.LBB0_842:
	ds_read_b128 v[156:159], v151
	ds_read_b128 v[160:163], v151 offset:1024
	ds_read_b128 v[164:167], v151 offset:2048
	ds_read_b128 v[168:171], v151 offset:3072
	ds_read_b128 v[172:175], v152
	ds_read_b128 v[176:179], v152 offset:1024
	ds_read_b128 v[180:183], v152 offset:2048
	ds_read_b128 v[188:191], v152 offset:3072
	s_add_u32 s30, s26, s28
	s_addc_u32 s31, s27, s29
	s_add_u32 s34, s30, 0x100
	s_addc_u32 s35, s31, 0
	s_add_u32 s30, s46, s28
	s_addc_u32 s31, s47, s29
	s_cmpk_eq_i32 s28, 0x2b00
	s_cselect_b32 s31, s25, s31
	s_cselect_b32 s30, s24, s30
	s_cselect_b32 s35, s7, s35
	s_cselect_b32 s34, s6, s34
	v_lshl_add_u64 v[184:185], v[144:145], 0, s[28:29]
	v_lshl_add_u64 v[224:225], v[184:185], 0, s[18:19]
	s_add_i32 m0, s3, 0x8000
	ds_read_b128 v[192:195], v153
	ds_read_b128 v[196:199], v153 offset:1024
	ds_read_b128 v[200:203], v153 offset:2048
	ds_read_b128 v[204:207], v153 offset:3072
	ds_read_b128 v[208:211], v153 offset:4096
	ds_read_b128 v[212:215], v153 offset:5120
	ds_read_b128 v[216:219], v153 offset:6144
	ds_read_b128 v[220:223], v153 offset:7168
	global_load_lds_dwordx4 v[224:225], off
	v_lshl_add_u64 v[224:225], v[146:147], 0, s[28:29]
	v_lshl_add_u64 v[226:227], v[224:225], 0, s[18:19]
	s_add_i32 m0, s3, 0xa000
	v_lshl_add_u64 v[184:185], v[184:185], 0, s[20:21]
	global_load_lds_dwordx4 v[226:227], off
	s_add_i32 m0, s3, 0xc000
	s_nop 0
	global_load_lds_dwordx4 v[184:185], off
	v_lshl_add_u64 v[184:185], v[224:225], 0, s[20:21]
	s_add_i32 m0, s3, 0xe000
	s_nop 0
	global_load_lds_dwordx4 v[184:185], off
	s_waitcnt vmcnt(8)
	s_waitcnt lgkmcnt(0)
	s_setprio 3
	s_barrier
; #define PG8_STAGE(bufoff, gbase, voff) do { _Pragma("unroll") for (int _i = 0; _i < 2; ++_i) \
;         __builtin_amdgcn_global_load_lds((const unsigned*)((const char*)(gbase) + (voff)[_i]), (LAS unsigned*)(lds + (bufoff) + ldsw + _i * 8192), 16, 0, 0); } while (0)
; #define PG8_LDA(dst, b, h) do { _Pragma("unroll") for (int m = 0; m < 4; ++m) _Pragma("unroll") for (int k = 0; k < 2; ++k) dst[m][k] = *(const LAS bf16x8*)(lds + PG8_SA(b, h) + aoff + m * 2048 + k * 1024); } while (0)
; #define PG8_MMA(ai, bj, At, Bt) do { __builtin_amdgcn_s_setprio(3); _Pragma("unroll") for (int m = 0; m < 4; ++m) _Pragma("unroll") for (int n = 0; n < 2; ++n) _Pragma("unroll") for (int k = 0; k < 2; ++k) \
;         acc[ai][bj][m][n] = __builtin_amdgcn_mfma_f32_16x16x32_bf16(Bt[n][k], At[m][k], acc[ai][bj][m][n], 0, 0, 0); __builtin_amdgcn_s_setprio(0); } while (0)
; #define PG8_WAIT_V(n) asm volatile("s_waitcnt vmcnt(" #n ")" ::: "memory")
; #define PG8_WAIT_L(n) asm volatile("s_waitcnt lgkmcnt(" #n ")" ::: "memory")
; #define PG8_BAR __builtin_amdgcn_s_barrier()
; #define PG8_SCHED __builtin_amdgcn_sched_barrier(0)
; template <class Epi, class Sched>
; __device__ __forceinline__ void gemm_phase(LAS unsigned char* lds, const Gemm g, const Sched& S, const Epi& E, int tid_in) {
;     ...
;             PG8_WAIT_V(8); PG8_WAIT_L(0); PG8_BAR; PG8_MMA(0, 0, At, B0); PG8_MMA(0, 1, At, B1); PG8_BAR; PG8_SCHED;
;             PG8_LDA(At, 0, 1); PG8_STAGE(PG8_SB(0, 0), b2, voffB); PG8_STAGE(PG8_SB(0, 1), b2 + hstep, voffB);
;             PG8_WAIT_V(6); PG8_WAIT_L(0); PG8_BAR; PG8_MMA(1, 0, At, B0); PG8_MMA(1, 1, At, B1); PG8_BAR; PG8_SCHED;
	v_mfma_f32_16x16x32_bf16 v[124:127], v[156:159], v[192:195], v[124:127]
	v_mfma_f32_16x16x32_bf16 v[120:123], v[164:167], v[192:195], v[120:123]
	v_mfma_f32_16x16x32_bf16 v[108:111], v[156:159], v[200:203], v[108:111]
	v_mfma_f32_16x16x32_bf16 v[104:107], v[164:167], v[200:203], v[104:107]
	v_mfma_f32_16x16x32_bf16 v[92:95], v[156:159], v[208:211], v[92:95]
	v_mfma_f32_16x16x32_bf16 v[88:91], v[164:167], v[208:211], v[88:91]
	v_mfma_f32_16x16x32_bf16 v[76:79], v[156:159], v[216:219], v[76:79]
	v_mfma_f32_16x16x32_bf16 v[72:75], v[164:167], v[216:219], v[72:75]
	v_mfma_f32_16x16x32_bf16 v[124:127], v[160:163], v[196:199], v[124:127]
	v_mfma_f32_16x16x32_bf16 v[120:123], v[168:171], v[196:199], v[120:123]
	v_mfma_f32_16x16x32_bf16 v[108:111], v[160:163], v[204:207], v[108:111]
	v_mfma_f32_16x16x32_bf16 v[104:107], v[168:171], v[204:207], v[104:107]
	v_mfma_f32_16x16x32_bf16 v[92:95], v[160:163], v[212:215], v[92:95]
	v_mfma_f32_16x16x32_bf16 v[88:91], v[168:171], v[212:215], v[88:91]
	v_mfma_f32_16x16x32_bf16 v[76:79], v[160:163], v[220:223], v[76:79]
	v_mfma_f32_16x16x32_bf16 v[72:75], v[168:171], v[220:223], v[72:75]
	s_setprio 0
	s_setprio 3
	v_mfma_f32_16x16x32_bf16 v[116:119], v[172:175], v[192:195], v[116:119]
	v_mfma_f32_16x16x32_bf16 v[112:115], v[180:183], v[192:195], v[112:115]
	v_mfma_f32_16x16x32_bf16 v[100:103], v[172:175], v[200:203], v[100:103]
	v_mfma_f32_16x16x32_bf16 v[96:99], v[180:183], v[200:203], v[96:99]
	v_mfma_f32_16x16x32_bf16 v[84:87], v[172:175], v[208:211], v[84:87]
	v_mfma_f32_16x16x32_bf16 v[80:83], v[180:183], v[208:211], v[80:83]
	v_mfma_f32_16x16x32_bf16 v[68:71], v[172:175], v[216:219], v[68:71]
	v_mfma_f32_16x16x32_bf16 v[64:67], v[180:183], v[216:219], v[64:67]
	v_mfma_f32_16x16x32_bf16 v[116:119], v[176:179], v[196:199], v[116:119]
	v_mfma_f32_16x16x32_bf16 v[112:115], v[188:191], v[196:199], v[112:115]
	v_mfma_f32_16x16x32_bf16 v[100:103], v[176:179], v[204:207], v[100:103]
	v_mfma_f32_16x16x32_bf16 v[96:99], v[188:191], v[204:207], v[96:99]
	v_mfma_f32_16x16x32_bf16 v[84:87], v[176:179], v[212:215], v[84:87]
	v_mfma_f32_16x16x32_bf16 v[80:83], v[188:191], v[212:215], v[80:83]
	v_mfma_f32_16x16x32_bf16 v[68:71], v[176:179], v[220:223], v[68:71]
	v_mfma_f32_16x16x32_bf16 v[64:67], v[188:191], v[220:223], v[64:67]
	s_setprio 0
	s_barrier
	s_add_i32 s49, s40, s2
	v_lshl_add_u64 v[184:185], s[30:31], 0, v[130:131]
	s_mov_b32 m0, s49
	ds_read_b128 v[192:195], v153 offset:16384
	ds_read_b128 v[196:199], v153 offset:17408
	ds_read_b128 v[200:203], v153 offset:18432
	ds_read_b128 v[204:207], v153 offset:19456
	ds_read_b128 v[208:211], v153 offset:20480
	ds_read_b128 v[212:215], v153 offset:21504
	ds_read_b128 v[216:219], v153 offset:22528
	ds_read_b128 v[220:223], v153 offset:23552
	global_load_lds_dwordx4 v[184:185], off
	s_add_i32 m0, s49, 0x2000
	s_add_u32 s68, s30, 0x160000
	v_lshl_add_u64 v[224:225], s[30:31], 0, v[134:135]
	s_addc_u32 s69, s31, 0
	s_add_i32 s49, s41, s2
	global_load_lds_dwordx4 v[224:225], off
	v_lshl_add_u64 v[226:227], s[68:69], 0, v[130:131]
	s_mov_b32 m0, s49
	s_nop 0
	global_load_lds_dwordx4 v[226:227], off
	v_lshl_add_u64 v[226:227], s[68:69], 0, v[134:135]
	s_add_i32 m0, s49, 0x2000
	s_nop 0
	global_load_lds_dwordx4 v[226:227], off
	s_waitcnt vmcnt(6)
	s_waitcnt lgkmcnt(0)
	s_setprio 3
	s_barrier
	v_mfma_f32_16x16x32_bf16 v[60:63], v[156:159], v[192:195], v[60:63]
	v_mfma_f32_16x16x32_bf16 v[56:59], v[164:167], v[192:195], v[56:59]
	v_mfma_f32_16x16x32_bf16 v[44:47], v[156:159], v[200:203], v[44:47]
	v_mfma_f32_16x16x32_bf16 v[40:43], v[164:167], v[200:203], v[40:43]
	v_mfma_f32_16x16x32_bf16 v[28:31], v[156:159], v[208:211], v[28:31]
	v_mfma_f32_16x16x32_bf16 v[24:27], v[164:167], v[208:211], v[24:27]
	v_mfma_f32_16x16x32_bf16 v[12:15], v[156:159], v[216:219], v[12:15]
	v_mfma_f32_16x16x32_bf16 v[8:11], v[164:167], v[216:219], v[8:11]
	v_mfma_f32_16x16x32_bf16 v[60:63], v[160:163], v[196:199], v[60:63]
	v_mfma_f32_16x16x32_bf16 v[56:59], v[168:171], v[196:199], v[56:59]
	v_mfma_f32_16x16x32_bf16 v[44:47], v[160:163], v[204:207], v[44:47]
	v_mfma_f32_16x16x32_bf16 v[40:43], v[168:171], v[204:207], v[40:43]
	v_mfma_f32_16x16x32_bf16 v[28:31], v[160:163], v[212:215], v[28:31]
	v_mfma_f32_16x16x32_bf16 v[24:27], v[168:171], v[212:215], v[24:27]
	v_mfma_f32_16x16x32_bf16 v[12:15], v[160:163], v[220:223], v[12:15]
	v_mfma_f32_16x16x32_bf16 v[8:11], v[168:171], v[220:223], v[8:11]
	s_setprio 0
	s_setprio 3
	v_mfma_f32_16x16x32_bf16 v[52:55], v[172:175], v[192:195], v[52:55]
	v_mfma_f32_16x16x32_bf16 v[48:51], v[180:183], v[192:195], v[48:51]
	v_mfma_f32_16x16x32_bf16 v[36:39], v[172:175], v[200:203], v[36:39]
	v_mfma_f32_16x16x32_bf16 v[32:35], v[180:183], v[200:203], v[32:35]
	v_mfma_f32_16x16x32_bf16 v[20:23], v[172:175], v[208:211], v[20:23]
	v_mfma_f32_16x16x32_bf16 v[16:19], v[180:183], v[208:211], v[16:19]
	v_mfma_f32_16x16x32_bf16 v[4:7], v[172:175], v[216:219], v[4:7]
	v_mfma_f32_16x16x32_bf16 v[0:3], v[180:183], v[216:219], v[0:3]
	v_mfma_f32_16x16x32_bf16 v[52:55], v[176:179], v[196:199], v[52:55]
	v_mfma_f32_16x16x32_bf16 v[48:51], v[188:191], v[196:199], v[48:51]
	v_mfma_f32_16x16x32_bf16 v[36:39], v[176:179], v[204:207], v[36:39]
	v_mfma_f32_16x16x32_bf16 v[32:35], v[188:191], v[204:207], v[32:35]
	v_mfma_f32_16x16x32_bf16 v[20:23], v[176:179], v[212:215], v[20:23]
	v_mfma_f32_16x16x32_bf16 v[16:19], v[188:191], v[212:215], v[16:19]
	v_mfma_f32_16x16x32_bf16 v[4:7], v[176:179], v[220:223], v[4:7]
	v_mfma_f32_16x16x32_bf16 v[0:3], v[188:191], v[220:223], v[0:3]
	s_setprio 0
	s_barrier
; #define PG8_STAGE(bufoff, gbase, voff) do { _Pragma("unroll") for (int _i = 0; _i < 2; ++_i) \
;         __builtin_amdgcn_global_load_lds((const unsigned*)((const char*)(gbase) + (voff)[_i]), (LAS unsigned*)(lds + (bufoff) + ldsw + _i * 8192), 16, 0, 0); } while (0)
; #define PG8_LDA(dst, b, h) do { _Pragma("unroll") for (int m = 0; m < 4; ++m) _Pragma("unroll") for (int k = 0; k < 2; ++k) dst[m][k] = *(const LAS bf16x8*)(lds + PG8_SA(b, h) + aoff + m * 2048 + k * 1024); } while (0)
; #define PG8_LDB(dst, b, h) do { _Pragma("unroll") for (int n = 0; n < 2; ++n) _Pragma("unroll") for (int k = 0; k < 2; ++k) dst[n][k] = *(const LAS bf16x8*)(lds + PG8_SB(b, h) + boff + n * 2048 + k * 1024); } while (0)
; #define PG8_MMA(ai, bj, At, Bt) do { __builtin_amdgcn_s_setprio(3); _Pragma("unroll") for (int m = 0; m < 4; ++m) _Pragma("unroll") for (int n = 0; n < 2; ++n) _Pragma("unroll") for (int k = 0; k < 2; ++k) \
;         acc[ai][bj][m][n] = __builtin_amdgcn_mfma_f32_16x16x32_bf16(Bt[n][k], At[m][k], acc[ai][bj][m][n], 0, 0, 0); __builtin_amdgcn_s_setprio(0); } while (0)
; #define PG8_WAIT_V(n) asm volatile("s_waitcnt vmcnt(" #n ")" ::: "memory")
; #define PG8_WAIT_L(n) asm volatile("s_waitcnt lgkmcnt(" #n ")" ::: "memory")
; #define PG8_BAR __builtin_amdgcn_s_barrier()
; #define PG8_SCHED __builtin_amdgcn_sched_barrier(0)
; template <class Epi, class Sched>
; __device__ __forceinline__ void gemm_phase(LAS unsigned char* lds, const Gemm g, const Sched& S, const Epi& E, int tid_in) {
;     ...
;             PG8_LDB(B0, 1, 0); PG8_LDB(B1, 1, 1); PG8_SCHED; PG8_LDA(At, 1, 0); PG8_STAGE(PG8_SA(0, 0), a2, voffA); PG8_STAGE(PG8_SA(0, 1), a2 + hstep, voffA);
;             PG8_WAIT_V(8); PG8_WAIT_L(0); PG8_BAR; PG8_MMA(0, 0, At, B0); PG8_MMA(0, 1, At, B1); PG8_BAR; PG8_SCHED;
	s_add_i32 s49, 0, 0x18000
	v_add_u32_e32 v155, s49, v149
	s_add_i32 s51, 0, 0x1c000
	ds_read_b128 v[156:159], v155
	ds_read_b128 v[160:163], v155 offset:1024
	ds_read_b128 v[164:167], v155 offset:2048
	ds_read_b128 v[168:171], v155 offset:3072
	v_add_u32_e32 v155, s51, v149
	ds_read_b128 v[172:175], v155
	ds_read_b128 v[176:179], v155 offset:1024
	ds_read_b128 v[180:183], v155 offset:2048
	ds_read_b128 v[188:191], v155 offset:3072
	s_mov_b32 m0, s3
	v_lshl_add_u64 v[226:227], s[34:35], 0, v[128:129]
	ds_read_b128 v[192:195], v153 offset:32768
	ds_read_b128 v[196:199], v153 offset:33792
	ds_read_b128 v[200:203], v153 offset:34816
	ds_read_b128 v[204:207], v153 offset:35840
	ds_read_b128 v[208:211], v153 offset:36864
	ds_read_b128 v[212:215], v153 offset:37888
	ds_read_b128 v[216:219], v153 offset:38912
	ds_read_b128 v[220:223], v153 offset:39936
	global_load_lds_dwordx4 v[226:227], off
	v_lshl_add_u64 v[226:227], s[34:35], 0, v[132:133]
	s_add_u32 s34, s34, 0x160000
	s_mov_b32 m0, s36
	s_addc_u32 s35, s35, 0
	global_load_lds_dwordx4 v[226:227], off
	v_lshl_add_u64 v[226:227], s[34:35], 0, v[128:129]
	s_mov_b32 m0, s37
	s_nop 0
	global_load_lds_dwordx4 v[226:227], off
	v_lshl_add_u64 v[226:227], s[34:35], 0, v[132:133]
	s_mov_b32 m0, s38
	s_nop 0
	global_load_lds_dwordx4 v[226:227], off
	s_waitcnt vmcnt(8)
	s_waitcnt lgkmcnt(0)
	s_setprio 3
	s_barrier
	v_mfma_f32_16x16x32_bf16 v[124:127], v[156:159], v[192:195], v[124:127]
	v_mfma_f32_16x16x32_bf16 v[120:123], v[164:167], v[192:195], v[120:123]
	v_mfma_f32_16x16x32_bf16 v[108:111], v[156:159], v[200:203], v[108:111]
	v_mfma_f32_16x16x32_bf16 v[104:107], v[164:167], v[200:203], v[104:107]
	v_mfma_f32_16x16x32_bf16 v[92:95], v[156:159], v[208:211], v[92:95]
	v_mfma_f32_16x16x32_bf16 v[88:91], v[164:167], v[208:211], v[88:91]
	v_mfma_f32_16x16x32_bf16 v[76:79], v[156:159], v[216:219], v[76:79]
	v_mfma_f32_16x16x32_bf16 v[72:75], v[164:167], v[216:219], v[72:75]
	v_mfma_f32_16x16x32_bf16 v[124:127], v[160:163], v[196:199], v[124:127]
	v_mfma_f32_16x16x32_bf16 v[120:123], v[168:171], v[196:199], v[120:123]
	v_mfma_f32_16x16x32_bf16 v[108:111], v[160:163], v[204:207], v[108:111]
	v_mfma_f32_16x16x32_bf16 v[104:107], v[168:171], v[204:207], v[104:107]
	v_mfma_f32_16x16x32_bf16 v[92:95], v[160:163], v[212:215], v[92:95]
	v_mfma_f32_16x16x32_bf16 v[88:91], v[168:171], v[212:215], v[88:91]
	v_mfma_f32_16x16x32_bf16 v[76:79], v[160:163], v[220:223], v[76:79]
	v_mfma_f32_16x16x32_bf16 v[72:75], v[168:171], v[220:223], v[72:75]
	s_setprio 0
	s_setprio 3
	v_mfma_f32_16x16x32_bf16 v[116:119], v[172:175], v[192:195], v[116:119]
	v_mfma_f32_16x16x32_bf16 v[112:115], v[180:183], v[192:195], v[112:115]
	v_mfma_f32_16x16x32_bf16 v[100:103], v[172:175], v[200:203], v[100:103]
	v_mfma_f32_16x16x32_bf16 v[96:99], v[180:183], v[200:203], v[96:99]
	v_mfma_f32_16x16x32_bf16 v[84:87], v[172:175], v[208:211], v[84:87]
	v_mfma_f32_16x16x32_bf16 v[80:83], v[180:183], v[208:211], v[80:83]
	v_mfma_f32_16x16x32_bf16 v[68:71], v[172:175], v[216:219], v[68:71]
	v_mfma_f32_16x16x32_bf16 v[64:67], v[180:183], v[216:219], v[64:67]
	v_mfma_f32_16x16x32_bf16 v[116:119], v[176:179], v[196:199], v[116:119]
	v_mfma_f32_16x16x32_bf16 v[112:115], v[188:191], v[196:199], v[112:115]
	v_mfma_f32_16x16x32_bf16 v[100:103], v[176:179], v[204:207], v[100:103]
	v_mfma_f32_16x16x32_bf16 v[96:99], v[188:191], v[204:207], v[96:99]
	v_mfma_f32_16x16x32_bf16 v[84:87], v[176:179], v[212:215], v[84:87]
	v_mfma_f32_16x16x32_bf16 v[80:83], v[188:191], v[212:215], v[80:83]
	v_mfma_f32_16x16x32_bf16 v[68:71], v[176:179], v[220:223], v[68:71]
	v_mfma_f32_16x16x32_bf16 v[64:67], v[188:191], v[220:223], v[64:67]
	s_setprio 0
	s_barrier
; #define PG8_STAGE(bufoff, gbase, voff) do { _Pragma("unroll") for (int _i = 0; _i < 2; ++_i) \
;         __builtin_amdgcn_global_load_lds((const unsigned*)((const char*)(gbase) + (voff)[_i]), (LAS unsigned*)(lds + (bufoff) + ldsw + _i * 8192), 16, 0, 0); } while (0)
; #define PG8_LDA(dst, b, h) do { _Pragma("unroll") for (int m = 0; m < 4; ++m) _Pragma("unroll") for (int k = 0; k < 2; ++k) dst[m][k] = *(const LAS bf16x8*)(lds + PG8_SA(b, h) + aoff + m * 2048 + k * 1024); } while (0)
; #define PG8_MMA(ai, bj, At, Bt) do { __builtin_amdgcn_s_setprio(3); _Pragma("unroll") for (int m = 0; m < 4; ++m) _Pragma("unroll") for (int n = 0; n < 2; ++n) _Pragma("unroll") for (int k = 0; k < 2; ++k) \
;         acc[ai][bj][m][n] = __builtin_amdgcn_mfma_f32_16x16x32_bf16(Bt[n][k], At[m][k], acc[ai][bj][m][n], 0, 0, 0); __builtin_amdgcn_s_setprio(0); } while (0)
; #define PG8_WAIT_V(n) asm volatile("s_waitcnt vmcnt(" #n ")" ::: "memory")
; #define PG8_WAIT_L(n) asm volatile("s_waitcnt lgkmcnt(" #n ")" ::: "memory")
; #define PG8_BAR __builtin_amdgcn_s_barrier()
; #define PG8_SCHED __builtin_amdgcn_sched_barrier(0)
; template <class Epi, class Sched>
; __device__ __forceinline__ void gemm_phase(LAS unsigned char* lds, const Gemm g, const Sched& S, const Epi& E, int tid_in) {
;     ...
;             PG8_LDA(At, 1, 1); PG8_STAGE(PG8_SB(1, 0), b3, voffB); PG8_STAGE(PG8_SB(1, 1), b3 + hstep, voffB);
;             PG8_WAIT_V(6); PG8_WAIT_L(0); PG8_BAR; PG8_MMA(1, 0, At, B0); PG8_MMA(1, 1, At, B1); PG8_BAR; PG8_SCHED;
;         }
	s_add_i32 s34, s49, s2
	v_lshl_add_u64 v[184:185], v[184:185], 0, s[18:19]
	s_mov_b32 m0, s34
	ds_read_b128 v[192:195], v153 offset:49152
	ds_read_b128 v[196:199], v153 offset:50176
	ds_read_b128 v[200:203], v153 offset:51200
	ds_read_b128 v[204:207], v153 offset:52224
	ds_read_b128 v[208:211], v153 offset:53248
	ds_read_b128 v[212:215], v153 offset:54272
	ds_read_b128 v[216:219], v153 offset:55296
	ds_read_b128 v[220:223], v153 offset:56320
	global_load_lds_dwordx4 v[184:185], off
	s_add_i32 m0, s34, 0x2000
	s_add_u32 s30, s30, 0x160080
	v_lshl_add_u64 v[184:185], v[224:225], 0, s[18:19]
	s_addc_u32 s31, s31, 0
	s_add_i32 s34, s51, s2
	global_load_lds_dwordx4 v[184:185], off
	v_lshl_add_u64 v[184:185], s[30:31], 0, v[130:131]
	s_mov_b32 m0, s34
	s_nop 0
	global_load_lds_dwordx4 v[184:185], off
	v_lshl_add_u64 v[184:185], s[30:31], 0, v[134:135]
	s_add_i32 m0, s34, 0x2000
	s_nop 0
	global_load_lds_dwordx4 v[184:185], off
	s_waitcnt vmcnt(6)
	s_waitcnt lgkmcnt(0)
	s_setprio 3
	s_barrier
	v_mfma_f32_16x16x32_bf16 v[60:63], v[156:159], v[192:195], v[60:63]
	v_mfma_f32_16x16x32_bf16 v[56:59], v[164:167], v[192:195], v[56:59]
	v_mfma_f32_16x16x32_bf16 v[44:47], v[156:159], v[200:203], v[44:47]
	v_mfma_f32_16x16x32_bf16 v[40:43], v[164:167], v[200:203], v[40:43]
	v_mfma_f32_16x16x32_bf16 v[28:31], v[156:159], v[208:211], v[28:31]
	v_mfma_f32_16x16x32_bf16 v[24:27], v[164:167], v[208:211], v[24:27]
	v_mfma_f32_16x16x32_bf16 v[12:15], v[156:159], v[216:219], v[12:15]
	v_mfma_f32_16x16x32_bf16 v[8:11], v[164:167], v[216:219], v[8:11]
	v_mfma_f32_16x16x32_bf16 v[60:63], v[160:163], v[196:199], v[60:63]
	v_mfma_f32_16x16x32_bf16 v[56:59], v[168:171], v[196:199], v[56:59]
	v_mfma_f32_16x16x32_bf16 v[44:47], v[160:163], v[204:207], v[44:47]
	v_mfma_f32_16x16x32_bf16 v[40:43], v[168:171], v[204:207], v[40:43]
	v_mfma_f32_16x16x32_bf16 v[28:31], v[160:163], v[212:215], v[28:31]
	v_mfma_f32_16x16x32_bf16 v[24:27], v[168:171], v[212:215], v[24:27]
	v_mfma_f32_16x16x32_bf16 v[12:15], v[160:163], v[220:223], v[12:15]
	v_mfma_f32_16x16x32_bf16 v[8:11], v[168:171], v[220:223], v[8:11]
	s_setprio 0
	s_setprio 3
	v_mfma_f32_16x16x32_bf16 v[52:55], v[172:175], v[192:195], v[52:55]
	v_mfma_f32_16x16x32_bf16 v[48:51], v[180:183], v[192:195], v[48:51]
	v_mfma_f32_16x16x32_bf16 v[36:39], v[172:175], v[200:203], v[36:39]
	v_mfma_f32_16x16x32_bf16 v[32:35], v[180:183], v[200:203], v[32:35]
	v_mfma_f32_16x16x32_bf16 v[20:23], v[172:175], v[208:211], v[20:23]
	v_mfma_f32_16x16x32_bf16 v[16:19], v[180:183], v[208:211], v[16:19]
	v_mfma_f32_16x16x32_bf16 v[4:7], v[172:175], v[216:219], v[4:7]
	v_mfma_f32_16x16x32_bf16 v[0:3], v[180:183], v[216:219], v[0:3]
	v_mfma_f32_16x16x32_bf16 v[52:55], v[176:179], v[196:199], v[52:55]
	v_mfma_f32_16x16x32_bf16 v[48:51], v[188:191], v[196:199], v[48:51]
	v_mfma_f32_16x16x32_bf16 v[36:39], v[176:179], v[204:207], v[36:39]
	v_mfma_f32_16x16x32_bf16 v[32:35], v[188:191], v[204:207], v[32:35]
	v_mfma_f32_16x16x32_bf16 v[20:23], v[176:179], v[212:215], v[20:23]
	v_mfma_f32_16x16x32_bf16 v[16:19], v[188:191], v[212:215], v[16:19]
	v_mfma_f32_16x16x32_bf16 v[4:7], v[176:179], v[220:223], v[4:7]
	v_mfma_f32_16x16x32_bf16 v[0:3], v[188:191], v[220:223], v[0:3]
	s_setprio 0
	s_barrier
	s_add_i32 s48, s48, 2
	s_add_u32 s28, s28, 0x100
	s_addc_u32 s29, s29, 0
	s_cmpk_gt_u32 s48, 0x55
	s_cbranch_scc0 .LBB0_842

;     __device__ bool next(int i, Unit& u) const { if (!b.next(i >> 1, u)) return false; u.half = i & 1; u.koff = (i & 1) * kbytes; return true; }
; #define PG8_STAGE(bufoff, gbase, voff) do { _Pragma("unroll") for (int _i = 0; _i < 2; ++_i) \
;         __builtin_amdgcn_global_load_lds((const unsigned*)((const char*)(gbase) + (voff)[_i]), (LAS unsigned*)(lds + (bufoff) + ldsw + _i * 8192), 16, 0, 0); } while (0)
; #define PG8_LDA(dst, b, h) do { _Pragma("unroll") for (int m = 0; m < 4; ++m) _Pragma("unroll") for (int k = 0; k < 2; ++k) dst[m][k] = *(const LAS bf16x8*)(lds + PG8_SA(b, h) + aoff + m * 2048 + k * 1024); } while (0)
; #define PG8_LDB(dst, b, h) do { _Pragma("unroll") for (int n = 0; n < 2; ++n) _Pragma("unroll") for (int k = 0; k < 2; ++k) dst[n][k] = *(const LAS bf16x8*)(lds + PG8_SB(b, h) + boff + n * 2048 + k * 1024); } while (0)
; #define PG8_WAIT_V(n) asm volatile("s_waitcnt vmcnt(" #n ")" ::: "memory")
; #define PG8_WAIT_L(n) asm volatile("s_waitcnt lgkmcnt(" #n ")" ::: "memory")
; #define PG8_BAR __builtin_amdgcn_s_barrier()
; #define PG8_SCHED __builtin_amdgcn_sched_barrier(0)
; template <class Epi, class Sched>
; __device__ __forceinline__ void gemm_phase(LAS unsigned char* lds, const Gemm g, const Sched& S, const Epi& E, int tid_in) {
;     ...
;         const bool has_next = S.next(ui + 1, nxt);
;         const char* nA = has_next ? (const char*)g.A + (size_t)nxt.pm * tstep + nxt.koff : cA; const char* nB = has_next ? (const char*)g.Bt + (size_t)nxt.pn * tstep + nxt.koff : cB;
;         for (int t = 0; t < nt; t += 2) {
;             const bool last = (t == nt - 2);
;             const char* a1 = cA + (size_t)(t + 1) * kstep;
;             const char* a2 = last ? nA : cA + (size_t)(t + 2) * kstep; const char* b2 = last ? nB : cB + (size_t)(t + 2) * kstep;
;             const char* a3 = a2 + kstep; const char* b3 = b2 + kstep;
;             PG8_LDB(B0, 0, 0); PG8_LDB(B1, 0, 1); PG8_SCHED; PG8_LDA(At, 0, 0); PG8_STAGE(PG8_SA(1, 0), a1, voffA); PG8_STAGE(PG8_SA(1, 1), a1 + hstep, voffA);
;             PG8_WAIT_V(8); PG8_WAIT_L(0); PG8_BAR; PG8_MMA(0, 0, At, B0); PG8_MMA(0, 1, At, B1); PG8_BAR; PG8_SCHED;
;             PG8_LDA(At, 0, 1); PG8_STAGE(PG8_SB(0, 0), b2, voffB); PG8_STAGE(PG8_SB(0, 1), b2 + hstep, voffB);
;             PG8_WAIT_V(6); PG8_WAIT_L(0); PG8_BAR; PG8_MMA(1, 0, At, B0); PG8_MMA(1, 1, At, B1); PG8_BAR; PG8_SCHED;
.LBB0_988:
	ds_read_b128 v[4:7], v143
	ds_read_b128 v[8:11], v143 offset:1024
	ds_read_b128 v[12:15], v143 offset:2048
	ds_read_b128 v[16:19], v143 offset:3072
	ds_read_b128 v[20:23], v144
	ds_read_b128 v[24:27], v144 offset:1024
	ds_read_b128 v[28:31], v144 offset:2048
	ds_read_b128 v[32:35], v144 offset:3072
	s_ashr_i32 s35, s34, 31
	s_lshl_b64 s[36:37], s[34:35], 17
	s_add_u32 s36, s3, s36
	s_addc_u32 s37, s51, s37
	s_and_b64 s[38:39], s[4:5], exec
	s_cselect_b32 s49, s37, s43
	s_cselect_b32 s48, s36, s42
	s_ashr_i32 s31, s30, 31
	s_lshl_b64 s[38:39], s[30:31], 17
	s_add_u32 s38, s62, s38
	s_addc_u32 s39, s63, s39
	s_and_b64 s[46:47], s[4:5], exec
	s_cselect_b32 s47, s39, s45
	s_cselect_b32 s46, s38, s44
	v_lshl_add_u64 v[0:1], s[42:43], 0, v[134:135]
	s_mov_b32 m0, s71
	v_lshl_add_u64 v[2:3], v[0:1], 0, s[8:9]
	ds_read_b128 v[36:39], v145
	ds_read_b128 v[40:43], v145 offset:1024
	ds_read_b128 v[44:47], v145 offset:2048
	ds_read_b128 v[48:51], v145 offset:3072
	ds_read_b128 v[52:55], v145 offset:4096
	ds_read_b128 v[56:59], v145 offset:5120
	ds_read_b128 v[60:63], v145 offset:6144
	ds_read_b128 v[64:67], v145 offset:7168
	global_load_lds_dwordx4 v[2:3], off
	v_lshl_add_u64 v[2:3], s[42:43], 0, v[130:131]
	s_add_u32 s80, s42, 0x10080
	v_lshl_add_u64 v[68:69], v[2:3], 0, s[8:9]
	s_mov_b32 m0, s72
	s_addc_u32 s81, s43, 0
	global_load_lds_dwordx4 v[68:69], off
	v_lshl_add_u64 v[68:69], s[80:81], 0, v[134:135]
	s_mov_b32 m0, s73
	s_nop 0
	global_load_lds_dwordx4 v[68:69], off
	v_lshl_add_u64 v[68:69], s[80:81], 0, v[130:131]
	s_mov_b32 m0, s74
	s_nop 0
	global_load_lds_dwordx4 v[68:69], off
	s_waitcnt vmcnt(8)
	s_waitcnt lgkmcnt(0)
	s_setprio 3
	s_barrier
	v_mfma_f32_16x16x32_bf16 v[68:71], v[4:7], v[36:39], 0
	v_mfma_f32_16x16x32_bf16 v[72:75], v[12:15], v[36:39], 0
	v_mfma_f32_16x16x32_bf16 v[76:79], v[4:7], v[44:47], 0
	v_mfma_f32_16x16x32_bf16 v[80:83], v[12:15], v[44:47], 0
	v_mfma_f32_16x16x32_bf16 v[84:87], v[4:7], v[52:55], 0
	v_mfma_f32_16x16x32_bf16 v[88:91], v[12:15], v[52:55], 0
	v_mfma_f32_16x16x32_bf16 v[92:95], v[4:7], v[60:63], 0
	v_mfma_f32_16x16x32_bf16 v[96:99], v[12:15], v[60:63], 0
	v_mfma_f32_16x16x32_bf16 v[68:71], v[8:11], v[40:43], v[68:71]
	v_mfma_f32_16x16x32_bf16 v[72:75], v[16:19], v[40:43], v[72:75]
	v_mfma_f32_16x16x32_bf16 v[76:79], v[8:11], v[48:51], v[76:79]
	v_mfma_f32_16x16x32_bf16 v[80:83], v[16:19], v[48:51], v[80:83]
	v_mfma_f32_16x16x32_bf16 v[84:87], v[8:11], v[56:59], v[84:87]
	v_mfma_f32_16x16x32_bf16 v[88:91], v[16:19], v[56:59], v[88:91]
	v_mfma_f32_16x16x32_bf16 v[92:95], v[8:11], v[64:67], v[92:95]
	v_mfma_f32_16x16x32_bf16 v[96:99], v[16:19], v[64:67], v[96:99]
	s_setprio 0
	s_setprio 3
	v_mfma_f32_16x16x32_bf16 v[100:103], v[20:23], v[36:39], 0
	v_mfma_f32_16x16x32_bf16 v[36:39], v[28:31], v[36:39], 0
	v_mfma_f32_16x16x32_bf16 v[100:103], v[24:27], v[40:43], v[100:103]
	v_mfma_f32_16x16x32_bf16 v[36:39], v[32:35], v[40:43], v[36:39]
	v_mfma_f32_16x16x32_bf16 v[40:43], v[20:23], v[44:47], 0
	v_mfma_f32_16x16x32_bf16 v[44:47], v[28:31], v[44:47], 0
	v_mfma_f32_16x16x32_bf16 v[40:43], v[24:27], v[48:51], v[40:43]
	v_mfma_f32_16x16x32_bf16 v[44:47], v[32:35], v[48:51], v[44:47]
	v_mfma_f32_16x16x32_bf16 v[48:51], v[20:23], v[52:55], 0
	v_mfma_f32_16x16x32_bf16 v[52:55], v[28:31], v[52:55], 0
	v_mfma_f32_16x16x32_bf16 v[48:51], v[24:27], v[56:59], v[48:51]
	v_mfma_f32_16x16x32_bf16 v[52:55], v[32:35], v[56:59], v[52:55]
	v_mfma_f32_16x16x32_bf16 v[56:59], v[20:23], v[60:63], 0
	v_mfma_f32_16x16x32_bf16 v[60:63], v[28:31], v[60:63], 0
	v_mfma_f32_16x16x32_bf16 v[56:59], v[24:27], v[64:67], v[56:59]
	v_mfma_f32_16x16x32_bf16 v[60:63], v[32:35], v[64:67], v[60:63]
	s_setprio 0
	s_barrier
	s_add_i32 s82, s69, s2
	v_lshl_add_u64 v[216:217], s[44:45], 0, v[132:133]
	s_add_i32 s31, s82, 0x2000
	v_lshl_add_u64 v[150:151], v[216:217], 0, s[18:19]
	s_mov_b32 m0, s82
	v_lshl_add_u64 v[218:219], s[44:45], 0, v[128:129]
	s_add_u32 s80, s44, 0x10100
	ds_read_b128 v[64:67], v145 offset:16384
	ds_read_b128 v[104:107], v145 offset:17408
	ds_read_b128 v[108:111], v145 offset:18432
	ds_read_b128 v[112:115], v145 offset:19456
	ds_read_b128 v[116:119], v145 offset:20480
	ds_read_b128 v[120:123], v145 offset:21504
	ds_read_b128 v[124:127], v145 offset:22528
	ds_read_b128 v[146:149], v145 offset:23552
	global_load_lds_dwordx4 v[150:151], off
	v_lshl_add_u64 v[150:151], v[218:219], 0, s[18:19]
	s_mov_b32 m0, s31
	s_addc_u32 s81, s45, 0
	s_add_i32 s35, s70, s2
	global_load_lds_dwordx4 v[150:151], off
	v_lshl_add_u64 v[150:151], s[80:81], 0, v[132:133]
	s_mov_b32 m0, s35
	s_nop 0
	global_load_lds_dwordx4 v[150:151], off
	v_lshl_add_u64 v[150:151], s[80:81], 0, v[128:129]
	s_add_i32 s80, s35, 0x2000
	s_mov_b32 m0, s80
	s_nop 0
	global_load_lds_dwordx4 v[150:151], off
	s_waitcnt vmcnt(6)
	s_waitcnt lgkmcnt(0)
	s_setprio 3
	s_barrier
; #define PG8_STAGE(bufoff, gbase, voff) do { _Pragma("unroll") for (int _i = 0; _i < 2; ++_i) \
;         __builtin_amdgcn_global_load_lds((const unsigned*)((const char*)(gbase) + (voff)[_i]), (LAS unsigned*)(lds + (bufoff) + ldsw + _i * 8192), 16, 0, 0); } while (0)
; #define PG8_LDA(dst, b, h) do { _Pragma("unroll") for (int m = 0; m < 4; ++m) _Pragma("unroll") for (int k = 0; k < 2; ++k) dst[m][k] = *(const LAS bf16x8*)(lds + PG8_SA(b, h) + aoff + m * 2048 + k * 1024); } while (0)
; #define PG8_LDB(dst, b, h) do { _Pragma("unroll") for (int n = 0; n < 2; ++n) _Pragma("unroll") for (int k = 0; k < 2; ++k) dst[n][k] = *(const LAS bf16x8*)(lds + PG8_SB(b, h) + boff + n * 2048 + k * 1024); } while (0)
; #define PG8_MMA(ai, bj, At, Bt) do { __builtin_amdgcn_s_setprio(3); _Pragma("unroll") for (int m = 0; m < 4; ++m) _Pragma("unroll") for (int n = 0; n < 2; ++n) _Pragma("unroll") for (int k = 0; k < 2; ++k) \
;         acc[ai][bj][m][n] = __builtin_amdgcn_mfma_f32_16x16x32_bf16(Bt[n][k], At[m][k], acc[ai][bj][m][n], 0, 0, 0); __builtin_amdgcn_s_setprio(0); } while (0)
; #define PG8_WAIT_V(n) asm volatile("s_waitcnt vmcnt(" #n ")" ::: "memory")
; #define PG8_WAIT_L(n) asm volatile("s_waitcnt lgkmcnt(" #n ")" ::: "memory")
; #define PG8_BAR __builtin_amdgcn_s_barrier()
; #define PG8_SCHED __builtin_amdgcn_sched_barrier(0)
; template <class Epi, class Sched>
; __device__ __forceinline__ void gemm_phase(LAS unsigned char* lds, const Gemm g, const Sched& S, const Epi& E, int tid_in) {
;     ...
;             PG8_WAIT_V(6); PG8_WAIT_L(0); PG8_BAR; PG8_MMA(1, 0, At, B0); PG8_MMA(1, 1, At, B1); PG8_BAR; PG8_SCHED;
;             PG8_LDB(B0, 1, 0); PG8_LDB(B1, 1, 1); PG8_SCHED; PG8_LDA(At, 1, 0); PG8_STAGE(PG8_SA(0, 0), a2, voffA); PG8_STAGE(PG8_SA(0, 1), a2 + hstep, voffA);
;             PG8_WAIT_V(8); PG8_WAIT_L(0); PG8_BAR; PG8_MMA(0, 0, At, B0); PG8_MMA(0, 1, At, B1); PG8_BAR; PG8_SCHED;
	v_mfma_f32_16x16x32_bf16 v[150:153], v[4:7], v[64:67], 0
	v_mfma_f32_16x16x32_bf16 v[158:161], v[4:7], v[108:111], 0
	v_mfma_f32_16x16x32_bf16 v[166:169], v[4:7], v[116:119], 0
	v_mfma_f32_16x16x32_bf16 v[4:7], v[4:7], v[124:127], 0
	v_mfma_f32_16x16x32_bf16 v[150:153], v[8:11], v[104:107], v[150:153]
	v_mfma_f32_16x16x32_bf16 v[158:161], v[8:11], v[112:115], v[158:161]
	v_mfma_f32_16x16x32_bf16 v[166:169], v[8:11], v[120:123], v[166:169]
	v_mfma_f32_16x16x32_bf16 v[4:7], v[8:11], v[146:149], v[4:7]
	v_mfma_f32_16x16x32_bf16 v[8:11], v[12:15], v[124:127], 0
	v_mfma_f32_16x16x32_bf16 v[154:157], v[12:15], v[64:67], 0
	v_mfma_f32_16x16x32_bf16 v[162:165], v[12:15], v[108:111], 0
	v_mfma_f32_16x16x32_bf16 v[170:173], v[12:15], v[116:119], 0
	v_mfma_f32_16x16x32_bf16 v[8:11], v[16:19], v[146:149], v[8:11]
	v_mfma_f32_16x16x32_bf16 v[154:157], v[16:19], v[104:107], v[154:157]
	v_mfma_f32_16x16x32_bf16 v[162:165], v[16:19], v[112:115], v[162:165]
	v_mfma_f32_16x16x32_bf16 v[170:173], v[16:19], v[120:123], v[170:173]
	s_setprio 0
	s_setprio 3
	v_mfma_f32_16x16x32_bf16 v[12:15], v[20:23], v[64:67], 0
	v_mfma_f32_16x16x32_bf16 v[16:19], v[28:31], v[64:67], 0
	v_mfma_f32_16x16x32_bf16 v[12:15], v[24:27], v[104:107], v[12:15]
	v_mfma_f32_16x16x32_bf16 v[16:19], v[32:35], v[104:107], v[16:19]
	v_mfma_f32_16x16x32_bf16 v[64:67], v[20:23], v[108:111], 0
	v_mfma_f32_16x16x32_bf16 v[104:107], v[28:31], v[108:111], 0
	v_mfma_f32_16x16x32_bf16 v[108:111], v[20:23], v[116:119], 0
	v_mfma_f32_16x16x32_bf16 v[20:23], v[20:23], v[124:127], 0
	v_mfma_f32_16x16x32_bf16 v[64:67], v[24:27], v[112:115], v[64:67]
	v_mfma_f32_16x16x32_bf16 v[104:107], v[32:35], v[112:115], v[104:107]
	v_mfma_f32_16x16x32_bf16 v[108:111], v[24:27], v[120:123], v[108:111]
	v_mfma_f32_16x16x32_bf16 v[112:115], v[28:31], v[116:119], 0
	v_mfma_f32_16x16x32_bf16 v[20:23], v[24:27], v[146:149], v[20:23]
	v_mfma_f32_16x16x32_bf16 v[24:27], v[28:31], v[124:127], 0
	v_mfma_f32_16x16x32_bf16 v[112:115], v[32:35], v[120:123], v[112:115]
	v_mfma_f32_16x16x32_bf16 v[24:27], v[32:35], v[146:149], v[24:27]
	s_setprio 0
	s_barrier
	s_add_i32 s83, 0, 0x18000
	s_add_i32 s87, 0, 0x1c000
	v_add_u32_e32 v224, s83, v141
	v_add_u32_e32 v225, s87, v141
	ds_read_b128 v[28:31], v224
	ds_read_b128 v[32:35], v224 offset:1024
	ds_read_b128 v[116:119], v224 offset:2048
	ds_read_b128 v[120:123], v224 offset:3072
	ds_read_b128 v[124:127], v225
	ds_read_b128 v[146:149], v225 offset:1024
	ds_read_b128 v[174:177], v225 offset:2048
	ds_read_b128 v[178:181], v225 offset:3072
	s_mov_b32 m0, s41
	v_lshl_add_u64 v[220:221], v[0:1], 0, s[18:19]
	s_add_u32 s88, s42, 0x10100
	ds_read_b128 v[182:185], v145 offset:32768
	ds_read_b128 v[188:191], v145 offset:33792
	ds_read_b128 v[192:195], v145 offset:34816
	ds_read_b128 v[196:199], v145 offset:35840
	ds_read_b128 v[200:203], v145 offset:36864
	ds_read_b128 v[204:207], v145 offset:37888
	ds_read_b128 v[208:211], v145 offset:38912
	ds_read_b128 v[212:215], v145 offset:39936
	global_load_lds_dwordx4 v[220:221], off
	v_lshl_add_u64 v[220:221], v[2:3], 0, s[18:19]
	s_mov_b32 m0, s66
	s_addc_u32 s89, s43, 0
	global_load_lds_dwordx4 v[220:221], off
	v_lshl_add_u64 v[220:221], s[88:89], 0, v[134:135]
	s_mov_b32 m0, s67
	s_nop 0
	global_load_lds_dwordx4 v[220:221], off
	v_lshl_add_u64 v[220:221], s[88:89], 0, v[130:131]
	s_mov_b32 m0, s68
	s_nop 0
	global_load_lds_dwordx4 v[220:221], off
	s_waitcnt vmcnt(8)
	s_waitcnt lgkmcnt(0)
	s_setprio 3
	s_barrier
	v_mfma_f32_16x16x32_bf16 v[68:71], v[28:31], v[182:185], v[68:71]
	v_mfma_f32_16x16x32_bf16 v[72:75], v[116:119], v[182:185], v[72:75]
	v_mfma_f32_16x16x32_bf16 v[76:79], v[28:31], v[192:195], v[76:79]
	v_mfma_f32_16x16x32_bf16 v[80:83], v[116:119], v[192:195], v[80:83]
	v_mfma_f32_16x16x32_bf16 v[84:87], v[28:31], v[200:203], v[84:87]
	v_mfma_f32_16x16x32_bf16 v[88:91], v[116:119], v[200:203], v[88:91]
	v_mfma_f32_16x16x32_bf16 v[92:95], v[28:31], v[208:211], v[92:95]
	v_mfma_f32_16x16x32_bf16 v[96:99], v[116:119], v[208:211], v[96:99]
	v_mfma_f32_16x16x32_bf16 v[68:71], v[32:35], v[188:191], v[68:71]
	v_mfma_f32_16x16x32_bf16 v[72:75], v[120:123], v[188:191], v[72:75]
	v_mfma_f32_16x16x32_bf16 v[76:79], v[32:35], v[196:199], v[76:79]
	v_mfma_f32_16x16x32_bf16 v[80:83], v[120:123], v[196:199], v[80:83]
	v_mfma_f32_16x16x32_bf16 v[84:87], v[32:35], v[204:207], v[84:87]
	v_mfma_f32_16x16x32_bf16 v[88:91], v[120:123], v[204:207], v[88:91]
	v_mfma_f32_16x16x32_bf16 v[92:95], v[32:35], v[212:215], v[92:95]
	v_mfma_f32_16x16x32_bf16 v[96:99], v[120:123], v[212:215], v[96:99]
	s_setprio 0
	s_setprio 3
	v_mfma_f32_16x16x32_bf16 v[100:103], v[124:127], v[182:185], v[100:103]
	v_mfma_f32_16x16x32_bf16 v[36:39], v[174:177], v[182:185], v[36:39]
	v_mfma_f32_16x16x32_bf16 v[40:43], v[124:127], v[192:195], v[40:43]
	v_mfma_f32_16x16x32_bf16 v[44:47], v[174:177], v[192:195], v[44:47]
	v_mfma_f32_16x16x32_bf16 v[48:51], v[124:127], v[200:203], v[48:51]
	v_mfma_f32_16x16x32_bf16 v[52:55], v[174:177], v[200:203], v[52:55]
	v_mfma_f32_16x16x32_bf16 v[56:59], v[124:127], v[208:211], v[56:59]
	v_mfma_f32_16x16x32_bf16 v[60:63], v[174:177], v[208:211], v[60:63]
	v_mfma_f32_16x16x32_bf16 v[100:103], v[146:149], v[188:191], v[100:103]
	v_mfma_f32_16x16x32_bf16 v[36:39], v[178:181], v[188:191], v[36:39]
	v_mfma_f32_16x16x32_bf16 v[40:43], v[146:149], v[196:199], v[40:43]
	v_mfma_f32_16x16x32_bf16 v[44:47], v[178:181], v[196:199], v[44:47]
	v_mfma_f32_16x16x32_bf16 v[48:51], v[146:149], v[204:207], v[48:51]
	v_mfma_f32_16x16x32_bf16 v[52:55], v[178:181], v[204:207], v[52:55]
	v_mfma_f32_16x16x32_bf16 v[56:59], v[146:149], v[212:215], v[56:59]
	v_mfma_f32_16x16x32_bf16 v[60:63], v[178:181], v[212:215], v[60:63]
	s_setprio 0
	s_barrier
; #define PG8_STAGE(bufoff, gbase, voff) do { _Pragma("unroll") for (int _i = 0; _i < 2; ++_i) \
;         __builtin_amdgcn_global_load_lds((const unsigned*)((const char*)(gbase) + (voff)[_i]), (LAS unsigned*)(lds + (bufoff) + ldsw + _i * 8192), 16, 0, 0); } while (0)
; #define PG8_LDA(dst, b, h) do { _Pragma("unroll") for (int m = 0; m < 4; ++m) _Pragma("unroll") for (int k = 0; k < 2; ++k) dst[m][k] = *(const LAS bf16x8*)(lds + PG8_SA(b, h) + aoff + m * 2048 + k * 1024); } while (0)
; #define PG8_LDB(dst, b, h) do { _Pragma("unroll") for (int n = 0; n < 2; ++n) _Pragma("unroll") for (int k = 0; k < 2; ++k) dst[n][k] = *(const LAS bf16x8*)(lds + PG8_SB(b, h) + boff + n * 2048 + k * 1024); } while (0)
; #define PG8_MMA(ai, bj, At, Bt) do { __builtin_amdgcn_s_setprio(3); _Pragma("unroll") for (int m = 0; m < 4; ++m) _Pragma("unroll") for (int n = 0; n < 2; ++n) _Pragma("unroll") for (int k = 0; k < 2; ++k) \
;         acc[ai][bj][m][n] = __builtin_amdgcn_mfma_f32_16x16x32_bf16(Bt[n][k], At[m][k], acc[ai][bj][m][n], 0, 0, 0); __builtin_amdgcn_s_setprio(0); } while (0)
; #define PG8_WAIT_V(n) asm volatile("s_waitcnt vmcnt(" #n ")" ::: "memory")
; #define PG8_WAIT_L(n) asm volatile("s_waitcnt lgkmcnt(" #n ")" ::: "memory")
; #define PG8_BAR __builtin_amdgcn_s_barrier()
; #define PG8_SCHED __builtin_amdgcn_sched_barrier(0)
; template <class Epi, class Sched>
; __device__ __forceinline__ void gemm_phase(LAS unsigned char* lds, const Gemm g, const Sched& S, const Epi& E, int tid_in) {
;     ...
;             PG8_LDB(B0, 0, 0); PG8_LDB(B1, 0, 1); PG8_SCHED; PG8_LDA(At, 0, 0); PG8_STAGE(PG8_SA(1, 0), a1, voffA); PG8_STAGE(PG8_SA(1, 1), a1 + hstep, voffA);
;             PG8_WAIT_V(8); PG8_WAIT_L(0); PG8_BAR; PG8_MMA(0, 0, At, B0); PG8_MMA(0, 1, At, B1); PG8_BAR; PG8_SCHED;
;     ...
;             PG8_LDA(At, 1, 1); PG8_STAGE(PG8_SB(1, 0), b3, voffB); PG8_STAGE(PG8_SB(1, 1), b3 + hstep, voffB);
;             PG8_WAIT_V(6); PG8_WAIT_L(0); PG8_BAR; PG8_MMA(1, 0, At, B0); PG8_MMA(1, 1, At, B1); PG8_BAR; PG8_SCHED;
	s_add_i32 s83, s83, s2
	s_add_i32 s81, s83, 0x2000
	v_lshl_add_u64 v[216:217], v[216:217], 0, s[20:21]
	s_mov_b32 m0, s83
	s_add_u32 s88, s44, 0x10180
	ds_read_b128 v[182:185], v145 offset:49152
	ds_read_b128 v[188:191], v145 offset:50176
	ds_read_b128 v[192:195], v145 offset:51200
	ds_read_b128 v[196:199], v145 offset:52224
	ds_read_b128 v[200:203], v145 offset:53248
	ds_read_b128 v[204:207], v145 offset:54272
	ds_read_b128 v[208:211], v145 offset:55296
	ds_read_b128 v[212:215], v145 offset:56320
	global_load_lds_dwordx4 v[216:217], off
	v_lshl_add_u64 v[216:217], v[218:219], 0, s[20:21]
	s_mov_b32 m0, s81
	s_addc_u32 s89, s45, 0
	s_add_i32 s44, s87, s2
	global_load_lds_dwordx4 v[216:217], off
	v_lshl_add_u64 v[216:217], s[88:89], 0, v[132:133]
	s_mov_b32 m0, s44
	s_add_i32 s45, s44, 0x2000
	global_load_lds_dwordx4 v[216:217], off
	v_lshl_add_u64 v[216:217], s[88:89], 0, v[128:129]
	s_mov_b32 m0, s45
	s_nop 0
	global_load_lds_dwordx4 v[216:217], off
	s_waitcnt vmcnt(6)
	s_waitcnt lgkmcnt(0)
	s_setprio 3
	s_barrier
	v_mfma_f32_16x16x32_bf16 v[4:7], v[28:31], v[208:211], v[4:7]
	v_mfma_f32_16x16x32_bf16 v[8:11], v[116:119], v[208:211], v[8:11]
	v_mfma_f32_16x16x32_bf16 v[150:153], v[28:31], v[182:185], v[150:153]
	v_mfma_f32_16x16x32_bf16 v[154:157], v[116:119], v[182:185], v[154:157]
	v_mfma_f32_16x16x32_bf16 v[158:161], v[28:31], v[192:195], v[158:161]
	v_mfma_f32_16x16x32_bf16 v[162:165], v[116:119], v[192:195], v[162:165]
	v_mfma_f32_16x16x32_bf16 v[166:169], v[28:31], v[200:203], v[166:169]
	v_mfma_f32_16x16x32_bf16 v[170:173], v[116:119], v[200:203], v[170:173]
	v_mfma_f32_16x16x32_bf16 v[4:7], v[32:35], v[212:215], v[4:7]
	v_mfma_f32_16x16x32_bf16 v[8:11], v[120:123], v[212:215], v[8:11]
	v_mfma_f32_16x16x32_bf16 v[150:153], v[32:35], v[188:191], v[150:153]
	v_mfma_f32_16x16x32_bf16 v[154:157], v[120:123], v[188:191], v[154:157]
	v_mfma_f32_16x16x32_bf16 v[158:161], v[32:35], v[196:199], v[158:161]
	v_mfma_f32_16x16x32_bf16 v[162:165], v[120:123], v[196:199], v[162:165]
	v_mfma_f32_16x16x32_bf16 v[166:169], v[32:35], v[204:207], v[166:169]
	v_mfma_f32_16x16x32_bf16 v[170:173], v[120:123], v[204:207], v[170:173]
	s_setprio 0
	s_setprio 3
	v_mfma_f32_16x16x32_bf16 v[12:15], v[124:127], v[182:185], v[12:15]
	v_mfma_f32_16x16x32_bf16 v[16:19], v[174:177], v[182:185], v[16:19]
	v_mfma_f32_16x16x32_bf16 v[28:31], v[124:127], v[192:195], v[64:67]
	v_mfma_f32_16x16x32_bf16 v[32:35], v[174:177], v[192:195], v[104:107]
	v_mfma_f32_16x16x32_bf16 v[64:67], v[124:127], v[200:203], v[108:111]
	v_mfma_f32_16x16x32_bf16 v[104:107], v[174:177], v[200:203], v[112:115]
	v_mfma_f32_16x16x32_bf16 v[20:23], v[124:127], v[208:211], v[20:23]
	v_mfma_f32_16x16x32_bf16 v[24:27], v[174:177], v[208:211], v[24:27]
	v_mfma_f32_16x16x32_bf16 v[12:15], v[146:149], v[188:191], v[12:15]
	v_mfma_f32_16x16x32_bf16 v[16:19], v[178:181], v[188:191], v[16:19]
	v_mfma_f32_16x16x32_bf16 v[28:31], v[146:149], v[196:199], v[28:31]
	v_mfma_f32_16x16x32_bf16 v[32:35], v[178:181], v[196:199], v[32:35]
	v_mfma_f32_16x16x32_bf16 v[64:67], v[146:149], v[204:207], v[64:67]
	v_mfma_f32_16x16x32_bf16 v[104:107], v[178:181], v[204:207], v[104:107]
	v_mfma_f32_16x16x32_bf16 v[20:23], v[146:149], v[212:215], v[20:23]
	v_mfma_f32_16x16x32_bf16 v[24:27], v[178:181], v[212:215], v[24:27]
	s_setprio 0
	s_barrier
	ds_read_b128 v[108:111], v143
	ds_read_b128 v[112:115], v143 offset:1024
	ds_read_b128 v[116:119], v143 offset:2048
	ds_read_b128 v[120:123], v143 offset:3072
	ds_read_b128 v[124:127], v144
	ds_read_b128 v[146:149], v144 offset:1024
	ds_read_b128 v[174:177], v144 offset:2048
	ds_read_b128 v[178:181], v144 offset:3072
	s_mov_b32 m0, s71
	v_lshl_add_u64 v[0:1], v[0:1], 0, s[20:21]
	s_add_u32 s42, s42, 0x10180
	ds_read_b128 v[182:185], v145
	ds_read_b128 v[188:191], v145 offset:1024
	ds_read_b128 v[192:195], v145 offset:2048
	ds_read_b128 v[196:199], v145 offset:3072
	ds_read_b128 v[200:203], v145 offset:4096
	ds_read_b128 v[204:207], v145 offset:5120
	ds_read_b128 v[208:211], v145 offset:6144
	ds_read_b128 v[212:215], v145 offset:7168
	global_load_lds_dwordx4 v[0:1], off
	v_lshl_add_u64 v[0:1], v[2:3], 0, s[20:21]
	s_mov_b32 m0, s72
	s_addc_u32 s43, s43, 0
	global_load_lds_dwordx4 v[0:1], off
	v_lshl_add_u64 v[0:1], s[42:43], 0, v[134:135]
	s_mov_b32 m0, s73
	s_nop 0
	global_load_lds_dwordx4 v[0:1], off
	v_lshl_add_u64 v[0:1], s[42:43], 0, v[130:131]
	s_mov_b32 m0, s74
	s_nop 0
	global_load_lds_dwordx4 v[0:1], off
	s_waitcnt vmcnt(8)
	s_waitcnt lgkmcnt(0)
	s_setprio 3
	s_barrier
; #define PG8_STAGE(bufoff, gbase, voff) do { _Pragma("unroll") for (int _i = 0; _i < 2; ++_i) \
;         __builtin_amdgcn_global_load_lds((const unsigned*)((const char*)(gbase) + (voff)[_i]), (LAS unsigned*)(lds + (bufoff) + ldsw + _i * 8192), 16, 0, 0); } while (0)
; #define PG8_LDA(dst, b, h) do { _Pragma("unroll") for (int m = 0; m < 4; ++m) _Pragma("unroll") for (int k = 0; k < 2; ++k) dst[m][k] = *(const LAS bf16x8*)(lds + PG8_SA(b, h) + aoff + m * 2048 + k * 1024); } while (0)
; #define PG8_MMA(ai, bj, At, Bt) do { __builtin_amdgcn_s_setprio(3); _Pragma("unroll") for (int m = 0; m < 4; ++m) _Pragma("unroll") for (int n = 0; n < 2; ++n) _Pragma("unroll") for (int k = 0; k < 2; ++k) \
;         acc[ai][bj][m][n] = __builtin_amdgcn_mfma_f32_16x16x32_bf16(Bt[n][k], At[m][k], acc[ai][bj][m][n], 0, 0, 0); __builtin_amdgcn_s_setprio(0); } while (0)
; #define PG8_WAIT_V(n) asm volatile("s_waitcnt vmcnt(" #n ")" ::: "memory")
; #define PG8_WAIT_L(n) asm volatile("s_waitcnt lgkmcnt(" #n ")" ::: "memory")
; #define PG8_BAR __builtin_amdgcn_s_barrier()
; #define PG8_SCHED __builtin_amdgcn_sched_barrier(0)
; template <class Epi, class Sched>
; __device__ __forceinline__ void gemm_phase(LAS unsigned char* lds, const Gemm g, const Sched& S, const Epi& E, int tid_in) {
;     ...
;             PG8_WAIT_V(8); PG8_WAIT_L(0); PG8_BAR; PG8_MMA(0, 0, At, B0); PG8_MMA(0, 1, At, B1); PG8_BAR; PG8_SCHED;
;             PG8_LDA(At, 0, 1); PG8_STAGE(PG8_SB(0, 0), b2, voffB); PG8_STAGE(PG8_SB(0, 1), b2 + hstep, voffB);
;             PG8_WAIT_V(6); PG8_WAIT_L(0); PG8_BAR; PG8_MMA(1, 0, At, B0); PG8_MMA(1, 1, At, B1); PG8_BAR; PG8_SCHED;
	v_mfma_f32_16x16x32_bf16 v[0:3], v[108:111], v[182:185], v[68:71]
	v_mfma_f32_16x16x32_bf16 v[68:71], v[116:119], v[182:185], v[72:75]
	v_mfma_f32_16x16x32_bf16 v[72:75], v[108:111], v[192:195], v[76:79]
	v_mfma_f32_16x16x32_bf16 v[76:79], v[116:119], v[192:195], v[80:83]
	v_mfma_f32_16x16x32_bf16 v[80:83], v[108:111], v[200:203], v[84:87]
	v_mfma_f32_16x16x32_bf16 v[84:87], v[116:119], v[200:203], v[88:91]
	v_mfma_f32_16x16x32_bf16 v[88:91], v[108:111], v[208:211], v[92:95]
	v_mfma_f32_16x16x32_bf16 v[92:95], v[116:119], v[208:211], v[96:99]
	v_mfma_f32_16x16x32_bf16 v[0:3], v[112:115], v[188:191], v[0:3]
	v_mfma_f32_16x16x32_bf16 v[68:71], v[120:123], v[188:191], v[68:71]
	v_mfma_f32_16x16x32_bf16 v[72:75], v[112:115], v[196:199], v[72:75]
	v_mfma_f32_16x16x32_bf16 v[76:79], v[120:123], v[196:199], v[76:79]
	v_mfma_f32_16x16x32_bf16 v[80:83], v[112:115], v[204:207], v[80:83]
	v_mfma_f32_16x16x32_bf16 v[84:87], v[120:123], v[204:207], v[84:87]
	v_mfma_f32_16x16x32_bf16 v[88:91], v[112:115], v[212:215], v[88:91]
	v_mfma_f32_16x16x32_bf16 v[96:99], v[120:123], v[212:215], v[92:95]
	s_setprio 0
	s_setprio 3
	v_mfma_f32_16x16x32_bf16 v[52:55], v[174:177], v[200:203], v[52:55]
	v_mfma_f32_16x16x32_bf16 v[92:95], v[124:127], v[182:185], v[100:103]
	v_mfma_f32_16x16x32_bf16 v[36:39], v[174:177], v[182:185], v[36:39]
	v_mfma_f32_16x16x32_bf16 v[40:43], v[124:127], v[192:195], v[40:43]
	v_mfma_f32_16x16x32_bf16 v[44:47], v[174:177], v[192:195], v[44:47]
	v_mfma_f32_16x16x32_bf16 v[48:51], v[124:127], v[200:203], v[48:51]
	v_mfma_f32_16x16x32_bf16 v[182:185], v[178:181], v[204:207], v[52:55]
	v_mfma_f32_16x16x32_bf16 v[52:55], v[124:127], v[208:211], v[56:59]
	v_mfma_f32_16x16x32_bf16 v[36:39], v[178:181], v[188:191], v[36:39]
	v_mfma_f32_16x16x32_bf16 v[40:43], v[146:149], v[196:199], v[40:43]
	v_mfma_f32_16x16x32_bf16 v[44:47], v[178:181], v[196:199], v[44:47]
	v_mfma_f32_16x16x32_bf16 v[48:51], v[146:149], v[204:207], v[48:51]
	v_mfma_f32_16x16x32_bf16 v[56:59], v[146:149], v[212:215], v[52:55]
	v_mfma_f32_16x16x32_bf16 v[52:55], v[174:177], v[208:211], v[60:63]
	v_mfma_f32_16x16x32_bf16 v[216:219], v[146:149], v[188:191], v[92:95]
	v_mfma_f32_16x16x32_bf16 v[188:191], v[178:181], v[212:215], v[52:55]
	s_setprio 0
	s_barrier
	s_mov_b32 m0, s82
	v_lshl_add_u64 v[252:253], s[46:47], 0, v[132:133]
	s_add_u32 s42, s46, 0x10000
	s_nop 0
	ds_read_b128 v[52:55], v145 offset:16384
	ds_read_b128 v[60:63], v145 offset:17408
	ds_read_b128 v[92:95], v145 offset:18432
	ds_read_b128 v[100:103], v145 offset:19456
	ds_read_b128 v[192:195], v145 offset:20480
	ds_read_b128 v[196:199], v145 offset:21504
	ds_read_b128 v[200:203], v145 offset:22528
	ds_read_b128 v[204:207], v145 offset:23552
	global_load_lds_dwordx4 v[252:253], off
	v_lshl_add_u64 v[186:187], s[46:47], 0, v[128:129]
	s_mov_b32 m0, s31
	s_addc_u32 s43, s47, 0
	global_load_lds_dwordx4 v[186:187], off
	v_lshl_add_u64 v[208:209], s[42:43], 0, v[132:133]
	s_mov_b32 m0, s35
	s_nop 0
	global_load_lds_dwordx4 v[208:209], off
	v_lshl_add_u64 v[208:209], s[42:43], 0, v[128:129]
	s_mov_b32 m0, s80
	s_nop 0
	global_load_lds_dwordx4 v[208:209], off
	s_waitcnt vmcnt(6)
	s_waitcnt lgkmcnt(0)
	s_setprio 3
	s_barrier
	v_mfma_f32_16x16x32_bf16 v[4:7], v[108:111], v[200:203], v[4:7]
	v_mfma_f32_16x16x32_bf16 v[8:11], v[116:119], v[200:203], v[8:11]
	v_mfma_f32_16x16x32_bf16 v[150:153], v[108:111], v[52:55], v[150:153]
	v_mfma_f32_16x16x32_bf16 v[154:157], v[116:119], v[52:55], v[154:157]
	v_mfma_f32_16x16x32_bf16 v[158:161], v[108:111], v[92:95], v[158:161]
	v_mfma_f32_16x16x32_bf16 v[162:165], v[116:119], v[92:95], v[162:165]
	v_mfma_f32_16x16x32_bf16 v[166:169], v[108:111], v[192:195], v[166:169]
	v_mfma_f32_16x16x32_bf16 v[170:173], v[116:119], v[192:195], v[170:173]
	v_mfma_f32_16x16x32_bf16 v[4:7], v[112:115], v[204:207], v[4:7]
	v_mfma_f32_16x16x32_bf16 v[8:11], v[120:123], v[204:207], v[8:11]
	v_mfma_f32_16x16x32_bf16 v[150:153], v[112:115], v[60:63], v[150:153]
	v_mfma_f32_16x16x32_bf16 v[154:157], v[120:123], v[60:63], v[154:157]
	v_mfma_f32_16x16x32_bf16 v[158:161], v[112:115], v[100:103], v[158:161]
	v_mfma_f32_16x16x32_bf16 v[162:165], v[120:123], v[100:103], v[162:165]
	v_mfma_f32_16x16x32_bf16 v[166:169], v[112:115], v[196:199], v[166:169]
	v_mfma_f32_16x16x32_bf16 v[170:173], v[120:123], v[196:199], v[170:173]
	s_setprio 0
	s_setprio 3
	v_mfma_f32_16x16x32_bf16 v[12:15], v[124:127], v[52:55], v[12:15]
	v_mfma_f32_16x16x32_bf16 v[208:211], v[146:149], v[60:63], v[12:15]
	v_mfma_f32_16x16x32_bf16 v[12:15], v[174:177], v[52:55], v[16:19]
	v_mfma_f32_16x16x32_bf16 v[16:19], v[178:181], v[60:63], v[12:15]
	v_mfma_f32_16x16x32_bf16 v[12:15], v[124:127], v[92:95], v[28:31]
	v_mfma_f32_16x16x32_bf16 v[212:215], v[146:149], v[100:103], v[12:15]
	v_mfma_f32_16x16x32_bf16 v[12:15], v[174:177], v[92:95], v[32:35]
	v_mfma_f32_16x16x32_bf16 v[32:35], v[178:181], v[100:103], v[12:15]
	v_mfma_f32_16x16x32_bf16 v[12:15], v[124:127], v[192:195], v[64:67]
	v_mfma_f32_16x16x32_bf16 v[220:223], v[146:149], v[196:199], v[12:15]
	v_mfma_f32_16x16x32_bf16 v[12:15], v[174:177], v[192:195], v[104:107]
	v_mfma_f32_16x16x32_bf16 v[192:195], v[178:181], v[196:199], v[12:15]
	v_mfma_f32_16x16x32_bf16 v[12:15], v[124:127], v[200:203], v[20:23]
	v_mfma_f32_16x16x32_bf16 v[146:149], v[146:149], v[204:207], v[12:15]
	v_mfma_f32_16x16x32_bf16 v[12:15], v[174:177], v[200:203], v[24:27]
	v_mfma_f32_16x16x32_bf16 v[174:177], v[178:181], v[204:207], v[12:15]
	s_setprio 0
	s_barrier
; #define PG8_STAGE(bufoff, gbase, voff) do { _Pragma("unroll") for (int _i = 0; _i < 2; ++_i) \
;         __builtin_amdgcn_global_load_lds((const unsigned*)((const char*)(gbase) + (voff)[_i]), (LAS unsigned*)(lds + (bufoff) + ldsw + _i * 8192), 16, 0, 0); } while (0)
; #define PG8_LDA(dst, b, h) do { _Pragma("unroll") for (int m = 0; m < 4; ++m) _Pragma("unroll") for (int k = 0; k < 2; ++k) dst[m][k] = *(const LAS bf16x8*)(lds + PG8_SA(b, h) + aoff + m * 2048 + k * 1024); } while (0)
; #define PG8_LDB(dst, b, h) do { _Pragma("unroll") for (int n = 0; n < 2; ++n) _Pragma("unroll") for (int k = 0; k < 2; ++k) dst[n][k] = *(const LAS bf16x8*)(lds + PG8_SB(b, h) + boff + n * 2048 + k * 1024); } while (0)
; #define PG8_MMA(ai, bj, At, Bt) do { __builtin_amdgcn_s_setprio(3); _Pragma("unroll") for (int m = 0; m < 4; ++m) _Pragma("unroll") for (int n = 0; n < 2; ++n) _Pragma("unroll") for (int k = 0; k < 2; ++k) \
;         acc[ai][bj][m][n] = __builtin_amdgcn_mfma_f32_16x16x32_bf16(Bt[n][k], At[m][k], acc[ai][bj][m][n], 0, 0, 0); __builtin_amdgcn_s_setprio(0); } while (0)
; #define PG8_WAIT_V(n) asm volatile("s_waitcnt vmcnt(" #n ")" ::: "memory")
; #define PG8_WAIT_L(n) asm volatile("s_waitcnt lgkmcnt(" #n ")" ::: "memory")
; #define PG8_BAR __builtin_amdgcn_s_barrier()
; #define PG8_SCHED __builtin_amdgcn_sched_barrier(0)
; template <class Epi, class Sched>
; __device__ __forceinline__ void gemm_phase(LAS unsigned char* lds, const Gemm g, const Sched& S, const Epi& E, int tid_in) {
;     ...
;             PG8_LDB(B0, 1, 0); PG8_LDB(B1, 1, 1); PG8_SCHED; PG8_LDA(At, 1, 0); PG8_STAGE(PG8_SA(0, 0), a2, voffA); PG8_STAGE(PG8_SA(0, 1), a2 + hstep, voffA);
;             PG8_WAIT_V(8); PG8_WAIT_L(0); PG8_BAR; PG8_MMA(0, 0, At, B0); PG8_MMA(0, 1, At, B1); PG8_BAR; PG8_SCHED;
;             PG8_LDA(At, 1, 1); PG8_STAGE(PG8_SB(1, 0), b3, voffB); PG8_STAGE(PG8_SB(1, 1), b3 + hstep, voffB);
;             PG8_WAIT_V(6); PG8_WAIT_L(0); PG8_BAR; PG8_MMA(1, 0, At, B0); PG8_MMA(1, 1, At, B1); PG8_BAR; PG8_SCHED;
;         }
;         if (wr == 0) PG8_BAR;
	s_nop 4
	ds_read_b128 v[12:15], v224
	ds_read_b128 v[24:27], v224 offset:1024
	ds_read_b128 v[64:67], v224 offset:2048
	ds_read_b128 v[178:181], v224 offset:3072
	ds_read_b128 v[196:199], v225
	ds_read_b128 v[200:203], v225 offset:1024
	ds_read_b128 v[204:207], v225 offset:2048
	ds_read_b128 v[224:227], v225 offset:3072
	s_mov_b32 m0, s41
	v_lshl_add_u64 v[52:53], s[48:49], 0, v[134:135]
	s_add_u32 s42, s48, 0x10000
	ds_read_b128 v[20:23], v145 offset:32768
	ds_read_b128 v[28:31], v145 offset:33792
	ds_read_b128 v[228:231], v145 offset:34816
	ds_read_b128 v[232:235], v145 offset:35840
	ds_read_b128 v[236:239], v145 offset:36864
	ds_read_b128 v[240:243], v145 offset:37888
	ds_read_b128 v[244:247], v145 offset:38912
	ds_read_b128 v[248:251], v145 offset:39936
	global_load_lds_dwordx4 v[52:53], off
	v_lshl_add_u64 v[52:53], s[48:49], 0, v[130:131]
	s_mov_b32 m0, s66
	s_addc_u32 s43, s49, 0
	global_load_lds_dwordx4 v[52:53], off
	v_lshl_add_u64 v[52:53], s[42:43], 0, v[134:135]
	s_mov_b32 m0, s67
	s_nop 0
	global_load_lds_dwordx4 v[52:53], off
	v_lshl_add_u64 v[52:53], s[42:43], 0, v[130:131]
	s_mov_b32 m0, s68
	s_nop 0
	global_load_lds_dwordx4 v[52:53], off
	s_waitcnt vmcnt(8)
	s_waitcnt lgkmcnt(0)
	s_setprio 3
	s_barrier
	v_mfma_f32_16x16x32_bf16 v[0:3], v[12:15], v[20:23], v[0:3]
	v_mfma_f32_16x16x32_bf16 v[124:127], v[24:27], v[28:31], v[0:3]
	v_mfma_f32_16x16x32_bf16 v[0:3], v[64:67], v[20:23], v[68:71]
	v_mfma_f32_16x16x32_bf16 v[116:119], v[178:181], v[28:31], v[0:3]
	v_mfma_f32_16x16x32_bf16 v[0:3], v[12:15], v[228:231], v[72:75]
	v_mfma_f32_16x16x32_bf16 v[108:111], v[24:27], v[232:235], v[0:3]
	v_mfma_f32_16x16x32_bf16 v[0:3], v[64:67], v[228:231], v[76:79]
	v_mfma_f32_16x16x32_bf16 v[100:103], v[178:181], v[232:235], v[0:3]
	v_mfma_f32_16x16x32_bf16 v[0:3], v[12:15], v[236:239], v[80:83]
	v_mfma_f32_16x16x32_bf16 v[92:95], v[24:27], v[240:243], v[0:3]
	v_mfma_f32_16x16x32_bf16 v[0:3], v[64:67], v[236:239], v[84:87]
	v_mfma_f32_16x16x32_bf16 v[84:87], v[178:181], v[240:243], v[0:3]
	v_mfma_f32_16x16x32_bf16 v[0:3], v[12:15], v[244:247], v[88:91]
	v_mfma_f32_16x16x32_bf16 v[60:63], v[24:27], v[248:251], v[0:3]
	v_mfma_f32_16x16x32_bf16 v[0:3], v[64:67], v[244:247], v[96:99]
	v_mfma_f32_16x16x32_bf16 v[52:55], v[178:181], v[248:251], v[0:3]
	s_setprio 0
	s_setprio 3
	v_mfma_f32_16x16x32_bf16 v[0:3], v[196:199], v[20:23], v[216:219]
	v_mfma_f32_16x16x32_bf16 v[120:123], v[200:203], v[28:31], v[0:3]
	v_mfma_f32_16x16x32_bf16 v[0:3], v[204:207], v[20:23], v[36:39]
	v_mfma_f32_16x16x32_bf16 v[112:115], v[224:227], v[28:31], v[0:3]
	v_mfma_f32_16x16x32_bf16 v[0:3], v[196:199], v[228:231], v[40:43]
	v_mfma_f32_16x16x32_bf16 v[104:107], v[200:203], v[232:235], v[0:3]
	v_mfma_f32_16x16x32_bf16 v[0:3], v[204:207], v[228:231], v[44:47]
	v_mfma_f32_16x16x32_bf16 v[96:99], v[224:227], v[232:235], v[0:3]
	v_mfma_f32_16x16x32_bf16 v[0:3], v[196:199], v[236:239], v[48:51]
	v_mfma_f32_16x16x32_bf16 v[88:91], v[200:203], v[240:243], v[0:3]
	v_mfma_f32_16x16x32_bf16 v[0:3], v[204:207], v[236:239], v[182:185]
	v_mfma_f32_16x16x32_bf16 v[80:83], v[224:227], v[240:243], v[0:3]
	v_mfma_f32_16x16x32_bf16 v[0:3], v[196:199], v[244:247], v[56:59]
	v_mfma_f32_16x16x32_bf16 v[56:59], v[200:203], v[248:251], v[0:3]
	v_mfma_f32_16x16x32_bf16 v[0:3], v[204:207], v[244:247], v[188:191]
	v_mfma_f32_16x16x32_bf16 v[48:51], v[224:227], v[248:251], v[0:3]
	s_setprio 0
	s_barrier
	s_mov_b32 m0, s83
	v_lshl_add_u64 v[20:21], v[252:253], 0, s[8:9]
	s_add_u32 s42, s46, 0x10080
	s_nop 1
	ds_read_b128 v[0:3], v145 offset:49152
	ds_read_b128 v[40:43], v145 offset:50176
	ds_read_b128 v[182:185], v145 offset:51200
	ds_read_b128 v[188:191], v145 offset:52224
	ds_read_b128 v[216:219], v145 offset:53248
	ds_read_b128 v[228:231], v145 offset:54272
	ds_read_b128 v[232:235], v145 offset:55296
	ds_read_b128 v[236:239], v145 offset:56320
	global_load_lds_dwordx4 v[20:21], off
	v_lshl_add_u64 v[20:21], v[186:187], 0, s[8:9]
	s_mov_b32 m0, s81
	s_addc_u32 s43, s47, 0
	global_load_lds_dwordx4 v[20:21], off
	v_lshl_add_u64 v[20:21], s[42:43], 0, v[132:133]
	s_mov_b32 m0, s44
	s_nop 0
	global_load_lds_dwordx4 v[20:21], off
	v_lshl_add_u64 v[20:21], s[42:43], 0, v[128:129]
	s_mov_b32 m0, s45
	s_nop 0
	global_load_lds_dwordx4 v[20:21], off
	s_waitcnt vmcnt(6)
	s_waitcnt lgkmcnt(0)
	s_setprio 3
	s_barrier
	v_mfma_f32_16x16x32_bf16 v[20:23], v[12:15], v[0:3], v[150:153]
	v_mfma_f32_16x16x32_bf16 v[76:79], v[24:27], v[40:43], v[20:23]
	v_mfma_f32_16x16x32_bf16 v[20:23], v[64:67], v[0:3], v[154:157]
	v_mfma_f32_16x16x32_bf16 v[68:71], v[178:181], v[40:43], v[20:23]
	v_mfma_f32_16x16x32_bf16 v[20:23], v[12:15], v[182:185], v[158:161]
	v_mfma_f32_16x16x32_bf16 v[44:47], v[24:27], v[188:191], v[20:23]
	v_mfma_f32_16x16x32_bf16 v[20:23], v[64:67], v[182:185], v[162:165]
	v_mfma_f32_16x16x32_bf16 v[36:39], v[178:181], v[188:191], v[20:23]
	v_mfma_f32_16x16x32_bf16 v[20:23], v[12:15], v[216:219], v[166:169]
	v_mfma_f32_16x16x32_bf16 v[4:7], v[12:15], v[232:235], v[4:7]
	v_mfma_f32_16x16x32_bf16 v[28:31], v[24:27], v[228:231], v[20:23]
	v_mfma_f32_16x16x32_bf16 v[20:23], v[64:67], v[216:219], v[170:173]
	v_mfma_f32_16x16x32_bf16 v[12:15], v[24:27], v[236:239], v[4:7]
	v_mfma_f32_16x16x32_bf16 v[4:7], v[64:67], v[232:235], v[8:11]
	v_mfma_f32_16x16x32_bf16 v[20:23], v[178:181], v[228:231], v[20:23]
	v_mfma_f32_16x16x32_bf16 v[4:7], v[178:181], v[236:239], v[4:7]
	s_setprio 0
	s_setprio 3
	v_mfma_f32_16x16x32_bf16 v[8:11], v[196:199], v[0:3], v[208:211]
	v_mfma_f32_16x16x32_bf16 v[0:3], v[204:207], v[0:3], v[16:19]
	v_mfma_f32_16x16x32_bf16 v[64:67], v[224:227], v[40:43], v[0:3]
	v_mfma_f32_16x16x32_bf16 v[0:3], v[196:199], v[182:185], v[212:215]
	v_mfma_f32_16x16x32_bf16 v[72:75], v[200:203], v[40:43], v[8:11]
	v_mfma_f32_16x16x32_bf16 v[40:43], v[200:203], v[188:191], v[0:3]
	v_mfma_f32_16x16x32_bf16 v[0:3], v[204:207], v[182:185], v[32:35]
	v_mfma_f32_16x16x32_bf16 v[32:35], v[224:227], v[188:191], v[0:3]
	v_mfma_f32_16x16x32_bf16 v[0:3], v[196:199], v[216:219], v[220:223]
	v_mfma_f32_16x16x32_bf16 v[24:27], v[200:203], v[228:231], v[0:3]
	v_mfma_f32_16x16x32_bf16 v[0:3], v[204:207], v[216:219], v[192:195]
	v_mfma_f32_16x16x32_bf16 v[16:19], v[224:227], v[228:231], v[0:3]
	v_mfma_f32_16x16x32_bf16 v[0:3], v[196:199], v[232:235], v[146:149]
	v_mfma_f32_16x16x32_bf16 v[8:11], v[200:203], v[236:239], v[0:3]
	v_mfma_f32_16x16x32_bf16 v[0:3], v[204:207], v[232:235], v[174:177]
	v_mfma_f32_16x16x32_bf16 v[0:3], v[224:227], v[236:239], v[0:3]
	s_setprio 0
	s_barrier
	s_andn2_b64 vcc, exec, s[14:15]
	s_cbranch_vccnz .LBB0_990
	s_barrier

;     __device__ bool next(int i, Unit& u) const { if (!b.next(i >> 1, u)) return false; u.half = i & 1; u.koff = (i & 1) * kbytes; return true; }
; #define PG8_STAGE(bufoff, gbase, voff) do { _Pragma("unroll") for (int _i = 0; _i < 2; ++_i) \
;         __builtin_amdgcn_global_load_lds((const unsigned*)((const char*)(gbase) + (voff)[_i]), (LAS unsigned*)(lds + (bufoff) + ldsw + _i * 8192), 16, 0, 0); } while (0)
; #define PG8_LDA(dst, b, h) do { _Pragma("unroll") for (int m = 0; m < 4; ++m) _Pragma("unroll") for (int k = 0; k < 2; ++k) dst[m][k] = *(const LAS bf16x8*)(lds + PG8_SA(b, h) + aoff + m * 2048 + k * 1024); } while (0)
; #define PG8_LDB(dst, b, h) do { _Pragma("unroll") for (int n = 0; n < 2; ++n) _Pragma("unroll") for (int k = 0; k < 2; ++k) dst[n][k] = *(const LAS bf16x8*)(lds + PG8_SB(b, h) + boff + n * 2048 + k * 1024); } while (0)
; #define PG8_WAIT_V(n) asm volatile("s_waitcnt vmcnt(" #n ")" ::: "memory")
; #define PG8_WAIT_L(n) asm volatile("s_waitcnt lgkmcnt(" #n ")" ::: "memory")
; #define PG8_BAR __builtin_amdgcn_s_barrier()
; #define PG8_SCHED __builtin_amdgcn_sched_barrier(0)
; template <class Epi, class Sched>
; __device__ __forceinline__ void gemm_phase(LAS unsigned char* lds, const Gemm g, const Sched& S, const Epi& E, int tid_in) {
;     ...
;         const bool has_next = S.next(ui + 1, nxt);
;         const char* nA = has_next ? (const char*)g.A + (size_t)nxt.pm * tstep + nxt.koff : cA; const char* nB = has_next ? (const char*)g.Bt + (size_t)nxt.pn * tstep + nxt.koff : cB;
;         for (int t = 0; t < nt; t += 2) {
;             const bool last = (t == nt - 2);
;             const char* a1 = cA + (size_t)(t + 1) * kstep;
;             const char* a2 = last ? nA : cA + (size_t)(t + 2) * kstep; const char* b2 = last ? nB : cB + (size_t)(t + 2) * kstep;
;             const char* a3 = a2 + kstep; const char* b3 = b2 + kstep;
;             PG8_LDB(B0, 0, 0); PG8_LDB(B1, 0, 1); PG8_SCHED; PG8_LDA(At, 0, 0); PG8_STAGE(PG8_SA(1, 0), a1, voffA); PG8_STAGE(PG8_SA(1, 1), a1 + hstep, voffA);
;             PG8_WAIT_V(8); PG8_WAIT_L(0); PG8_BAR; PG8_MMA(0, 0, At, B0); PG8_MMA(0, 1, At, B1); PG8_BAR; PG8_SCHED;
;             PG8_LDA(At, 0, 1); PG8_STAGE(PG8_SB(0, 0), b2, voffB); PG8_STAGE(PG8_SB(0, 1), b2 + hstep, voffB);
;             PG8_WAIT_V(6); PG8_WAIT_L(0); PG8_BAR; PG8_MMA(1, 0, At, B0); PG8_MMA(1, 1, At, B1); PG8_BAR; PG8_SCHED;
.LBB0_1008:
	s_ashr_i32 s23, s22, 31
	s_lshl_b64 s[24:25], s[22:23], 20
	s_add_u32 s24, s58, s24
	s_addc_u32 s25, s59, s25
	s_and_b64 s[26:27], s[4:5], exec
	s_cselect_b32 s23, s25, s31
	s_cselect_b32 s29, s24, s30
	s_ashr_i32 s21, s20, 31
	s_lshl_b64 s[26:27], s[20:21], 20
	s_add_u32 s26, s60, s26
	s_addc_u32 s27, s61, s27
	s_and_b64 s[36:37], s[4:5], exec
	s_cselect_b32 s21, s27, s35
	s_cselect_b32 s47, s26, s34
	s_add_u32 s48, s34, 0x100
	v_lshl_add_u64 v[144:145], s[30:31], 0, v[136:137]
	v_lshl_add_u64 v[146:147], s[30:31], 0, v[138:139]
	s_addc_u32 s49, s35, 0
	s_mov_b32 s51, -2
	s_mov_b64 s[34:35], 0
	s_waitcnt lgkmcnt(0)
	ds_read_b128 v[158:161], v153
	ds_read_b128 v[162:165], v153 offset:1024
	ds_read_b128 v[166:169], v153 offset:2048
	ds_read_b128 v[170:173], v153 offset:3072
	ds_read_b128 v[174:177], v154
	ds_read_b128 v[178:181], v154 offset:1024
	ds_read_b128 v[182:185], v154 offset:2048
	ds_read_b128 v[188:191], v154 offset:3072
	s_add_u32 s36, s30, s34
	s_addc_u32 s37, s31, s35
	s_add_u32 s38, s36, 0x100
	s_addc_u32 s39, s37, 0
	s_add_u32 s36, s48, s34
	s_addc_u32 s37, s49, s35
	s_cmpk_eq_i32 s34, 0xf00
	s_cselect_b32 s37, s21, s37
	s_cselect_b32 s36, s47, s36
	s_cselect_b32 s39, s23, s39
	s_cselect_b32 s38, s29, s38
	v_lshl_add_u64 v[148:149], v[146:147], 0, s[34:35]
	v_lshl_add_u64 v[186:187], v[148:149], 0, s[14:15]
	s_add_i32 m0, s3, 0x8000
	ds_read_b128 v[192:195], v155
	ds_read_b128 v[196:199], v155 offset:1024
	ds_read_b128 v[200:203], v155 offset:2048
	ds_read_b128 v[204:207], v155 offset:3072
	ds_read_b128 v[208:211], v155 offset:4096
	ds_read_b128 v[212:215], v155 offset:5120
	ds_read_b128 v[216:219], v155 offset:6144
	ds_read_b128 v[220:223], v155 offset:7168
	global_load_lds_dwordx4 v[186:187], off
	v_lshl_add_u64 v[186:187], v[144:145], 0, s[34:35]
	v_lshl_add_u64 v[224:225], v[186:187], 0, s[14:15]
	s_add_i32 m0, s3, 0xa000
	v_lshl_add_u64 v[148:149], v[148:149], 0, s[16:17]
	global_load_lds_dwordx4 v[224:225], off
	s_add_i32 m0, s3, 0xc000
	s_nop 0
	global_load_lds_dwordx4 v[148:149], off
	v_lshl_add_u64 v[148:149], v[186:187], 0, s[16:17]
	s_add_i32 m0, s3, 0xe000
	s_nop 0
	global_load_lds_dwordx4 v[148:149], off
	s_waitcnt vmcnt(8)
	s_waitcnt lgkmcnt(0)
	s_setprio 3
	s_barrier
	v_mfma_f32_16x16x32_bf16 v[124:127], v[158:161], v[192:195], 0
	v_mfma_f32_16x16x32_bf16 v[120:123], v[166:169], v[192:195], 0
	v_mfma_f32_16x16x32_bf16 v[108:111], v[158:161], v[200:203], 0
	v_mfma_f32_16x16x32_bf16 v[104:107], v[166:169], v[200:203], 0
	v_mfma_f32_16x16x32_bf16 v[92:95], v[158:161], v[208:211], 0
	v_mfma_f32_16x16x32_bf16 v[88:91], v[166:169], v[208:211], 0
	v_mfma_f32_16x16x32_bf16 v[76:79], v[158:161], v[216:219], 0
	v_mfma_f32_16x16x32_bf16 v[72:75], v[166:169], v[216:219], 0
	v_mfma_f32_16x16x32_bf16 v[124:127], v[162:165], v[196:199], v[124:127]
	v_mfma_f32_16x16x32_bf16 v[120:123], v[170:173], v[196:199], v[120:123]
	v_mfma_f32_16x16x32_bf16 v[108:111], v[162:165], v[204:207], v[108:111]
	v_mfma_f32_16x16x32_bf16 v[104:107], v[170:173], v[204:207], v[104:107]
	v_mfma_f32_16x16x32_bf16 v[92:95], v[162:165], v[212:215], v[92:95]
	v_mfma_f32_16x16x32_bf16 v[88:91], v[170:173], v[212:215], v[88:91]
	v_mfma_f32_16x16x32_bf16 v[76:79], v[162:165], v[220:223], v[76:79]
	v_mfma_f32_16x16x32_bf16 v[72:75], v[170:173], v[220:223], v[72:75]
	s_setprio 0
	s_setprio 3
	v_mfma_f32_16x16x32_bf16 v[116:119], v[174:177], v[192:195], 0
	v_mfma_f32_16x16x32_bf16 v[112:115], v[182:185], v[192:195], 0
	v_mfma_f32_16x16x32_bf16 v[100:103], v[174:177], v[200:203], 0
	v_mfma_f32_16x16x32_bf16 v[96:99], v[182:185], v[200:203], 0
	v_mfma_f32_16x16x32_bf16 v[84:87], v[174:177], v[208:211], 0
	v_mfma_f32_16x16x32_bf16 v[80:83], v[182:185], v[208:211], 0
	v_mfma_f32_16x16x32_bf16 v[68:71], v[174:177], v[216:219], 0
	v_mfma_f32_16x16x32_bf16 v[64:67], v[182:185], v[216:219], 0
	v_mfma_f32_16x16x32_bf16 v[116:119], v[178:181], v[196:199], v[116:119]
	v_mfma_f32_16x16x32_bf16 v[112:115], v[188:191], v[196:199], v[112:115]
	v_mfma_f32_16x16x32_bf16 v[100:103], v[178:181], v[204:207], v[100:103]
	v_mfma_f32_16x16x32_bf16 v[96:99], v[188:191], v[204:207], v[96:99]
	v_mfma_f32_16x16x32_bf16 v[84:87], v[178:181], v[212:215], v[84:87]
	v_mfma_f32_16x16x32_bf16 v[80:83], v[188:191], v[212:215], v[80:83]
	v_mfma_f32_16x16x32_bf16 v[68:71], v[178:181], v[220:223], v[68:71]
	v_mfma_f32_16x16x32_bf16 v[64:67], v[188:191], v[220:223], v[64:67]
	s_setprio 0
	s_barrier
	s_add_i32 s62, s44, s2
	v_lshl_add_u64 v[148:149], s[36:37], 0, v[130:131]
	s_mov_b32 m0, s62
	ds_read_b128 v[192:195], v155 offset:16384
	ds_read_b128 v[196:199], v155 offset:17408
	ds_read_b128 v[200:203], v155 offset:18432
	ds_read_b128 v[204:207], v155 offset:19456
	ds_read_b128 v[208:211], v155 offset:20480
	ds_read_b128 v[212:215], v155 offset:21504
	ds_read_b128 v[216:219], v155 offset:22528
	ds_read_b128 v[220:223], v155 offset:23552
	global_load_lds_dwordx4 v[148:149], off
	s_add_i32 m0, s62, 0x2000
	s_add_u32 s62, s36, 0x80000
	v_lshl_add_u64 v[186:187], s[36:37], 0, v[134:135]
	s_addc_u32 s63, s37, 0
	s_add_i32 s64, s45, s2
	global_load_lds_dwordx4 v[186:187], off
	v_lshl_add_u64 v[224:225], s[62:63], 0, v[130:131]
	s_mov_b32 m0, s64
	s_nop 0
	global_load_lds_dwordx4 v[224:225], off
	v_lshl_add_u64 v[224:225], s[62:63], 0, v[134:135]
	s_add_i32 m0, s64, 0x2000
	s_nop 0
	global_load_lds_dwordx4 v[224:225], off
	s_waitcnt vmcnt(6)
	s_waitcnt lgkmcnt(0)
	s_setprio 3
	s_barrier
; #define PG8_STAGE(bufoff, gbase, voff) do { _Pragma("unroll") for (int _i = 0; _i < 2; ++_i) \
;         __builtin_amdgcn_global_load_lds((const unsigned*)((const char*)(gbase) + (voff)[_i]), (LAS unsigned*)(lds + (bufoff) + ldsw + _i * 8192), 16, 0, 0); } while (0)
; #define PG8_LDA(dst, b, h) do { _Pragma("unroll") for (int m = 0; m < 4; ++m) _Pragma("unroll") for (int k = 0; k < 2; ++k) dst[m][k] = *(const LAS bf16x8*)(lds + PG8_SA(b, h) + aoff + m * 2048 + k * 1024); } while (0)
; #define PG8_LDB(dst, b, h) do { _Pragma("unroll") for (int n = 0; n < 2; ++n) _Pragma("unroll") for (int k = 0; k < 2; ++k) dst[n][k] = *(const LAS bf16x8*)(lds + PG8_SB(b, h) + boff + n * 2048 + k * 1024); } while (0)
; #define PG8_MMA(ai, bj, At, Bt) do { __builtin_amdgcn_s_setprio(3); _Pragma("unroll") for (int m = 0; m < 4; ++m) _Pragma("unroll") for (int n = 0; n < 2; ++n) _Pragma("unroll") for (int k = 0; k < 2; ++k) \
;         acc[ai][bj][m][n] = __builtin_amdgcn_mfma_f32_16x16x32_bf16(Bt[n][k], At[m][k], acc[ai][bj][m][n], 0, 0, 0); __builtin_amdgcn_s_setprio(0); } while (0)
; #define PG8_WAIT_V(n) asm volatile("s_waitcnt vmcnt(" #n ")" ::: "memory")
; #define PG8_WAIT_L(n) asm volatile("s_waitcnt lgkmcnt(" #n ")" ::: "memory")
; #define PG8_BAR __builtin_amdgcn_s_barrier()
; #define PG8_SCHED __builtin_amdgcn_sched_barrier(0)
; template <class Epi, class Sched>
; __device__ __forceinline__ void gemm_phase(LAS unsigned char* lds, const Gemm g, const Sched& S, const Epi& E, int tid_in) {
;     ...
;             PG8_WAIT_V(6); PG8_WAIT_L(0); PG8_BAR; PG8_MMA(1, 0, At, B0); PG8_MMA(1, 1, At, B1); PG8_BAR; PG8_SCHED;
;             PG8_LDB(B0, 1, 0); PG8_LDB(B1, 1, 1); PG8_SCHED; PG8_LDA(At, 1, 0); PG8_STAGE(PG8_SA(0, 0), a2, voffA); PG8_STAGE(PG8_SA(0, 1), a2 + hstep, voffA);
;             PG8_WAIT_V(8); PG8_WAIT_L(0); PG8_BAR; PG8_MMA(0, 0, At, B0); PG8_MMA(0, 1, At, B1); PG8_BAR; PG8_SCHED;
	v_mfma_f32_16x16x32_bf16 v[60:63], v[158:161], v[192:195], 0
	v_mfma_f32_16x16x32_bf16 v[56:59], v[166:169], v[192:195], 0
	v_mfma_f32_16x16x32_bf16 v[44:47], v[158:161], v[200:203], 0
	v_mfma_f32_16x16x32_bf16 v[40:43], v[166:169], v[200:203], 0
	v_mfma_f32_16x16x32_bf16 v[28:31], v[158:161], v[208:211], 0
	v_mfma_f32_16x16x32_bf16 v[24:27], v[166:169], v[208:211], 0
	v_mfma_f32_16x16x32_bf16 v[12:15], v[158:161], v[216:219], 0
	v_mfma_f32_16x16x32_bf16 v[8:11], v[166:169], v[216:219], 0
	v_mfma_f32_16x16x32_bf16 v[60:63], v[162:165], v[196:199], v[60:63]
	v_mfma_f32_16x16x32_bf16 v[56:59], v[170:173], v[196:199], v[56:59]
	v_mfma_f32_16x16x32_bf16 v[44:47], v[162:165], v[204:207], v[44:47]
	v_mfma_f32_16x16x32_bf16 v[40:43], v[170:173], v[204:207], v[40:43]
	v_mfma_f32_16x16x32_bf16 v[28:31], v[162:165], v[212:215], v[28:31]
	v_mfma_f32_16x16x32_bf16 v[24:27], v[170:173], v[212:215], v[24:27]
	v_mfma_f32_16x16x32_bf16 v[12:15], v[162:165], v[220:223], v[12:15]
	v_mfma_f32_16x16x32_bf16 v[8:11], v[170:173], v[220:223], v[8:11]
	s_setprio 0
	s_setprio 3
	v_mfma_f32_16x16x32_bf16 v[52:55], v[174:177], v[192:195], 0
	v_mfma_f32_16x16x32_bf16 v[48:51], v[182:185], v[192:195], 0
	v_mfma_f32_16x16x32_bf16 v[36:39], v[174:177], v[200:203], 0
	v_mfma_f32_16x16x32_bf16 v[32:35], v[182:185], v[200:203], 0
	v_mfma_f32_16x16x32_bf16 v[20:23], v[174:177], v[208:211], 0
	v_mfma_f32_16x16x32_bf16 v[16:19], v[182:185], v[208:211], 0
	v_mfma_f32_16x16x32_bf16 v[4:7], v[174:177], v[216:219], 0
	v_mfma_f32_16x16x32_bf16 v[0:3], v[182:185], v[216:219], 0
	v_mfma_f32_16x16x32_bf16 v[52:55], v[178:181], v[196:199], v[52:55]
	v_mfma_f32_16x16x32_bf16 v[48:51], v[188:191], v[196:199], v[48:51]
	v_mfma_f32_16x16x32_bf16 v[36:39], v[178:181], v[204:207], v[36:39]
	v_mfma_f32_16x16x32_bf16 v[32:35], v[188:191], v[204:207], v[32:35]
	v_mfma_f32_16x16x32_bf16 v[20:23], v[178:181], v[212:215], v[20:23]
	v_mfma_f32_16x16x32_bf16 v[16:19], v[188:191], v[212:215], v[16:19]
	v_mfma_f32_16x16x32_bf16 v[4:7], v[178:181], v[220:223], v[4:7]
	v_mfma_f32_16x16x32_bf16 v[0:3], v[188:191], v[220:223], v[0:3]
	s_setprio 0
	s_barrier
	s_add_i32 s62, 0, 0x18000
	v_add_u32_e32 v157, s62, v151
	s_add_i32 s63, 0, 0x1c000
	ds_read_b128 v[158:161], v157
	ds_read_b128 v[162:165], v157 offset:1024
	ds_read_b128 v[166:169], v157 offset:2048
	ds_read_b128 v[170:173], v157 offset:3072
	v_add_u32_e32 v157, s63, v151
	ds_read_b128 v[174:177], v157
	ds_read_b128 v[178:181], v157 offset:1024
	ds_read_b128 v[182:185], v157 offset:2048
	ds_read_b128 v[188:191], v157 offset:3072
	s_mov_b32 m0, s3
	v_lshl_add_u64 v[224:225], s[38:39], 0, v[128:129]
	ds_read_b128 v[192:195], v155 offset:32768
	ds_read_b128 v[196:199], v155 offset:33792
	ds_read_b128 v[200:203], v155 offset:34816
	ds_read_b128 v[204:207], v155 offset:35840
	ds_read_b128 v[208:211], v155 offset:36864
	ds_read_b128 v[212:215], v155 offset:37888
	ds_read_b128 v[216:219], v155 offset:38912
	ds_read_b128 v[220:223], v155 offset:39936
	global_load_lds_dwordx4 v[224:225], off
	v_lshl_add_u64 v[224:225], s[38:39], 0, v[132:133]
	s_add_u32 s38, s38, 0x80000
	s_mov_b32 m0, s40
	s_addc_u32 s39, s39, 0
	global_load_lds_dwordx4 v[224:225], off
	v_lshl_add_u64 v[224:225], s[38:39], 0, v[128:129]
	s_mov_b32 m0, s41
	s_nop 0
	global_load_lds_dwordx4 v[224:225], off
	v_lshl_add_u64 v[224:225], s[38:39], 0, v[132:133]
	s_mov_b32 m0, s42
	s_nop 0
	global_load_lds_dwordx4 v[224:225], off
	s_waitcnt vmcnt(8)
	s_waitcnt lgkmcnt(0)
	s_setprio 3
	s_barrier
	v_mfma_f32_16x16x32_bf16 v[124:127], v[158:161], v[192:195], v[124:127]
	v_mfma_f32_16x16x32_bf16 v[120:123], v[166:169], v[192:195], v[120:123]
	v_mfma_f32_16x16x32_bf16 v[108:111], v[158:161], v[200:203], v[108:111]
	v_mfma_f32_16x16x32_bf16 v[104:107], v[166:169], v[200:203], v[104:107]
	v_mfma_f32_16x16x32_bf16 v[92:95], v[158:161], v[208:211], v[92:95]
	v_mfma_f32_16x16x32_bf16 v[88:91], v[166:169], v[208:211], v[88:91]
	v_mfma_f32_16x16x32_bf16 v[76:79], v[158:161], v[216:219], v[76:79]
	v_mfma_f32_16x16x32_bf16 v[72:75], v[166:169], v[216:219], v[72:75]
	v_mfma_f32_16x16x32_bf16 v[124:127], v[162:165], v[196:199], v[124:127]
	v_mfma_f32_16x16x32_bf16 v[120:123], v[170:173], v[196:199], v[120:123]
	v_mfma_f32_16x16x32_bf16 v[108:111], v[162:165], v[204:207], v[108:111]
	v_mfma_f32_16x16x32_bf16 v[104:107], v[170:173], v[204:207], v[104:107]
	v_mfma_f32_16x16x32_bf16 v[92:95], v[162:165], v[212:215], v[92:95]
	v_mfma_f32_16x16x32_bf16 v[88:91], v[170:173], v[212:215], v[88:91]
	v_mfma_f32_16x16x32_bf16 v[76:79], v[162:165], v[220:223], v[76:79]
	v_mfma_f32_16x16x32_bf16 v[72:75], v[170:173], v[220:223], v[72:75]
	s_setprio 0
	s_setprio 3
	v_mfma_f32_16x16x32_bf16 v[116:119], v[174:177], v[192:195], v[116:119]
	v_mfma_f32_16x16x32_bf16 v[112:115], v[182:185], v[192:195], v[112:115]
	v_mfma_f32_16x16x32_bf16 v[100:103], v[174:177], v[200:203], v[100:103]
	v_mfma_f32_16x16x32_bf16 v[96:99], v[182:185], v[200:203], v[96:99]
	v_mfma_f32_16x16x32_bf16 v[84:87], v[174:177], v[208:211], v[84:87]
	v_mfma_f32_16x16x32_bf16 v[80:83], v[182:185], v[208:211], v[80:83]
	v_mfma_f32_16x16x32_bf16 v[68:71], v[174:177], v[216:219], v[68:71]
	v_mfma_f32_16x16x32_bf16 v[64:67], v[182:185], v[216:219], v[64:67]
	v_mfma_f32_16x16x32_bf16 v[116:119], v[178:181], v[196:199], v[116:119]
	v_mfma_f32_16x16x32_bf16 v[112:115], v[188:191], v[196:199], v[112:115]
	v_mfma_f32_16x16x32_bf16 v[100:103], v[178:181], v[204:207], v[100:103]
	v_mfma_f32_16x16x32_bf16 v[96:99], v[188:191], v[204:207], v[96:99]
	v_mfma_f32_16x16x32_bf16 v[84:87], v[178:181], v[212:215], v[84:87]
	v_mfma_f32_16x16x32_bf16 v[80:83], v[188:191], v[212:215], v[80:83]
	v_mfma_f32_16x16x32_bf16 v[68:71], v[178:181], v[220:223], v[68:71]
	v_mfma_f32_16x16x32_bf16 v[64:67], v[188:191], v[220:223], v[64:67]
	s_setprio 0
	s_barrier
; #define PG8_STAGE(bufoff, gbase, voff) do { _Pragma("unroll") for (int _i = 0; _i < 2; ++_i) \
;         __builtin_amdgcn_global_load_lds((const unsigned*)((const char*)(gbase) + (voff)[_i]), (LAS unsigned*)(lds + (bufoff) + ldsw + _i * 8192), 16, 0, 0); } while (0)
; #define PG8_LDA(dst, b, h) do { _Pragma("unroll") for (int m = 0; m < 4; ++m) _Pragma("unroll") for (int k = 0; k < 2; ++k) dst[m][k] = *(const LAS bf16x8*)(lds + PG8_SA(b, h) + aoff + m * 2048 + k * 1024); } while (0)
; #define PG8_LDB(dst, b, h) do { _Pragma("unroll") for (int n = 0; n < 2; ++n) _Pragma("unroll") for (int k = 0; k < 2; ++k) dst[n][k] = *(const LAS bf16x8*)(lds + PG8_SB(b, h) + boff + n * 2048 + k * 1024); } while (0)
; #define PG8_MMA(ai, bj, At, Bt) do { __builtin_amdgcn_s_setprio(3); _Pragma("unroll") for (int m = 0; m < 4; ++m) _Pragma("unroll") for (int n = 0; n < 2; ++n) _Pragma("unroll") for (int k = 0; k < 2; ++k) \
;         acc[ai][bj][m][n] = __builtin_amdgcn_mfma_f32_16x16x32_bf16(Bt[n][k], At[m][k], acc[ai][bj][m][n], 0, 0, 0); __builtin_amdgcn_s_setprio(0); } while (0)
; #define PG8_WAIT_V(n) asm volatile("s_waitcnt vmcnt(" #n ")" ::: "memory")
; #define PG8_WAIT_L(n) asm volatile("s_waitcnt lgkmcnt(" #n ")" ::: "memory")
; #define PG8_BAR __builtin_amdgcn_s_barrier()
; #define PG8_SCHED __builtin_amdgcn_sched_barrier(0)
; template <class Epi, class Sched>
; __device__ __forceinline__ void gemm_phase(LAS unsigned char* lds, const Gemm g, const Sched& S, const Epi& E, int tid_in) {
;     ...
;         for (int t = 0; t < nt; t += 2) {
;             const bool last = (t == nt - 2);
;             const char* a1 = cA + (size_t)(t + 1) * kstep;
;             const char* a2 = last ? nA : cA + (size_t)(t + 2) * kstep; const char* b2 = last ? nB : cB + (size_t)(t + 2) * kstep;
;             const char* a3 = a2 + kstep; const char* b3 = b2 + kstep;
;             PG8_LDB(B0, 0, 0); PG8_LDB(B1, 0, 1); PG8_SCHED; PG8_LDA(At, 0, 0); PG8_STAGE(PG8_SA(1, 0), a1, voffA); PG8_STAGE(PG8_SA(1, 1), a1 + hstep, voffA);
;     ...
;             PG8_LDA(At, 1, 1); PG8_STAGE(PG8_SB(1, 0), b3, voffB); PG8_STAGE(PG8_SB(1, 1), b3 + hstep, voffB);
;             PG8_WAIT_V(6); PG8_WAIT_L(0); PG8_BAR; PG8_MMA(1, 0, At, B0); PG8_MMA(1, 1, At, B1); PG8_BAR; PG8_SCHED;
	s_add_i32 s38, s62, s2
	v_lshl_add_u64 v[148:149], v[148:149], 0, s[14:15]
	s_mov_b32 m0, s38
	ds_read_b128 v[192:195], v155 offset:49152
	ds_read_b128 v[196:199], v155 offset:50176
	ds_read_b128 v[200:203], v155 offset:51200
	ds_read_b128 v[204:207], v155 offset:52224
	ds_read_b128 v[208:211], v155 offset:53248
	ds_read_b128 v[212:215], v155 offset:54272
	ds_read_b128 v[216:219], v155 offset:55296
	ds_read_b128 v[220:223], v155 offset:56320
	global_load_lds_dwordx4 v[148:149], off
	s_add_i32 m0, s38, 0x2000
	s_add_u32 s36, s36, 0x80080
	v_lshl_add_u64 v[148:149], v[186:187], 0, s[14:15]
	s_addc_u32 s37, s37, 0
	s_add_i32 s38, s63, s2
	global_load_lds_dwordx4 v[148:149], off
	v_lshl_add_u64 v[148:149], s[36:37], 0, v[130:131]
	s_mov_b32 m0, s38
	s_nop 0
	global_load_lds_dwordx4 v[148:149], off
	v_lshl_add_u64 v[148:149], s[36:37], 0, v[134:135]
	s_add_i32 m0, s38, 0x2000
	s_nop 0
	global_load_lds_dwordx4 v[148:149], off
	s_waitcnt vmcnt(6)
	s_waitcnt lgkmcnt(0)
	s_setprio 3
	s_barrier
	v_mfma_f32_16x16x32_bf16 v[60:63], v[158:161], v[192:195], v[60:63]
	v_mfma_f32_16x16x32_bf16 v[56:59], v[166:169], v[192:195], v[56:59]
	v_mfma_f32_16x16x32_bf16 v[44:47], v[158:161], v[200:203], v[44:47]
	v_mfma_f32_16x16x32_bf16 v[40:43], v[166:169], v[200:203], v[40:43]
	v_mfma_f32_16x16x32_bf16 v[28:31], v[158:161], v[208:211], v[28:31]
	v_mfma_f32_16x16x32_bf16 v[24:27], v[166:169], v[208:211], v[24:27]
	v_mfma_f32_16x16x32_bf16 v[12:15], v[158:161], v[216:219], v[12:15]
	v_mfma_f32_16x16x32_bf16 v[8:11], v[166:169], v[216:219], v[8:11]
	v_mfma_f32_16x16x32_bf16 v[60:63], v[162:165], v[196:199], v[60:63]
	v_mfma_f32_16x16x32_bf16 v[56:59], v[170:173], v[196:199], v[56:59]
	v_mfma_f32_16x16x32_bf16 v[44:47], v[162:165], v[204:207], v[44:47]
	v_mfma_f32_16x16x32_bf16 v[40:43], v[170:173], v[204:207], v[40:43]
	v_mfma_f32_16x16x32_bf16 v[28:31], v[162:165], v[212:215], v[28:31]
	v_mfma_f32_16x16x32_bf16 v[24:27], v[170:173], v[212:215], v[24:27]
	v_mfma_f32_16x16x32_bf16 v[12:15], v[162:165], v[220:223], v[12:15]
	v_mfma_f32_16x16x32_bf16 v[8:11], v[170:173], v[220:223], v[8:11]
	s_setprio 0
	s_setprio 3
	v_mfma_f32_16x16x32_bf16 v[52:55], v[174:177], v[192:195], v[52:55]
	v_mfma_f32_16x16x32_bf16 v[48:51], v[182:185], v[192:195], v[48:51]
	v_mfma_f32_16x16x32_bf16 v[36:39], v[174:177], v[200:203], v[36:39]
	v_mfma_f32_16x16x32_bf16 v[32:35], v[182:185], v[200:203], v[32:35]
	v_mfma_f32_16x16x32_bf16 v[20:23], v[174:177], v[208:211], v[20:23]
	v_mfma_f32_16x16x32_bf16 v[16:19], v[182:185], v[208:211], v[16:19]
	v_mfma_f32_16x16x32_bf16 v[4:7], v[174:177], v[216:219], v[4:7]
	v_mfma_f32_16x16x32_bf16 v[0:3], v[182:185], v[216:219], v[0:3]
	v_mfma_f32_16x16x32_bf16 v[52:55], v[178:181], v[196:199], v[52:55]
	v_mfma_f32_16x16x32_bf16 v[48:51], v[188:191], v[196:199], v[48:51]
	v_mfma_f32_16x16x32_bf16 v[36:39], v[178:181], v[204:207], v[36:39]
	v_mfma_f32_16x16x32_bf16 v[32:35], v[188:191], v[204:207], v[32:35]
	v_mfma_f32_16x16x32_bf16 v[20:23], v[178:181], v[212:215], v[20:23]
	v_mfma_f32_16x16x32_bf16 v[16:19], v[188:191], v[212:215], v[16:19]
	v_mfma_f32_16x16x32_bf16 v[4:7], v[178:181], v[220:223], v[4:7]
	v_mfma_f32_16x16x32_bf16 v[0:3], v[188:191], v[220:223], v[0:3]
	s_setprio 0
	s_barrier
	s_add_i32 s51, s51, 2
	s_add_u32 s34, s34, 0x100
	s_addc_u32 s35, s35, 0
	s_cmp_gt_u32 s51, 29
	s_cbranch_scc0 .LBB0_1009
	s_branch .Lpeel_exit_4
.LBB0_1009:
	ds_read_b128 v[158:161], v153
	ds_read_b128 v[162:165], v153 offset:1024
	ds_read_b128 v[166:169], v153 offset:2048
	ds_read_b128 v[170:173], v153 offset:3072
	ds_read_b128 v[174:177], v154
	ds_read_b128 v[178:181], v154 offset:1024
	ds_read_b128 v[182:185], v154 offset:2048
	ds_read_b128 v[188:191], v154 offset:3072
	s_add_u32 s36, s30, s34
	s_addc_u32 s37, s31, s35
	s_add_u32 s38, s36, 0x100
	s_addc_u32 s39, s37, 0
	s_add_u32 s36, s48, s34
	s_addc_u32 s37, s49, s35
	s_cmpk_eq_i32 s34, 0xf00
	s_cselect_b32 s37, s21, s37
	s_cselect_b32 s36, s47, s36
	s_cselect_b32 s39, s23, s39
	s_cselect_b32 s38, s29, s38
	v_lshl_add_u64 v[148:149], v[146:147], 0, s[34:35]
	v_lshl_add_u64 v[186:187], v[148:149], 0, s[14:15]
	s_add_i32 m0, s3, 0x8000
	ds_read_b128 v[192:195], v155
	ds_read_b128 v[196:199], v155 offset:1024
	ds_read_b128 v[200:203], v155 offset:2048
	ds_read_b128 v[204:207], v155 offset:3072
	ds_read_b128 v[208:211], v155 offset:4096
	ds_read_b128 v[212:215], v155 offset:5120
	ds_read_b128 v[216:219], v155 offset:6144
	ds_read_b128 v[220:223], v155 offset:7168
	global_load_lds_dwordx4 v[186:187], off
	v_lshl_add_u64 v[186:187], v[144:145], 0, s[34:35]
	v_lshl_add_u64 v[224:225], v[186:187], 0, s[14:15]
	s_add_i32 m0, s3, 0xa000
	v_lshl_add_u64 v[148:149], v[148:149], 0, s[16:17]
	global_load_lds_dwordx4 v[224:225], off
	s_add_i32 m0, s3, 0xc000
	s_nop 0
	global_load_lds_dwordx4 v[148:149], off
	v_lshl_add_u64 v[148:149], v[186:187], 0, s[16:17]
	s_add_i32 m0, s3, 0xe000
	s_nop 0
	global_load_lds_dwordx4 v[148:149], off
	s_waitcnt vmcnt(8)
	s_waitcnt lgkmcnt(0)
	s_setprio 3
	s_barrier
; #define PG8_STAGE(bufoff, gbase, voff) do { _Pragma("unroll") for (int _i = 0; _i < 2; ++_i) \
;         __builtin_amdgcn_global_load_lds((const unsigned*)((const char*)(gbase) + (voff)[_i]), (LAS unsigned*)(lds + (bufoff) + ldsw + _i * 8192), 16, 0, 0); } while (0)
; #define PG8_LDA(dst, b, h) do { _Pragma("unroll") for (int m = 0; m < 4; ++m) _Pragma("unroll") for (int k = 0; k < 2; ++k) dst[m][k] = *(const LAS bf16x8*)(lds + PG8_SA(b, h) + aoff + m * 2048 + k * 1024); } while (0)
; #define PG8_MMA(ai, bj, At, Bt) do { __builtin_amdgcn_s_setprio(3); _Pragma("unroll") for (int m = 0; m < 4; ++m) _Pragma("unroll") for (int n = 0; n < 2; ++n) _Pragma("unroll") for (int k = 0; k < 2; ++k) \
;         acc[ai][bj][m][n] = __builtin_amdgcn_mfma_f32_16x16x32_bf16(Bt[n][k], At[m][k], acc[ai][bj][m][n], 0, 0, 0); __builtin_amdgcn_s_setprio(0); } while (0)
; #define PG8_WAIT_V(n) asm volatile("s_waitcnt vmcnt(" #n ")" ::: "memory")
; #define PG8_WAIT_L(n) asm volatile("s_waitcnt lgkmcnt(" #n ")" ::: "memory")
; #define PG8_BAR __builtin_amdgcn_s_barrier()
; #define PG8_SCHED __builtin_amdgcn_sched_barrier(0)
; template <class Epi, class Sched>
; __device__ __forceinline__ void gemm_phase(LAS unsigned char* lds, const Gemm g, const Sched& S, const Epi& E, int tid_in) {
;     ...
;             PG8_WAIT_V(8); PG8_WAIT_L(0); PG8_BAR; PG8_MMA(0, 0, At, B0); PG8_MMA(0, 1, At, B1); PG8_BAR; PG8_SCHED;
;             PG8_LDA(At, 0, 1); PG8_STAGE(PG8_SB(0, 0), b2, voffB); PG8_STAGE(PG8_SB(0, 1), b2 + hstep, voffB);
;             PG8_WAIT_V(6); PG8_WAIT_L(0); PG8_BAR; PG8_MMA(1, 0, At, B0); PG8_MMA(1, 1, At, B1); PG8_BAR; PG8_SCHED;
	v_mfma_f32_16x16x32_bf16 v[124:127], v[158:161], v[192:195], v[124:127]
	v_mfma_f32_16x16x32_bf16 v[120:123], v[166:169], v[192:195], v[120:123]
	v_mfma_f32_16x16x32_bf16 v[108:111], v[158:161], v[200:203], v[108:111]
	v_mfma_f32_16x16x32_bf16 v[104:107], v[166:169], v[200:203], v[104:107]
	v_mfma_f32_16x16x32_bf16 v[92:95], v[158:161], v[208:211], v[92:95]
	v_mfma_f32_16x16x32_bf16 v[88:91], v[166:169], v[208:211], v[88:91]
	v_mfma_f32_16x16x32_bf16 v[76:79], v[158:161], v[216:219], v[76:79]
	v_mfma_f32_16x16x32_bf16 v[72:75], v[166:169], v[216:219], v[72:75]
	v_mfma_f32_16x16x32_bf16 v[124:127], v[162:165], v[196:199], v[124:127]
	v_mfma_f32_16x16x32_bf16 v[120:123], v[170:173], v[196:199], v[120:123]
	v_mfma_f32_16x16x32_bf16 v[108:111], v[162:165], v[204:207], v[108:111]
	v_mfma_f32_16x16x32_bf16 v[104:107], v[170:173], v[204:207], v[104:107]
	v_mfma_f32_16x16x32_bf16 v[92:95], v[162:165], v[212:215], v[92:95]
	v_mfma_f32_16x16x32_bf16 v[88:91], v[170:173], v[212:215], v[88:91]
	v_mfma_f32_16x16x32_bf16 v[76:79], v[162:165], v[220:223], v[76:79]
	v_mfma_f32_16x16x32_bf16 v[72:75], v[170:173], v[220:223], v[72:75]
	s_setprio 0
	s_setprio 3
	v_mfma_f32_16x16x32_bf16 v[116:119], v[174:177], v[192:195], v[116:119]
	v_mfma_f32_16x16x32_bf16 v[112:115], v[182:185], v[192:195], v[112:115]
	v_mfma_f32_16x16x32_bf16 v[100:103], v[174:177], v[200:203], v[100:103]
	v_mfma_f32_16x16x32_bf16 v[96:99], v[182:185], v[200:203], v[96:99]
	v_mfma_f32_16x16x32_bf16 v[84:87], v[174:177], v[208:211], v[84:87]
	v_mfma_f32_16x16x32_bf16 v[80:83], v[182:185], v[208:211], v[80:83]
	v_mfma_f32_16x16x32_bf16 v[68:71], v[174:177], v[216:219], v[68:71]
	v_mfma_f32_16x16x32_bf16 v[64:67], v[182:185], v[216:219], v[64:67]
	v_mfma_f32_16x16x32_bf16 v[116:119], v[178:181], v[196:199], v[116:119]
	v_mfma_f32_16x16x32_bf16 v[112:115], v[188:191], v[196:199], v[112:115]
	v_mfma_f32_16x16x32_bf16 v[100:103], v[178:181], v[204:207], v[100:103]
	v_mfma_f32_16x16x32_bf16 v[96:99], v[188:191], v[204:207], v[96:99]
	v_mfma_f32_16x16x32_bf16 v[84:87], v[178:181], v[212:215], v[84:87]
	v_mfma_f32_16x16x32_bf16 v[80:83], v[188:191], v[212:215], v[80:83]
	v_mfma_f32_16x16x32_bf16 v[68:71], v[178:181], v[220:223], v[68:71]
	v_mfma_f32_16x16x32_bf16 v[64:67], v[188:191], v[220:223], v[64:67]
	s_setprio 0
	s_barrier
	s_add_i32 s62, s44, s2
	v_lshl_add_u64 v[148:149], s[36:37], 0, v[130:131]
	s_mov_b32 m0, s62
	ds_read_b128 v[192:195], v155 offset:16384
	ds_read_b128 v[196:199], v155 offset:17408
	ds_read_b128 v[200:203], v155 offset:18432
	ds_read_b128 v[204:207], v155 offset:19456
	ds_read_b128 v[208:211], v155 offset:20480
	ds_read_b128 v[212:215], v155 offset:21504
	ds_read_b128 v[216:219], v155 offset:22528
	ds_read_b128 v[220:223], v155 offset:23552
	global_load_lds_dwordx4 v[148:149], off
	s_add_i32 m0, s62, 0x2000
	s_add_u32 s62, s36, 0x80000
	v_lshl_add_u64 v[186:187], s[36:37], 0, v[134:135]
	s_addc_u32 s63, s37, 0
	s_add_i32 s64, s45, s2
	global_load_lds_dwordx4 v[186:187], off
	v_lshl_add_u64 v[224:225], s[62:63], 0, v[130:131]
	s_mov_b32 m0, s64
	s_nop 0
	global_load_lds_dwordx4 v[224:225], off
	v_lshl_add_u64 v[224:225], s[62:63], 0, v[134:135]
	s_add_i32 m0, s64, 0x2000
	s_nop 0
	global_load_lds_dwordx4 v[224:225], off
	s_waitcnt vmcnt(6)
	s_waitcnt lgkmcnt(0)
	s_setprio 3
	s_barrier
	v_mfma_f32_16x16x32_bf16 v[60:63], v[158:161], v[192:195], v[60:63]
	v_mfma_f32_16x16x32_bf16 v[56:59], v[166:169], v[192:195], v[56:59]
	v_mfma_f32_16x16x32_bf16 v[44:47], v[158:161], v[200:203], v[44:47]
	v_mfma_f32_16x16x32_bf16 v[40:43], v[166:169], v[200:203], v[40:43]
	v_mfma_f32_16x16x32_bf16 v[28:31], v[158:161], v[208:211], v[28:31]
	v_mfma_f32_16x16x32_bf16 v[24:27], v[166:169], v[208:211], v[24:27]
	v_mfma_f32_16x16x32_bf16 v[12:15], v[158:161], v[216:219], v[12:15]
	v_mfma_f32_16x16x32_bf16 v[8:11], v[166:169], v[216:219], v[8:11]
	v_mfma_f32_16x16x32_bf16 v[60:63], v[162:165], v[196:199], v[60:63]
	v_mfma_f32_16x16x32_bf16 v[56:59], v[170:173], v[196:199], v[56:59]
	v_mfma_f32_16x16x32_bf16 v[44:47], v[162:165], v[204:207], v[44:47]
	v_mfma_f32_16x16x32_bf16 v[40:43], v[170:173], v[204:207], v[40:43]
	v_mfma_f32_16x16x32_bf16 v[28:31], v[162:165], v[212:215], v[28:31]
	v_mfma_f32_16x16x32_bf16 v[24:27], v[170:173], v[212:215], v[24:27]
	v_mfma_f32_16x16x32_bf16 v[12:15], v[162:165], v[220:223], v[12:15]
	v_mfma_f32_16x16x32_bf16 v[8:11], v[170:173], v[220:223], v[8:11]
	s_setprio 0
	s_setprio 3
	v_mfma_f32_16x16x32_bf16 v[52:55], v[174:177], v[192:195], v[52:55]
	v_mfma_f32_16x16x32_bf16 v[48:51], v[182:185], v[192:195], v[48:51]
	v_mfma_f32_16x16x32_bf16 v[36:39], v[174:177], v[200:203], v[36:39]
	v_mfma_f32_16x16x32_bf16 v[32:35], v[182:185], v[200:203], v[32:35]
	v_mfma_f32_16x16x32_bf16 v[20:23], v[174:177], v[208:211], v[20:23]
	v_mfma_f32_16x16x32_bf16 v[16:19], v[182:185], v[208:211], v[16:19]
	v_mfma_f32_16x16x32_bf16 v[4:7], v[174:177], v[216:219], v[4:7]
	v_mfma_f32_16x16x32_bf16 v[0:3], v[182:185], v[216:219], v[0:3]
	v_mfma_f32_16x16x32_bf16 v[52:55], v[178:181], v[196:199], v[52:55]
	v_mfma_f32_16x16x32_bf16 v[48:51], v[188:191], v[196:199], v[48:51]
	v_mfma_f32_16x16x32_bf16 v[36:39], v[178:181], v[204:207], v[36:39]
	v_mfma_f32_16x16x32_bf16 v[32:35], v[188:191], v[204:207], v[32:35]
	v_mfma_f32_16x16x32_bf16 v[20:23], v[178:181], v[212:215], v[20:23]
	v_mfma_f32_16x16x32_bf16 v[16:19], v[188:191], v[212:215], v[16:19]
	v_mfma_f32_16x16x32_bf16 v[4:7], v[178:181], v[220:223], v[4:7]
	v_mfma_f32_16x16x32_bf16 v[0:3], v[188:191], v[220:223], v[0:3]
	s_setprio 0
	s_barrier
; #define PG8_STAGE(bufoff, gbase, voff) do { _Pragma("unroll") for (int _i = 0; _i < 2; ++_i) \
;         __builtin_amdgcn_global_load_lds((const unsigned*)((const char*)(gbase) + (voff)[_i]), (LAS unsigned*)(lds + (bufoff) + ldsw + _i * 8192), 16, 0, 0); } while (0)
; #define PG8_LDA(dst, b, h) do { _Pragma("unroll") for (int m = 0; m < 4; ++m) _Pragma("unroll") for (int k = 0; k < 2; ++k) dst[m][k] = *(const LAS bf16x8*)(lds + PG8_SA(b, h) + aoff + m * 2048 + k * 1024); } while (0)
; #define PG8_LDB(dst, b, h) do { _Pragma("unroll") for (int n = 0; n < 2; ++n) _Pragma("unroll") for (int k = 0; k < 2; ++k) dst[n][k] = *(const LAS bf16x8*)(lds + PG8_SB(b, h) + boff + n * 2048 + k * 1024); } while (0)
; #define PG8_MMA(ai, bj, At, Bt) do { __builtin_amdgcn_s_setprio(3); _Pragma("unroll") for (int m = 0; m < 4; ++m) _Pragma("unroll") for (int n = 0; n < 2; ++n) _Pragma("unroll") for (int k = 0; k < 2; ++k) \
;         acc[ai][bj][m][n] = __builtin_amdgcn_mfma_f32_16x16x32_bf16(Bt[n][k], At[m][k], acc[ai][bj][m][n], 0, 0, 0); __builtin_amdgcn_s_setprio(0); } while (0)
; #define PG8_WAIT_V(n) asm volatile("s_waitcnt vmcnt(" #n ")" ::: "memory")
; #define PG8_WAIT_L(n) asm volatile("s_waitcnt lgkmcnt(" #n ")" ::: "memory")
; #define PG8_BAR __builtin_amdgcn_s_barrier()
; #define PG8_SCHED __builtin_amdgcn_sched_barrier(0)
; template <class Epi, class Sched>
; __device__ __forceinline__ void gemm_phase(LAS unsigned char* lds, const Gemm g, const Sched& S, const Epi& E, int tid_in) {
;     ...
;             PG8_LDB(B0, 1, 0); PG8_LDB(B1, 1, 1); PG8_SCHED; PG8_LDA(At, 1, 0); PG8_STAGE(PG8_SA(0, 0), a2, voffA); PG8_STAGE(PG8_SA(0, 1), a2 + hstep, voffA);
;             PG8_WAIT_V(8); PG8_WAIT_L(0); PG8_BAR; PG8_MMA(0, 0, At, B0); PG8_MMA(0, 1, At, B1); PG8_BAR; PG8_SCHED;
;             PG8_LDA(At, 1, 1); PG8_STAGE(PG8_SB(1, 0), b3, voffB); PG8_STAGE(PG8_SB(1, 1), b3 + hstep, voffB);
;             PG8_WAIT_V(6); PG8_WAIT_L(0); PG8_BAR; PG8_MMA(1, 0, At, B0); PG8_MMA(1, 1, At, B1); PG8_BAR; PG8_SCHED;
	s_add_i32 s62, 0, 0x18000
	v_add_u32_e32 v157, s62, v151
	s_add_i32 s63, 0, 0x1c000
	ds_read_b128 v[158:161], v157
	ds_read_b128 v[162:165], v157 offset:1024
	ds_read_b128 v[166:169], v157 offset:2048
	ds_read_b128 v[170:173], v157 offset:3072
	v_add_u32_e32 v157, s63, v151
	ds_read_b128 v[174:177], v157
	ds_read_b128 v[178:181], v157 offset:1024
	ds_read_b128 v[182:185], v157 offset:2048
	ds_read_b128 v[188:191], v157 offset:3072
	s_mov_b32 m0, s3
	v_lshl_add_u64 v[224:225], s[38:39], 0, v[128:129]
	ds_read_b128 v[192:195], v155 offset:32768
	ds_read_b128 v[196:199], v155 offset:33792
	ds_read_b128 v[200:203], v155 offset:34816
	ds_read_b128 v[204:207], v155 offset:35840
	ds_read_b128 v[208:211], v155 offset:36864
	ds_read_b128 v[212:215], v155 offset:37888
	ds_read_b128 v[216:219], v155 offset:38912
	ds_read_b128 v[220:223], v155 offset:39936
	global_load_lds_dwordx4 v[224:225], off
	v_lshl_add_u64 v[224:225], s[38:39], 0, v[132:133]
	s_add_u32 s38, s38, 0x80000
	s_mov_b32 m0, s40
	s_addc_u32 s39, s39, 0
	global_load_lds_dwordx4 v[224:225], off
	v_lshl_add_u64 v[224:225], s[38:39], 0, v[128:129]
	s_mov_b32 m0, s41
	s_nop 0
	global_load_lds_dwordx4 v[224:225], off
	v_lshl_add_u64 v[224:225], s[38:39], 0, v[132:133]
	s_mov_b32 m0, s42
	s_nop 0
	global_load_lds_dwordx4 v[224:225], off
	s_waitcnt vmcnt(8)
	s_waitcnt lgkmcnt(0)
	s_setprio 3
	s_barrier
	v_mfma_f32_16x16x32_bf16 v[124:127], v[158:161], v[192:195], v[124:127]
	v_mfma_f32_16x16x32_bf16 v[120:123], v[166:169], v[192:195], v[120:123]
	v_mfma_f32_16x16x32_bf16 v[108:111], v[158:161], v[200:203], v[108:111]
	v_mfma_f32_16x16x32_bf16 v[104:107], v[166:169], v[200:203], v[104:107]
	v_mfma_f32_16x16x32_bf16 v[92:95], v[158:161], v[208:211], v[92:95]
	v_mfma_f32_16x16x32_bf16 v[88:91], v[166:169], v[208:211], v[88:91]
	v_mfma_f32_16x16x32_bf16 v[76:79], v[158:161], v[216:219], v[76:79]
	v_mfma_f32_16x16x32_bf16 v[72:75], v[166:169], v[216:219], v[72:75]
	v_mfma_f32_16x16x32_bf16 v[124:127], v[162:165], v[196:199], v[124:127]
	v_mfma_f32_16x16x32_bf16 v[120:123], v[170:173], v[196:199], v[120:123]
	v_mfma_f32_16x16x32_bf16 v[108:111], v[162:165], v[204:207], v[108:111]
	v_mfma_f32_16x16x32_bf16 v[104:107], v[170:173], v[204:207], v[104:107]
	v_mfma_f32_16x16x32_bf16 v[92:95], v[162:165], v[212:215], v[92:95]
	v_mfma_f32_16x16x32_bf16 v[88:91], v[170:173], v[212:215], v[88:91]
	v_mfma_f32_16x16x32_bf16 v[76:79], v[162:165], v[220:223], v[76:79]
	v_mfma_f32_16x16x32_bf16 v[72:75], v[170:173], v[220:223], v[72:75]
	s_setprio 0
	s_setprio 3
	v_mfma_f32_16x16x32_bf16 v[116:119], v[174:177], v[192:195], v[116:119]
	v_mfma_f32_16x16x32_bf16 v[112:115], v[182:185], v[192:195], v[112:115]
	v_mfma_f32_16x16x32_bf16 v[100:103], v[174:177], v[200:203], v[100:103]
	v_mfma_f32_16x16x32_bf16 v[96:99], v[182:185], v[200:203], v[96:99]
	v_mfma_f32_16x16x32_bf16 v[84:87], v[174:177], v[208:211], v[84:87]
	v_mfma_f32_16x16x32_bf16 v[80:83], v[182:185], v[208:211], v[80:83]
	v_mfma_f32_16x16x32_bf16 v[68:71], v[174:177], v[216:219], v[68:71]
	v_mfma_f32_16x16x32_bf16 v[64:67], v[182:185], v[216:219], v[64:67]
	v_mfma_f32_16x16x32_bf16 v[116:119], v[178:181], v[196:199], v[116:119]
	v_mfma_f32_16x16x32_bf16 v[112:115], v[188:191], v[196:199], v[112:115]
	v_mfma_f32_16x16x32_bf16 v[100:103], v[178:181], v[204:207], v[100:103]
	v_mfma_f32_16x16x32_bf16 v[96:99], v[188:191], v[204:207], v[96:99]
	v_mfma_f32_16x16x32_bf16 v[84:87], v[178:181], v[212:215], v[84:87]
	v_mfma_f32_16x16x32_bf16 v[80:83], v[188:191], v[212:215], v[80:83]
	v_mfma_f32_16x16x32_bf16 v[68:71], v[178:181], v[220:223], v[68:71]
	v_mfma_f32_16x16x32_bf16 v[64:67], v[188:191], v[220:223], v[64:67]
	s_setprio 0
	s_barrier
	s_add_i32 s38, s62, s2
	v_lshl_add_u64 v[148:149], v[148:149], 0, s[14:15]
	s_mov_b32 m0, s38
	ds_read_b128 v[192:195], v155 offset:49152
	ds_read_b128 v[196:199], v155 offset:50176
	ds_read_b128 v[200:203], v155 offset:51200
	ds_read_b128 v[204:207], v155 offset:52224
	ds_read_b128 v[208:211], v155 offset:53248
	ds_read_b128 v[212:215], v155 offset:54272
	ds_read_b128 v[216:219], v155 offset:55296
	ds_read_b128 v[220:223], v155 offset:56320
	global_load_lds_dwordx4 v[148:149], off
	s_add_i32 m0, s38, 0x2000
	s_add_u32 s36, s36, 0x80080
	v_lshl_add_u64 v[148:149], v[186:187], 0, s[14:15]
	s_addc_u32 s37, s37, 0
	s_add_i32 s38, s63, s2
	global_load_lds_dwordx4 v[148:149], off
	v_lshl_add_u64 v[148:149], s[36:37], 0, v[130:131]
	s_mov_b32 m0, s38
	s_nop 0
	global_load_lds_dwordx4 v[148:149], off
	v_lshl_add_u64 v[148:149], s[36:37], 0, v[134:135]
	s_add_i32 m0, s38, 0x2000
	s_nop 0
	global_load_lds_dwordx4 v[148:149], off
	s_waitcnt vmcnt(6)
	s_waitcnt lgkmcnt(0)
	s_setprio 3
	s_barrier
	v_mfma_f32_16x16x32_bf16 v[60:63], v[158:161], v[192:195], v[60:63]
	v_mfma_f32_16x16x32_bf16 v[56:59], v[166:169], v[192:195], v[56:59]
	v_mfma_f32_16x16x32_bf16 v[44:47], v[158:161], v[200:203], v[44:47]
	v_mfma_f32_16x16x32_bf16 v[40:43], v[166:169], v[200:203], v[40:43]
	v_mfma_f32_16x16x32_bf16 v[28:31], v[158:161], v[208:211], v[28:31]
	v_mfma_f32_16x16x32_bf16 v[24:27], v[166:169], v[208:211], v[24:27]
	v_mfma_f32_16x16x32_bf16 v[12:15], v[158:161], v[216:219], v[12:15]
	v_mfma_f32_16x16x32_bf16 v[8:11], v[166:169], v[216:219], v[8:11]
	v_mfma_f32_16x16x32_bf16 v[60:63], v[162:165], v[196:199], v[60:63]
	v_mfma_f32_16x16x32_bf16 v[56:59], v[170:173], v[196:199], v[56:59]
	v_mfma_f32_16x16x32_bf16 v[44:47], v[162:165], v[204:207], v[44:47]
	v_mfma_f32_16x16x32_bf16 v[40:43], v[170:173], v[204:207], v[40:43]
	v_mfma_f32_16x16x32_bf16 v[28:31], v[162:165], v[212:215], v[28:31]
	v_mfma_f32_16x16x32_bf16 v[24:27], v[170:173], v[212:215], v[24:27]
	v_mfma_f32_16x16x32_bf16 v[12:15], v[162:165], v[220:223], v[12:15]
	v_mfma_f32_16x16x32_bf16 v[8:11], v[170:173], v[220:223], v[8:11]
	s_setprio 0
	s_setprio 3
	v_mfma_f32_16x16x32_bf16 v[52:55], v[174:177], v[192:195], v[52:55]
	v_mfma_f32_16x16x32_bf16 v[48:51], v[182:185], v[192:195], v[48:51]
	v_mfma_f32_16x16x32_bf16 v[36:39], v[174:177], v[200:203], v[36:39]
	v_mfma_f32_16x16x32_bf16 v[32:35], v[182:185], v[200:203], v[32:35]
	v_mfma_f32_16x16x32_bf16 v[20:23], v[174:177], v[208:211], v[20:23]
	v_mfma_f32_16x16x32_bf16 v[16:19], v[182:185], v[208:211], v[16:19]
	v_mfma_f32_16x16x32_bf16 v[4:7], v[174:177], v[216:219], v[4:7]
	v_mfma_f32_16x16x32_bf16 v[0:3], v[182:185], v[216:219], v[0:3]
	v_mfma_f32_16x16x32_bf16 v[52:55], v[178:181], v[196:199], v[52:55]
	v_mfma_f32_16x16x32_bf16 v[48:51], v[188:191], v[196:199], v[48:51]
	v_mfma_f32_16x16x32_bf16 v[36:39], v[178:181], v[204:207], v[36:39]
	v_mfma_f32_16x16x32_bf16 v[32:35], v[188:191], v[204:207], v[32:35]
	v_mfma_f32_16x16x32_bf16 v[20:23], v[178:181], v[212:215], v[20:23]
	v_mfma_f32_16x16x32_bf16 v[16:19], v[188:191], v[212:215], v[16:19]
	v_mfma_f32_16x16x32_bf16 v[4:7], v[178:181], v[220:223], v[4:7]
	v_mfma_f32_16x16x32_bf16 v[0:3], v[188:191], v[220:223], v[0:3]
	s_setprio 0
	s_barrier
	s_add_i32 s51, s51, 2
	s_add_u32 s34, s34, 0x100
	s_addc_u32 s35, s35, 0
	s_cmp_gt_u32 s51, 29
	s_cbranch_scc0 .LBB0_1009
